# speedup vs baseline: 1.0412x; 1.0412x over previous
.LBB0_615:
	s_andn2_saveexec_b64 s[0:1], s[0:1]
	v_mul_f32_e32 v7, v6, v6
	v_fmamk_f32 v8, v7, 0xba1345e1, v157
	v_fmaak_f32 v8, v7, v8, 0xbcdac9b8
	v_fmaak_f32 v8, v7, v8, 0x3de703be
	v_fmaak_f32 v8, v7, v8, 0xbec09330
	v_fmaak_f32 v7, v7, v8, 0x3e0375d0
	v_fma_f32 v7, |v6|, v7, |v6|
	s_or_b64 exec, exec, s[0:1]
	v_readlane_b32 s48, v254, 40
	v_lshlrev_b64 v[8:9], 7, v[108:109]
	v_readlane_b32 s58, v254, 50
	v_readlane_b32 s59, v254, 51
	v_lshl_add_u64 v[8:9], v[8:9], 2, v[138:139]
	v_bfi_b32 v3, s78, v4, v3
	v_lshl_add_u64 v[10:11], v[54:55], 2, s[58:59]
	v_lshl_add_u64 v[12:13], v[56:57], 2, s[58:59]
	global_load_dwordx2 v[8:9], v[8:9], off
	s_nop 0
	global_load_dword v10, v[10:11], off
	s_nop 0
	global_load_dword v11, v[12:13], off
	v_mul_f32_e32 v4, 0.5, v5
	v_bfi_b32 v5, s78, v7, v6
	v_mul_f32_e32 v2, 0.5, v2
	v_add_f32_e32 v3, 1.0, v3
	v_add_f32_e32 v5, 1.0, v5
	v_mul_f32_e32 v2, v2, v3
	v_mul_f32_e32 v3, v4, v5
	v_mov_b32_e32 v92, 0
	s_mov_b32 s0, 0
	v_mov_b32_e32 v93, v92
	v_mov_b32_e32 v90, v92
	v_mov_b32_e32 v91, v92
	v_mov_b32_e32 v86, v92
	v_mov_b32_e32 v87, v92
	v_mov_b32_e32 v84, v92
	v_mov_b32_e32 v85, v92
	v_mov_b32_e32 v80, v92
	v_mov_b32_e32 v81, v92
	v_mov_b32_e32 v78, v92
	v_mov_b32_e32 v79, v92
	v_mov_b32_e32 v70, v92
	v_mov_b32_e32 v71, v92
	v_mov_b32_e32 v62, v92
	v_mov_b32_e32 v63, v92
	v_readlane_b32 s49, v254, 41
	v_readlane_b32 s50, v254, 42
	v_readlane_b32 s51, v254, 43
	v_readlane_b32 s52, v254, 44
	v_readlane_b32 s53, v254, 45
	v_readlane_b32 s54, v254, 46
	v_readlane_b32 s55, v254, 47
	v_readlane_b32 s56, v254, 48
	v_readlane_b32 s57, v254, 49
	v_readlane_b32 s60, v254, 52
	v_readlane_b32 s61, v254, 53
	v_readlane_b32 s62, v254, 54
	v_readlane_b32 s63, v254, 55
	s_waitcnt vmcnt(2)
	v_pk_mul_f32 v[2:3], v[2:3], v[8:9]
	s_waitcnt vmcnt(0)
	v_pk_mul_f32 v[24:25], v[2:3], v[10:11]
	ds_write_b64 v149, v[24:25] offset:512
	s_mov_b32 s0, 0x0f0f0f0f
	s_mov_b32 s1, 0xf0f0f0f0
	v_readfirstlane_b32 s38, v114
	v_readfirstlane_b32 s39, v115
	v_mul_f32_e32 v146, 0x3d800000, v24
	v_mul_f32_e32 v147, 0x3d800000, v25
	v_subrev_u32_e32 v100, s38, v114
	ds_write_b64 v149, v[146:147] offset:1536
	ds_read_b128 v[72:75], v1 offset:0
	ds_read_b128 v[94:97], v1 offset:16
	ds_read_b128 v[50:53], v1 offset:32
	ds_read_b128 v[54:57], v1 offset:48
	s_waitcnt lgkmcnt(2)
	v_lshl_add_u32 v72, v72, 9, v100
	v_lshl_add_u32 v73, v73, 9, v100
	v_lshl_add_u32 v74, v74, 9, v100
	v_lshl_add_u32 v75, v75, 9, v100
	v_lshl_add_u32 v94, v94, 9, v100
	v_lshl_add_u32 v95, v95, 9, v100
	v_lshl_add_u32 v96, v96, 9, v100
	v_lshl_add_u32 v97, v97, 9, v100
	global_load_dwordx2 v[164:165], v72, s[38:39]
	global_load_dwordx2 v[166:167], v73, s[38:39]
	global_load_dwordx2 v[168:169], v74, s[38:39]
	global_load_dwordx2 v[170:171], v75, s[38:39]
	global_load_dwordx2 v[172:173], v94, s[38:39]
	global_load_dwordx2 v[174:175], v95, s[38:39]
	global_load_dwordx2 v[176:177], v96, s[38:39]
	global_load_dwordx2 v[178:179], v97, s[38:39]
	ds_read_b128 v[72:75], v1 offset:64
	ds_read_b128 v[94:97], v1 offset:80
	s_waitcnt lgkmcnt(2)
	v_lshl_add_u32 v50, v50, 9, v100
	v_lshl_add_u32 v51, v51, 9, v100
	v_lshl_add_u32 v52, v52, 9, v100
	v_lshl_add_u32 v53, v53, 9, v100
	v_lshl_add_u32 v54, v54, 9, v100
	v_lshl_add_u32 v55, v55, 9, v100
	v_lshl_add_u32 v56, v56, 9, v100
	v_lshl_add_u32 v57, v57, 9, v100
	global_load_dwordx2 v[180:181], v50, s[38:39]
	global_load_dwordx2 v[182:183], v51, s[38:39]
	global_load_dwordx2 v[184:185], v52, s[38:39]
	global_load_dwordx2 v[186:187], v53, s[38:39]
	global_load_dwordx2 v[188:189], v54, s[38:39]
	global_load_dwordx2 v[190:191], v55, s[38:39]
	global_load_dwordx2 v[192:193], v56, s[38:39]
	global_load_dwordx2 v[194:195], v57, s[38:39]
	ds_read_b128 v[50:53], v1 offset:96
	ds_read_b128 v[54:57], v1 offset:112
	s_waitcnt lgkmcnt(2)
	v_lshl_add_u32 v72, v72, 9, v100
	v_lshl_add_u32 v73, v73, 9, v100
	v_lshl_add_u32 v74, v74, 9, v100
	v_lshl_add_u32 v75, v75, 9, v100
	v_lshl_add_u32 v94, v94, 9, v100
	v_lshl_add_u32 v95, v95, 9, v100
	v_lshl_add_u32 v96, v96, 9, v100
	v_lshl_add_u32 v97, v97, 9, v100
	global_load_dwordx2 v[196:197], v72, s[38:39]
	global_load_dwordx2 v[198:199], v73, s[38:39]
	global_load_dwordx2 v[200:201], v74, s[38:39]
	global_load_dwordx2 v[202:203], v75, s[38:39]
	global_load_dwordx2 v[204:205], v94, s[38:39]
	global_load_dwordx2 v[206:207], v95, s[38:39]
	global_load_dwordx2 v[208:209], v96, s[38:39]
	global_load_dwordx2 v[210:211], v97, s[38:39]
	ds_read_b128 v[72:75], v1 offset:128
	ds_read_b128 v[94:97], v1 offset:144
	s_waitcnt lgkmcnt(2)
	v_lshl_add_u32 v50, v50, 9, v100
	v_lshl_add_u32 v51, v51, 9, v100
	v_lshl_add_u32 v52, v52, 9, v100
	v_lshl_add_u32 v53, v53, 9, v100
	v_lshl_add_u32 v54, v54, 9, v100
	v_lshl_add_u32 v55, v55, 9, v100
	v_lshl_add_u32 v56, v56, 9, v100
	v_lshl_add_u32 v57, v57, 9, v100
	global_load_dwordx2 v[212:213], v50, s[38:39]
	global_load_dwordx2 v[214:215], v51, s[38:39]
	global_load_dwordx2 v[216:217], v52, s[38:39]
	global_load_dwordx2 v[218:219], v53, s[38:39]
	global_load_dwordx2 v[220:221], v54, s[38:39]
	global_load_dwordx2 v[222:223], v55, s[38:39]
	global_load_dwordx2 v[224:225], v56, s[38:39]
	global_load_dwordx2 v[226:227], v57, s[38:39]
	s_waitcnt lgkmcnt(0)
	v_lshl_add_u32 v72, v72, 9, v100
	v_lshl_add_u32 v73, v73, 9, v100
	v_lshl_add_u32 v74, v74, 9, v100
	v_lshl_add_u32 v75, v75, 9, v100
	v_lshl_add_u32 v94, v94, 9, v100
	v_lshl_add_u32 v95, v95, 9, v100
	v_lshl_add_u32 v96, v96, 9, v100
	v_lshl_add_u32 v97, v97, 9, v100
	global_load_dwordx2 v[2:3], v72, s[38:39]
	global_load_dwordx2 v[4:5], v73, s[38:39]
	global_load_dwordx2 v[6:7], v74, s[38:39]
	global_load_dwordx2 v[8:9], v75, s[38:39]
	global_load_dwordx2 v[10:11], v94, s[38:39]
	global_load_dwordx2 v[12:13], v95, s[38:39]
	global_load_dwordx2 v[14:15], v96, s[38:39]
	global_load_dwordx2 v[16:17], v97, s[38:39]
	v_add_f32_e32 v146, v24, v25
	ds_bpermute_b32 v147, v150, v146
	s_waitcnt lgkmcnt(0)
	v_add_f32_e32 v146, v146, v147
	ds_bpermute_b32 v147, v151, v146
	s_waitcnt lgkmcnt(0)
	v_add_f32_e32 v146, v146, v147
	ds_bpermute_b32 v147, v152, v146
	s_waitcnt lgkmcnt(0)
	v_add_f32_e32 v146, v146, v147
	ds_bpermute_b32 v147, v153, v146
	s_waitcnt lgkmcnt(0)
	v_add_f32_e32 v146, v146, v147
	ds_bpermute_b32 v147, v154, v146
	s_waitcnt lgkmcnt(0)
	v_add_f32_e32 v101, v146, v147
	ds_bpermute_b32 v162, v155, v101
	ds_read_b128 v[72:75], v1 offset:160
	ds_read_b128 v[94:97], v1 offset:176
	ds_read_b128 v[34:37], v1 offset:512
	ds_read_b128 v[38:41], v1 offset:528
	ds_read_b128 v[42:45], v1 offset:1536
	ds_read_b128 v[46:49], v1 offset:1552
	s_waitcnt lgkmcnt(0)
	v_lshl_add_u32 v72, v72, 9, v100
	v_lshl_add_u32 v73, v73, 9, v100
	v_lshl_add_u32 v74, v74, 9, v100
	v_lshl_add_u32 v75, v75, 9, v100
	v_lshl_add_u32 v94, v94, 9, v100
	v_lshl_add_u32 v95, v95, 9, v100
	v_lshl_add_u32 v96, v96, 9, v100
	v_lshl_add_u32 v97, v97, 9, v100
	global_load_dwordx2 v[18:19], v72, s[38:39]
	global_load_dwordx2 v[20:21], v73, s[38:39]
	global_load_dwordx2 v[22:23], v74, s[38:39]
	global_load_dwordx2 v[24:25], v75, s[38:39]
	global_load_dwordx2 v[26:27], v94, s[38:39]
	global_load_dwordx2 v[28:29], v95, s[38:39]
	global_load_dwordx2 v[30:31], v96, s[38:39]
	global_load_dwordx2 v[32:33], v97, s[38:39]
	ds_read_b128 v[72:75], v1 offset:192
	ds_read_b128 v[94:97], v1 offset:208
	ds_read_b128 v[50:53], v1 offset:544
	ds_read_b128 v[54:57], v1 offset:560
	ds_read_b128 v[58:61], v1 offset:1568
	ds_read_b128 v[64:67], v1 offset:1584
	s_waitcnt vmcnt(40)
	v_and_b32_e32 v68, s0, v164
	v_and_b32_e32 v69, s1, v164
	v_and_b32_e32 v76, s0, v165
	v_and_b32_e32 v77, s1, v165
	v_cvt_f32_ubyte0_e32 v98, v68
	v_cvt_f32_ubyte1_e32 v99, v68
	v_cvt_f32_ubyte2_e32 v102, v68
	v_cvt_f32_ubyte3_e32 v103, v68
	v_pk_fma_f32 v[92:93], v[34:35], v[98:99], v[92:93] op_sel_hi:[0,1,1]
	v_cvt_f32_ubyte0_e32 v104, v69
	v_cvt_f32_ubyte1_e32 v105, v69
	v_pk_fma_f32 v[90:91], v[34:35], v[102:103], v[90:91] op_sel_hi:[0,1,1]
	v_cvt_f32_ubyte2_e32 v146, v69
	v_cvt_f32_ubyte3_e32 v147, v69
	v_pk_fma_f32 v[86:87], v[42:43], v[104:105], v[86:87] op_sel_hi:[0,1,1]
	v_cvt_f32_ubyte0_e32 v98, v76
	v_cvt_f32_ubyte1_e32 v99, v76
	v_pk_fma_f32 v[84:85], v[42:43], v[146:147], v[84:85] op_sel_hi:[0,1,1]
	v_and_b32_e32 v82, s0, v166
	v_and_b32_e32 v83, s1, v166
	v_and_b32_e32 v88, s0, v167
	v_and_b32_e32 v89, s1, v167
	v_cvt_f32_ubyte2_e32 v102, v76
	v_cvt_f32_ubyte3_e32 v103, v76
	v_pk_fma_f32 v[80:81], v[34:35], v[98:99], v[80:81] op_sel_hi:[0,1,1]
	v_cvt_f32_ubyte0_e32 v104, v77
	v_cvt_f32_ubyte1_e32 v105, v77
	v_pk_fma_f32 v[78:79], v[34:35], v[102:103], v[78:79] op_sel_hi:[0,1,1]
	v_cvt_f32_ubyte2_e32 v146, v77
	v_cvt_f32_ubyte3_e32 v147, v77
	v_pk_fma_f32 v[70:71], v[42:43], v[104:105], v[70:71] op_sel_hi:[0,1,1]
	v_cvt_f32_ubyte0_e32 v98, v82
	v_cvt_f32_ubyte1_e32 v99, v82
	v_pk_fma_f32 v[62:63], v[42:43], v[146:147], v[62:63] op_sel_hi:[0,1,1]
	v_cvt_f32_ubyte2_e32 v102, v82
	v_cvt_f32_ubyte3_e32 v103, v82
	v_pk_fma_f32 v[92:93], v[34:35], v[98:99], v[92:93] op_sel:[1,0,0]
	v_cvt_f32_ubyte0_e32 v104, v83
	v_cvt_f32_ubyte1_e32 v105, v83
	v_pk_fma_f32 v[90:91], v[34:35], v[102:103], v[90:91] op_sel:[1,0,0]
	v_cvt_f32_ubyte2_e32 v146, v83
	v_cvt_f32_ubyte3_e32 v147, v83
	v_pk_fma_f32 v[86:87], v[42:43], v[104:105], v[86:87] op_sel:[1,0,0]
	v_cvt_f32_ubyte0_e32 v98, v88
	v_cvt_f32_ubyte1_e32 v99, v88
	v_pk_fma_f32 v[84:85], v[42:43], v[146:147], v[84:85] op_sel:[1,0,0]
	v_and_b32_e32 v68, s0, v168
	v_and_b32_e32 v69, s1, v168
	v_and_b32_e32 v76, s0, v169
	v_and_b32_e32 v77, s1, v169
	v_cvt_f32_ubyte2_e32 v102, v88
	v_cvt_f32_ubyte3_e32 v103, v88
	v_pk_fma_f32 v[80:81], v[34:35], v[98:99], v[80:81] op_sel:[1,0,0]
	v_cvt_f32_ubyte0_e32 v104, v89
	v_cvt_f32_ubyte1_e32 v105, v89
	v_pk_fma_f32 v[78:79], v[34:35], v[102:103], v[78:79] op_sel:[1,0,0]
	v_cvt_f32_ubyte2_e32 v146, v89
	v_cvt_f32_ubyte3_e32 v147, v89
	v_pk_fma_f32 v[70:71], v[42:43], v[104:105], v[70:71] op_sel:[1,0,0]
	v_cvt_f32_ubyte0_e32 v98, v68
	v_cvt_f32_ubyte1_e32 v99, v68
	v_pk_fma_f32 v[62:63], v[42:43], v[146:147], v[62:63] op_sel:[1,0,0]
	v_cvt_f32_ubyte2_e32 v102, v68
	v_cvt_f32_ubyte3_e32 v103, v68
	v_pk_fma_f32 v[92:93], v[36:37], v[98:99], v[92:93] op_sel_hi:[0,1,1]
	v_cvt_f32_ubyte0_e32 v104, v69
	v_cvt_f32_ubyte1_e32 v105, v69
	v_pk_fma_f32 v[90:91], v[36:37], v[102:103], v[90:91] op_sel_hi:[0,1,1]
	v_cvt_f32_ubyte2_e32 v146, v69
	v_cvt_f32_ubyte3_e32 v147, v69
	v_pk_fma_f32 v[86:87], v[44:45], v[104:105], v[86:87] op_sel_hi:[0,1,1]
	v_cvt_f32_ubyte0_e32 v98, v76
	v_cvt_f32_ubyte1_e32 v99, v76
	v_pk_fma_f32 v[84:85], v[44:45], v[146:147], v[84:85] op_sel_hi:[0,1,1]
	v_and_b32_e32 v82, s0, v170
	v_and_b32_e32 v83, s1, v170
	v_and_b32_e32 v88, s0, v171
	v_and_b32_e32 v89, s1, v171
	v_cvt_f32_ubyte2_e32 v102, v76
	v_cvt_f32_ubyte3_e32 v103, v76
	v_pk_fma_f32 v[80:81], v[36:37], v[98:99], v[80:81] op_sel_hi:[0,1,1]
	v_cvt_f32_ubyte0_e32 v104, v77
	v_cvt_f32_ubyte1_e32 v105, v77
	v_pk_fma_f32 v[78:79], v[36:37], v[102:103], v[78:79] op_sel_hi:[0,1,1]
	v_cvt_f32_ubyte2_e32 v146, v77
	v_cvt_f32_ubyte3_e32 v147, v77
	v_pk_fma_f32 v[70:71], v[44:45], v[104:105], v[70:71] op_sel_hi:[0,1,1]
	v_cvt_f32_ubyte0_e32 v98, v82
	v_cvt_f32_ubyte1_e32 v99, v82
	v_pk_fma_f32 v[62:63], v[44:45], v[146:147], v[62:63] op_sel_hi:[0,1,1]
	v_cvt_f32_ubyte2_e32 v102, v82
	v_cvt_f32_ubyte3_e32 v103, v82
	v_pk_fma_f32 v[92:93], v[36:37], v[98:99], v[92:93] op_sel:[1,0,0]
	v_cvt_f32_ubyte0_e32 v104, v83
	v_cvt_f32_ubyte1_e32 v105, v83
	v_pk_fma_f32 v[90:91], v[36:37], v[102:103], v[90:91] op_sel:[1,0,0]
	v_cvt_f32_ubyte2_e32 v146, v83
	v_cvt_f32_ubyte3_e32 v147, v83
	v_pk_fma_f32 v[86:87], v[44:45], v[104:105], v[86:87] op_sel:[1,0,0]
	v_cvt_f32_ubyte0_e32 v98, v88
	v_cvt_f32_ubyte1_e32 v99, v88
	v_pk_fma_f32 v[84:85], v[44:45], v[146:147], v[84:85] op_sel:[1,0,0]
	v_and_b32_e32 v68, s0, v172
	v_and_b32_e32 v69, s1, v172
	v_and_b32_e32 v76, s0, v173
	v_and_b32_e32 v77, s1, v173
	v_cvt_f32_ubyte2_e32 v102, v88
	v_cvt_f32_ubyte3_e32 v103, v88
	v_pk_fma_f32 v[80:81], v[36:37], v[98:99], v[80:81] op_sel:[1,0,0]
	v_cvt_f32_ubyte0_e32 v104, v89
	v_cvt_f32_ubyte1_e32 v105, v89
	v_pk_fma_f32 v[78:79], v[36:37], v[102:103], v[78:79] op_sel:[1,0,0]
	v_cvt_f32_ubyte2_e32 v146, v89
	v_cvt_f32_ubyte3_e32 v147, v89
	v_pk_fma_f32 v[70:71], v[44:45], v[104:105], v[70:71] op_sel:[1,0,0]
	v_cvt_f32_ubyte0_e32 v98, v68
	v_cvt_f32_ubyte1_e32 v99, v68
	v_pk_fma_f32 v[62:63], v[44:45], v[146:147], v[62:63] op_sel:[1,0,0]
	v_cvt_f32_ubyte2_e32 v102, v68
	v_cvt_f32_ubyte3_e32 v103, v68
	v_pk_fma_f32 v[92:93], v[38:39], v[98:99], v[92:93] op_sel_hi:[0,1,1]
	v_cvt_f32_ubyte0_e32 v104, v69
	v_cvt_f32_ubyte1_e32 v105, v69
	v_pk_fma_f32 v[90:91], v[38:39], v[102:103], v[90:91] op_sel_hi:[0,1,1]
	v_cvt_f32_ubyte2_e32 v146, v69
	v_cvt_f32_ubyte3_e32 v147, v69
	v_pk_fma_f32 v[86:87], v[46:47], v[104:105], v[86:87] op_sel_hi:[0,1,1]
	v_cvt_f32_ubyte0_e32 v98, v76
	v_cvt_f32_ubyte1_e32 v99, v76
	v_pk_fma_f32 v[84:85], v[46:47], v[146:147], v[84:85] op_sel_hi:[0,1,1]
	v_and_b32_e32 v82, s0, v174
	v_and_b32_e32 v83, s1, v174
	v_and_b32_e32 v88, s0, v175
	v_and_b32_e32 v89, s1, v175
	v_cvt_f32_ubyte2_e32 v102, v76
	v_cvt_f32_ubyte3_e32 v103, v76
	v_pk_fma_f32 v[80:81], v[38:39], v[98:99], v[80:81] op_sel_hi:[0,1,1]
	v_cvt_f32_ubyte0_e32 v104, v77
	v_cvt_f32_ubyte1_e32 v105, v77
	v_pk_fma_f32 v[78:79], v[38:39], v[102:103], v[78:79] op_sel_hi:[0,1,1]
	v_cvt_f32_ubyte2_e32 v146, v77
	v_cvt_f32_ubyte3_e32 v147, v77
	v_pk_fma_f32 v[70:71], v[46:47], v[104:105], v[70:71] op_sel_hi:[0,1,1]
	v_cvt_f32_ubyte0_e32 v98, v82
	v_cvt_f32_ubyte1_e32 v99, v82
	v_pk_fma_f32 v[62:63], v[46:47], v[146:147], v[62:63] op_sel_hi:[0,1,1]
	v_cvt_f32_ubyte2_e32 v102, v82
	v_cvt_f32_ubyte3_e32 v103, v82
	v_pk_fma_f32 v[92:93], v[38:39], v[98:99], v[92:93] op_sel:[1,0,0]
	v_cvt_f32_ubyte0_e32 v104, v83
	v_cvt_f32_ubyte1_e32 v105, v83
	v_pk_fma_f32 v[90:91], v[38:39], v[102:103], v[90:91] op_sel:[1,0,0]
	v_cvt_f32_ubyte2_e32 v146, v83
	v_cvt_f32_ubyte3_e32 v147, v83
	v_pk_fma_f32 v[86:87], v[46:47], v[104:105], v[86:87] op_sel:[1,0,0]
	v_cvt_f32_ubyte0_e32 v98, v88
	v_cvt_f32_ubyte1_e32 v99, v88
	v_pk_fma_f32 v[84:85], v[46:47], v[146:147], v[84:85] op_sel:[1,0,0]
	v_and_b32_e32 v68, s0, v176
	v_and_b32_e32 v69, s1, v176
	v_and_b32_e32 v76, s0, v177
	v_and_b32_e32 v77, s1, v177
	v_cvt_f32_ubyte2_e32 v102, v88
	v_cvt_f32_ubyte3_e32 v103, v88
	v_pk_fma_f32 v[80:81], v[38:39], v[98:99], v[80:81] op_sel:[1,0,0]
	v_cvt_f32_ubyte0_e32 v104, v89
	v_cvt_f32_ubyte1_e32 v105, v89
	v_pk_fma_f32 v[78:79], v[38:39], v[102:103], v[78:79] op_sel:[1,0,0]
	v_cvt_f32_ubyte2_e32 v146, v89
	v_cvt_f32_ubyte3_e32 v147, v89
	v_pk_fma_f32 v[70:71], v[46:47], v[104:105], v[70:71] op_sel:[1,0,0]
	v_cvt_f32_ubyte0_e32 v98, v68
	v_cvt_f32_ubyte1_e32 v99, v68
	v_pk_fma_f32 v[62:63], v[46:47], v[146:147], v[62:63] op_sel:[1,0,0]
	v_cvt_f32_ubyte2_e32 v102, v68
	v_cvt_f32_ubyte3_e32 v103, v68
	v_pk_fma_f32 v[92:93], v[40:41], v[98:99], v[92:93] op_sel_hi:[0,1,1]
	v_cvt_f32_ubyte0_e32 v104, v69
	v_cvt_f32_ubyte1_e32 v105, v69
	v_pk_fma_f32 v[90:91], v[40:41], v[102:103], v[90:91] op_sel_hi:[0,1,1]
	v_cvt_f32_ubyte2_e32 v146, v69
	v_cvt_f32_ubyte3_e32 v147, v69
	v_pk_fma_f32 v[86:87], v[48:49], v[104:105], v[86:87] op_sel_hi:[0,1,1]
	v_cvt_f32_ubyte0_e32 v98, v76
	v_cvt_f32_ubyte1_e32 v99, v76
	v_pk_fma_f32 v[84:85], v[48:49], v[146:147], v[84:85] op_sel_hi:[0,1,1]
	v_and_b32_e32 v82, s0, v178
	v_and_b32_e32 v83, s1, v178
	v_and_b32_e32 v88, s0, v179
	v_and_b32_e32 v89, s1, v179
	v_cvt_f32_ubyte2_e32 v102, v76
	v_cvt_f32_ubyte3_e32 v103, v76
	v_pk_fma_f32 v[80:81], v[40:41], v[98:99], v[80:81] op_sel_hi:[0,1,1]
	v_cvt_f32_ubyte0_e32 v104, v77
	v_cvt_f32_ubyte1_e32 v105, v77
	v_pk_fma_f32 v[78:79], v[40:41], v[102:103], v[78:79] op_sel_hi:[0,1,1]
	v_cvt_f32_ubyte2_e32 v146, v77
	v_cvt_f32_ubyte3_e32 v147, v77
	v_pk_fma_f32 v[70:71], v[48:49], v[104:105], v[70:71] op_sel_hi:[0,1,1]
	v_cvt_f32_ubyte0_e32 v98, v82
	v_cvt_f32_ubyte1_e32 v99, v82
	v_pk_fma_f32 v[62:63], v[48:49], v[146:147], v[62:63] op_sel_hi:[0,1,1]
	v_cvt_f32_ubyte2_e32 v102, v82
	v_cvt_f32_ubyte3_e32 v103, v82
	v_pk_fma_f32 v[92:93], v[40:41], v[98:99], v[92:93] op_sel:[1,0,0]
	v_cvt_f32_ubyte0_e32 v104, v83
	v_cvt_f32_ubyte1_e32 v105, v83
	v_pk_fma_f32 v[90:91], v[40:41], v[102:103], v[90:91] op_sel:[1,0,0]
	v_cvt_f32_ubyte2_e32 v146, v83
	v_cvt_f32_ubyte3_e32 v147, v83
	v_pk_fma_f32 v[86:87], v[48:49], v[104:105], v[86:87] op_sel:[1,0,0]
	v_cvt_f32_ubyte0_e32 v98, v88
	v_cvt_f32_ubyte1_e32 v99, v88
	v_pk_fma_f32 v[84:85], v[48:49], v[146:147], v[84:85] op_sel:[1,0,0]
	v_cvt_f32_ubyte2_e32 v102, v88
	v_cvt_f32_ubyte3_e32 v103, v88
	v_pk_fma_f32 v[80:81], v[40:41], v[98:99], v[80:81] op_sel:[1,0,0]
	v_cvt_f32_ubyte0_e32 v104, v89
	v_cvt_f32_ubyte1_e32 v105, v89
	v_pk_fma_f32 v[78:79], v[40:41], v[102:103], v[78:79] op_sel:[1,0,0]
	v_cvt_f32_ubyte2_e32 v146, v89
	v_cvt_f32_ubyte3_e32 v147, v89
	v_pk_fma_f32 v[70:71], v[48:49], v[104:105], v[70:71] op_sel:[1,0,0]
	v_pk_fma_f32 v[62:63], v[48:49], v[146:147], v[62:63] op_sel:[1,0,0]
	s_waitcnt lgkmcnt(0)
	v_lshl_add_u32 v72, v72, 9, v100
	v_lshl_add_u32 v73, v73, 9, v100
	v_lshl_add_u32 v74, v74, 9, v100
	v_lshl_add_u32 v75, v75, 9, v100
	v_lshl_add_u32 v94, v94, 9, v100
	v_lshl_add_u32 v95, v95, 9, v100
	v_lshl_add_u32 v96, v96, 9, v100
	v_lshl_add_u32 v97, v97, 9, v100
	global_load_dwordx2 v[164:165], v72, s[38:39]
	global_load_dwordx2 v[166:167], v73, s[38:39]
	global_load_dwordx2 v[168:169], v74, s[38:39]
	global_load_dwordx2 v[170:171], v75, s[38:39]
	global_load_dwordx2 v[172:173], v94, s[38:39]
	global_load_dwordx2 v[174:175], v95, s[38:39]
	global_load_dwordx2 v[176:177], v96, s[38:39]
	global_load_dwordx2 v[178:179], v97, s[38:39]
	ds_read_b128 v[72:75], v1 offset:224
	ds_read_b128 v[94:97], v1 offset:240
	ds_read_b128 v[34:37], v1 offset:576
	ds_read_b128 v[38:41], v1 offset:592
	ds_read_b128 v[42:45], v1 offset:1600
	ds_read_b128 v[46:49], v1 offset:1616
	s_waitcnt vmcnt(40)
	v_and_b32_e32 v68, s0, v180
	v_and_b32_e32 v69, s1, v180
	v_and_b32_e32 v76, s0, v181
	v_and_b32_e32 v77, s1, v181
	v_cvt_f32_ubyte0_e32 v98, v68
	v_cvt_f32_ubyte1_e32 v99, v68
	v_cvt_f32_ubyte2_e32 v102, v68
	v_cvt_f32_ubyte3_e32 v103, v68
	v_pk_fma_f32 v[92:93], v[50:51], v[98:99], v[92:93] op_sel_hi:[0,1,1]
	v_cvt_f32_ubyte0_e32 v104, v69
	v_cvt_f32_ubyte1_e32 v105, v69
	v_pk_fma_f32 v[90:91], v[50:51], v[102:103], v[90:91] op_sel_hi:[0,1,1]
	v_cvt_f32_ubyte2_e32 v146, v69
	v_cvt_f32_ubyte3_e32 v147, v69
	v_pk_fma_f32 v[86:87], v[58:59], v[104:105], v[86:87] op_sel_hi:[0,1,1]
	v_cvt_f32_ubyte0_e32 v98, v76
	v_cvt_f32_ubyte1_e32 v99, v76
	v_pk_fma_f32 v[84:85], v[58:59], v[146:147], v[84:85] op_sel_hi:[0,1,1]
	v_and_b32_e32 v82, s0, v182
	v_and_b32_e32 v83, s1, v182
	v_and_b32_e32 v88, s0, v183
	v_and_b32_e32 v89, s1, v183
	v_cvt_f32_ubyte2_e32 v102, v76
	v_cvt_f32_ubyte3_e32 v103, v76
	v_pk_fma_f32 v[80:81], v[50:51], v[98:99], v[80:81] op_sel_hi:[0,1,1]
	v_cvt_f32_ubyte0_e32 v104, v77
	v_cvt_f32_ubyte1_e32 v105, v77
	v_pk_fma_f32 v[78:79], v[50:51], v[102:103], v[78:79] op_sel_hi:[0,1,1]
	v_cvt_f32_ubyte2_e32 v146, v77
	v_cvt_f32_ubyte3_e32 v147, v77
	v_pk_fma_f32 v[70:71], v[58:59], v[104:105], v[70:71] op_sel_hi:[0,1,1]
	v_cvt_f32_ubyte0_e32 v98, v82
	v_cvt_f32_ubyte1_e32 v99, v82
	v_pk_fma_f32 v[62:63], v[58:59], v[146:147], v[62:63] op_sel_hi:[0,1,1]
	v_cvt_f32_ubyte2_e32 v102, v82
	v_cvt_f32_ubyte3_e32 v103, v82
	v_pk_fma_f32 v[92:93], v[50:51], v[98:99], v[92:93] op_sel:[1,0,0]
	v_cvt_f32_ubyte0_e32 v104, v83
	v_cvt_f32_ubyte1_e32 v105, v83
	v_pk_fma_f32 v[90:91], v[50:51], v[102:103], v[90:91] op_sel:[1,0,0]
	v_cvt_f32_ubyte2_e32 v146, v83
	v_cvt_f32_ubyte3_e32 v147, v83
	v_pk_fma_f32 v[86:87], v[58:59], v[104:105], v[86:87] op_sel:[1,0,0]
	v_cvt_f32_ubyte0_e32 v98, v88
	v_cvt_f32_ubyte1_e32 v99, v88
	v_pk_fma_f32 v[84:85], v[58:59], v[146:147], v[84:85] op_sel:[1,0,0]
	v_and_b32_e32 v68, s0, v184
	v_and_b32_e32 v69, s1, v184
	v_and_b32_e32 v76, s0, v185
	v_and_b32_e32 v77, s1, v185
	v_cvt_f32_ubyte2_e32 v102, v88
	v_cvt_f32_ubyte3_e32 v103, v88
	v_pk_fma_f32 v[80:81], v[50:51], v[98:99], v[80:81] op_sel:[1,0,0]
	v_cvt_f32_ubyte0_e32 v104, v89
	v_cvt_f32_ubyte1_e32 v105, v89
	v_pk_fma_f32 v[78:79], v[50:51], v[102:103], v[78:79] op_sel:[1,0,0]
	v_cvt_f32_ubyte2_e32 v146, v89
	v_cvt_f32_ubyte3_e32 v147, v89
	v_pk_fma_f32 v[70:71], v[58:59], v[104:105], v[70:71] op_sel:[1,0,0]
	v_cvt_f32_ubyte0_e32 v98, v68
	v_cvt_f32_ubyte1_e32 v99, v68
	v_pk_fma_f32 v[62:63], v[58:59], v[146:147], v[62:63] op_sel:[1,0,0]
	v_cvt_f32_ubyte2_e32 v102, v68
	v_cvt_f32_ubyte3_e32 v103, v68
	v_pk_fma_f32 v[92:93], v[52:53], v[98:99], v[92:93] op_sel_hi:[0,1,1]
	v_cvt_f32_ubyte0_e32 v104, v69
	v_cvt_f32_ubyte1_e32 v105, v69
	v_pk_fma_f32 v[90:91], v[52:53], v[102:103], v[90:91] op_sel_hi:[0,1,1]
	v_cvt_f32_ubyte2_e32 v146, v69
	v_cvt_f32_ubyte3_e32 v147, v69
	v_pk_fma_f32 v[86:87], v[60:61], v[104:105], v[86:87] op_sel_hi:[0,1,1]
	v_cvt_f32_ubyte0_e32 v98, v76
	v_cvt_f32_ubyte1_e32 v99, v76
	v_pk_fma_f32 v[84:85], v[60:61], v[146:147], v[84:85] op_sel_hi:[0,1,1]
	v_and_b32_e32 v82, s0, v186
	v_and_b32_e32 v83, s1, v186
	v_and_b32_e32 v88, s0, v187
	v_and_b32_e32 v89, s1, v187
	v_cvt_f32_ubyte2_e32 v102, v76
	v_cvt_f32_ubyte3_e32 v103, v76
	v_pk_fma_f32 v[80:81], v[52:53], v[98:99], v[80:81] op_sel_hi:[0,1,1]
	v_cvt_f32_ubyte0_e32 v104, v77
	v_cvt_f32_ubyte1_e32 v105, v77
	v_pk_fma_f32 v[78:79], v[52:53], v[102:103], v[78:79] op_sel_hi:[0,1,1]
	v_cvt_f32_ubyte2_e32 v146, v77
	v_cvt_f32_ubyte3_e32 v147, v77
	v_pk_fma_f32 v[70:71], v[60:61], v[104:105], v[70:71] op_sel_hi:[0,1,1]
	v_cvt_f32_ubyte0_e32 v98, v82
	v_cvt_f32_ubyte1_e32 v99, v82
	v_pk_fma_f32 v[62:63], v[60:61], v[146:147], v[62:63] op_sel_hi:[0,1,1]
	v_cvt_f32_ubyte2_e32 v102, v82
	v_cvt_f32_ubyte3_e32 v103, v82
	v_pk_fma_f32 v[92:93], v[52:53], v[98:99], v[92:93] op_sel:[1,0,0]
	v_cvt_f32_ubyte0_e32 v104, v83
	v_cvt_f32_ubyte1_e32 v105, v83
	v_pk_fma_f32 v[90:91], v[52:53], v[102:103], v[90:91] op_sel:[1,0,0]
	v_cvt_f32_ubyte2_e32 v146, v83
	v_cvt_f32_ubyte3_e32 v147, v83
	v_pk_fma_f32 v[86:87], v[60:61], v[104:105], v[86:87] op_sel:[1,0,0]
	v_cvt_f32_ubyte0_e32 v98, v88
	v_cvt_f32_ubyte1_e32 v99, v88
	v_pk_fma_f32 v[84:85], v[60:61], v[146:147], v[84:85] op_sel:[1,0,0]
	v_and_b32_e32 v68, s0, v188
	v_and_b32_e32 v69, s1, v188
	v_and_b32_e32 v76, s0, v189
	v_and_b32_e32 v77, s1, v189
	v_cvt_f32_ubyte2_e32 v102, v88
	v_cvt_f32_ubyte3_e32 v103, v88
	v_pk_fma_f32 v[80:81], v[52:53], v[98:99], v[80:81] op_sel:[1,0,0]
	v_cvt_f32_ubyte0_e32 v104, v89
	v_cvt_f32_ubyte1_e32 v105, v89
	v_pk_fma_f32 v[78:79], v[52:53], v[102:103], v[78:79] op_sel:[1,0,0]
	v_cvt_f32_ubyte2_e32 v146, v89
	v_cvt_f32_ubyte3_e32 v147, v89
	v_pk_fma_f32 v[70:71], v[60:61], v[104:105], v[70:71] op_sel:[1,0,0]
	v_cvt_f32_ubyte0_e32 v98, v68
	v_cvt_f32_ubyte1_e32 v99, v68
	v_pk_fma_f32 v[62:63], v[60:61], v[146:147], v[62:63] op_sel:[1,0,0]
	v_cvt_f32_ubyte2_e32 v102, v68
	v_cvt_f32_ubyte3_e32 v103, v68
	v_pk_fma_f32 v[92:93], v[54:55], v[98:99], v[92:93] op_sel_hi:[0,1,1]
	v_cvt_f32_ubyte0_e32 v104, v69
	v_cvt_f32_ubyte1_e32 v105, v69
	v_pk_fma_f32 v[90:91], v[54:55], v[102:103], v[90:91] op_sel_hi:[0,1,1]
	v_cvt_f32_ubyte2_e32 v146, v69
	v_cvt_f32_ubyte3_e32 v147, v69
	v_pk_fma_f32 v[86:87], v[64:65], v[104:105], v[86:87] op_sel_hi:[0,1,1]
	v_cvt_f32_ubyte0_e32 v98, v76
	v_cvt_f32_ubyte1_e32 v99, v76
	v_pk_fma_f32 v[84:85], v[64:65], v[146:147], v[84:85] op_sel_hi:[0,1,1]
	v_and_b32_e32 v82, s0, v190
	v_and_b32_e32 v83, s1, v190
	v_and_b32_e32 v88, s0, v191
	v_and_b32_e32 v89, s1, v191
	v_cvt_f32_ubyte2_e32 v102, v76
	v_cvt_f32_ubyte3_e32 v103, v76
	v_pk_fma_f32 v[80:81], v[54:55], v[98:99], v[80:81] op_sel_hi:[0,1,1]
	v_cvt_f32_ubyte0_e32 v104, v77
	v_cvt_f32_ubyte1_e32 v105, v77
	v_pk_fma_f32 v[78:79], v[54:55], v[102:103], v[78:79] op_sel_hi:[0,1,1]
	v_cvt_f32_ubyte2_e32 v146, v77
	v_cvt_f32_ubyte3_e32 v147, v77
	v_pk_fma_f32 v[70:71], v[64:65], v[104:105], v[70:71] op_sel_hi:[0,1,1]
	v_cvt_f32_ubyte0_e32 v98, v82
	v_cvt_f32_ubyte1_e32 v99, v82
	v_pk_fma_f32 v[62:63], v[64:65], v[146:147], v[62:63] op_sel_hi:[0,1,1]
	v_cvt_f32_ubyte2_e32 v102, v82
	v_cvt_f32_ubyte3_e32 v103, v82
	v_pk_fma_f32 v[92:93], v[54:55], v[98:99], v[92:93] op_sel:[1,0,0]
	v_cvt_f32_ubyte0_e32 v104, v83
	v_cvt_f32_ubyte1_e32 v105, v83
	v_pk_fma_f32 v[90:91], v[54:55], v[102:103], v[90:91] op_sel:[1,0,0]
	v_cvt_f32_ubyte2_e32 v146, v83
	v_cvt_f32_ubyte3_e32 v147, v83
	v_pk_fma_f32 v[86:87], v[64:65], v[104:105], v[86:87] op_sel:[1,0,0]
	v_cvt_f32_ubyte0_e32 v98, v88
	v_cvt_f32_ubyte1_e32 v99, v88
	v_pk_fma_f32 v[84:85], v[64:65], v[146:147], v[84:85] op_sel:[1,0,0]
	v_and_b32_e32 v68, s0, v192
	v_and_b32_e32 v69, s1, v192
	v_and_b32_e32 v76, s0, v193
	v_and_b32_e32 v77, s1, v193
	v_cvt_f32_ubyte2_e32 v102, v88
	v_cvt_f32_ubyte3_e32 v103, v88
	v_pk_fma_f32 v[80:81], v[54:55], v[98:99], v[80:81] op_sel:[1,0,0]
	v_cvt_f32_ubyte0_e32 v104, v89
	v_cvt_f32_ubyte1_e32 v105, v89
	v_pk_fma_f32 v[78:79], v[54:55], v[102:103], v[78:79] op_sel:[1,0,0]
	v_cvt_f32_ubyte2_e32 v146, v89
	v_cvt_f32_ubyte3_e32 v147, v89
	v_pk_fma_f32 v[70:71], v[64:65], v[104:105], v[70:71] op_sel:[1,0,0]
	v_cvt_f32_ubyte0_e32 v98, v68
	v_cvt_f32_ubyte1_e32 v99, v68
	v_pk_fma_f32 v[62:63], v[64:65], v[146:147], v[62:63] op_sel:[1,0,0]
	v_cvt_f32_ubyte2_e32 v102, v68
	v_cvt_f32_ubyte3_e32 v103, v68
	v_pk_fma_f32 v[92:93], v[56:57], v[98:99], v[92:93] op_sel_hi:[0,1,1]
	v_cvt_f32_ubyte0_e32 v104, v69
	v_cvt_f32_ubyte1_e32 v105, v69
	v_pk_fma_f32 v[90:91], v[56:57], v[102:103], v[90:91] op_sel_hi:[0,1,1]
	v_cvt_f32_ubyte2_e32 v146, v69
	v_cvt_f32_ubyte3_e32 v147, v69
	v_pk_fma_f32 v[86:87], v[66:67], v[104:105], v[86:87] op_sel_hi:[0,1,1]
	v_cvt_f32_ubyte0_e32 v98, v76
	v_cvt_f32_ubyte1_e32 v99, v76
	v_pk_fma_f32 v[84:85], v[66:67], v[146:147], v[84:85] op_sel_hi:[0,1,1]
	v_and_b32_e32 v82, s0, v194
	v_and_b32_e32 v83, s1, v194
	v_and_b32_e32 v88, s0, v195
	v_and_b32_e32 v89, s1, v195
	v_cvt_f32_ubyte2_e32 v102, v76
	v_cvt_f32_ubyte3_e32 v103, v76
	v_pk_fma_f32 v[80:81], v[56:57], v[98:99], v[80:81] op_sel_hi:[0,1,1]
	v_cvt_f32_ubyte0_e32 v104, v77
	v_cvt_f32_ubyte1_e32 v105, v77
	v_pk_fma_f32 v[78:79], v[56:57], v[102:103], v[78:79] op_sel_hi:[0,1,1]
	v_cvt_f32_ubyte2_e32 v146, v77
	v_cvt_f32_ubyte3_e32 v147, v77
	v_pk_fma_f32 v[70:71], v[66:67], v[104:105], v[70:71] op_sel_hi:[0,1,1]
	v_cvt_f32_ubyte0_e32 v98, v82
	v_cvt_f32_ubyte1_e32 v99, v82
	v_pk_fma_f32 v[62:63], v[66:67], v[146:147], v[62:63] op_sel_hi:[0,1,1]
	v_cvt_f32_ubyte2_e32 v102, v82
	v_cvt_f32_ubyte3_e32 v103, v82
	v_pk_fma_f32 v[92:93], v[56:57], v[98:99], v[92:93] op_sel:[1,0,0]
	v_cvt_f32_ubyte0_e32 v104, v83
	v_cvt_f32_ubyte1_e32 v105, v83
	v_pk_fma_f32 v[90:91], v[56:57], v[102:103], v[90:91] op_sel:[1,0,0]
	v_cvt_f32_ubyte2_e32 v146, v83
	v_cvt_f32_ubyte3_e32 v147, v83
	v_pk_fma_f32 v[86:87], v[66:67], v[104:105], v[86:87] op_sel:[1,0,0]
	v_cvt_f32_ubyte0_e32 v98, v88
	v_cvt_f32_ubyte1_e32 v99, v88
	v_pk_fma_f32 v[84:85], v[66:67], v[146:147], v[84:85] op_sel:[1,0,0]
	v_cvt_f32_ubyte2_e32 v102, v88
	v_cvt_f32_ubyte3_e32 v103, v88
	v_pk_fma_f32 v[80:81], v[56:57], v[98:99], v[80:81] op_sel:[1,0,0]
	v_cvt_f32_ubyte0_e32 v104, v89
	v_cvt_f32_ubyte1_e32 v105, v89
	v_pk_fma_f32 v[78:79], v[56:57], v[102:103], v[78:79] op_sel:[1,0,0]
	v_cvt_f32_ubyte2_e32 v146, v89
	v_cvt_f32_ubyte3_e32 v147, v89
	v_pk_fma_f32 v[70:71], v[66:67], v[104:105], v[70:71] op_sel:[1,0,0]
	v_pk_fma_f32 v[62:63], v[66:67], v[146:147], v[62:63] op_sel:[1,0,0]
	s_waitcnt lgkmcnt(0)
	v_lshl_add_u32 v72, v72, 9, v100
	v_lshl_add_u32 v73, v73, 9, v100
	v_lshl_add_u32 v74, v74, 9, v100
	v_lshl_add_u32 v75, v75, 9, v100
	v_lshl_add_u32 v94, v94, 9, v100
	v_lshl_add_u32 v95, v95, 9, v100
	v_lshl_add_u32 v96, v96, 9, v100
	v_lshl_add_u32 v97, v97, 9, v100
	global_load_dwordx2 v[180:181], v72, s[38:39]
	global_load_dwordx2 v[182:183], v73, s[38:39]
	global_load_dwordx2 v[184:185], v74, s[38:39]
	global_load_dwordx2 v[186:187], v75, s[38:39]
	global_load_dwordx2 v[188:189], v94, s[38:39]
	global_load_dwordx2 v[190:191], v95, s[38:39]
	global_load_dwordx2 v[192:193], v96, s[38:39]
	global_load_dwordx2 v[194:195], v97, s[38:39]
	ds_read_b128 v[72:75], v1 offset:256
	ds_read_b128 v[94:97], v1 offset:272
	ds_read_b128 v[50:53], v1 offset:608
	ds_read_b128 v[54:57], v1 offset:624
	ds_read_b128 v[58:61], v1 offset:1632
	ds_read_b128 v[64:67], v1 offset:1648
	s_waitcnt vmcnt(40)
	v_and_b32_e32 v68, s0, v196
	v_and_b32_e32 v69, s1, v196
	v_and_b32_e32 v76, s0, v197
	v_and_b32_e32 v77, s1, v197
	v_cvt_f32_ubyte0_e32 v98, v68
	v_cvt_f32_ubyte1_e32 v99, v68
	v_cvt_f32_ubyte2_e32 v102, v68
	v_cvt_f32_ubyte3_e32 v103, v68
	v_pk_fma_f32 v[92:93], v[34:35], v[98:99], v[92:93] op_sel_hi:[0,1,1]
	v_cvt_f32_ubyte0_e32 v104, v69
	v_cvt_f32_ubyte1_e32 v105, v69
	v_pk_fma_f32 v[90:91], v[34:35], v[102:103], v[90:91] op_sel_hi:[0,1,1]
	v_cvt_f32_ubyte2_e32 v146, v69
	v_cvt_f32_ubyte3_e32 v147, v69
	v_pk_fma_f32 v[86:87], v[42:43], v[104:105], v[86:87] op_sel_hi:[0,1,1]
	v_cvt_f32_ubyte0_e32 v98, v76
	v_cvt_f32_ubyte1_e32 v99, v76
	v_pk_fma_f32 v[84:85], v[42:43], v[146:147], v[84:85] op_sel_hi:[0,1,1]
	v_and_b32_e32 v82, s0, v198
	v_and_b32_e32 v83, s1, v198
	v_and_b32_e32 v88, s0, v199
	v_and_b32_e32 v89, s1, v199
	v_cvt_f32_ubyte2_e32 v102, v76
	v_cvt_f32_ubyte3_e32 v103, v76
	v_pk_fma_f32 v[80:81], v[34:35], v[98:99], v[80:81] op_sel_hi:[0,1,1]
	v_cvt_f32_ubyte0_e32 v104, v77
	v_cvt_f32_ubyte1_e32 v105, v77
	v_pk_fma_f32 v[78:79], v[34:35], v[102:103], v[78:79] op_sel_hi:[0,1,1]
	v_cvt_f32_ubyte2_e32 v146, v77
	v_cvt_f32_ubyte3_e32 v147, v77
	v_pk_fma_f32 v[70:71], v[42:43], v[104:105], v[70:71] op_sel_hi:[0,1,1]
	v_cvt_f32_ubyte0_e32 v98, v82
	v_cvt_f32_ubyte1_e32 v99, v82
	v_pk_fma_f32 v[62:63], v[42:43], v[146:147], v[62:63] op_sel_hi:[0,1,1]
	v_cvt_f32_ubyte2_e32 v102, v82
	v_cvt_f32_ubyte3_e32 v103, v82
	v_pk_fma_f32 v[92:93], v[34:35], v[98:99], v[92:93] op_sel:[1,0,0]
	v_cvt_f32_ubyte0_e32 v104, v83
	v_cvt_f32_ubyte1_e32 v105, v83
	v_pk_fma_f32 v[90:91], v[34:35], v[102:103], v[90:91] op_sel:[1,0,0]
	v_cvt_f32_ubyte2_e32 v146, v83
	v_cvt_f32_ubyte3_e32 v147, v83
	v_pk_fma_f32 v[86:87], v[42:43], v[104:105], v[86:87] op_sel:[1,0,0]
	v_cvt_f32_ubyte0_e32 v98, v88
	v_cvt_f32_ubyte1_e32 v99, v88
	v_pk_fma_f32 v[84:85], v[42:43], v[146:147], v[84:85] op_sel:[1,0,0]
	v_and_b32_e32 v68, s0, v200
	v_and_b32_e32 v69, s1, v200
	v_and_b32_e32 v76, s0, v201
	v_and_b32_e32 v77, s1, v201
	v_cvt_f32_ubyte2_e32 v102, v88
	v_cvt_f32_ubyte3_e32 v103, v88
	v_pk_fma_f32 v[80:81], v[34:35], v[98:99], v[80:81] op_sel:[1,0,0]
	v_cvt_f32_ubyte0_e32 v104, v89
	v_cvt_f32_ubyte1_e32 v105, v89
	v_pk_fma_f32 v[78:79], v[34:35], v[102:103], v[78:79] op_sel:[1,0,0]
	v_cvt_f32_ubyte2_e32 v146, v89
	v_cvt_f32_ubyte3_e32 v147, v89
	v_pk_fma_f32 v[70:71], v[42:43], v[104:105], v[70:71] op_sel:[1,0,0]
	v_cvt_f32_ubyte0_e32 v98, v68
	v_cvt_f32_ubyte1_e32 v99, v68
	v_pk_fma_f32 v[62:63], v[42:43], v[146:147], v[62:63] op_sel:[1,0,0]
	v_cvt_f32_ubyte2_e32 v102, v68
	v_cvt_f32_ubyte3_e32 v103, v68
	v_pk_fma_f32 v[92:93], v[36:37], v[98:99], v[92:93] op_sel_hi:[0,1,1]
	v_cvt_f32_ubyte0_e32 v104, v69
	v_cvt_f32_ubyte1_e32 v105, v69
	v_pk_fma_f32 v[90:91], v[36:37], v[102:103], v[90:91] op_sel_hi:[0,1,1]
	v_cvt_f32_ubyte2_e32 v146, v69
	v_cvt_f32_ubyte3_e32 v147, v69
	v_pk_fma_f32 v[86:87], v[44:45], v[104:105], v[86:87] op_sel_hi:[0,1,1]
	v_cvt_f32_ubyte0_e32 v98, v76
	v_cvt_f32_ubyte1_e32 v99, v76
	v_pk_fma_f32 v[84:85], v[44:45], v[146:147], v[84:85] op_sel_hi:[0,1,1]
	v_and_b32_e32 v82, s0, v202
	v_and_b32_e32 v83, s1, v202
	v_and_b32_e32 v88, s0, v203
	v_and_b32_e32 v89, s1, v203
	v_cvt_f32_ubyte2_e32 v102, v76
	v_cvt_f32_ubyte3_e32 v103, v76
	v_pk_fma_f32 v[80:81], v[36:37], v[98:99], v[80:81] op_sel_hi:[0,1,1]
	v_cvt_f32_ubyte0_e32 v104, v77
	v_cvt_f32_ubyte1_e32 v105, v77
	v_pk_fma_f32 v[78:79], v[36:37], v[102:103], v[78:79] op_sel_hi:[0,1,1]
	v_cvt_f32_ubyte2_e32 v146, v77
	v_cvt_f32_ubyte3_e32 v147, v77
	v_pk_fma_f32 v[70:71], v[44:45], v[104:105], v[70:71] op_sel_hi:[0,1,1]
	v_cvt_f32_ubyte0_e32 v98, v82
	v_cvt_f32_ubyte1_e32 v99, v82
	v_pk_fma_f32 v[62:63], v[44:45], v[146:147], v[62:63] op_sel_hi:[0,1,1]
	v_cvt_f32_ubyte2_e32 v102, v82
	v_cvt_f32_ubyte3_e32 v103, v82
	v_pk_fma_f32 v[92:93], v[36:37], v[98:99], v[92:93] op_sel:[1,0,0]
	v_cvt_f32_ubyte0_e32 v104, v83
	v_cvt_f32_ubyte1_e32 v105, v83
	v_pk_fma_f32 v[90:91], v[36:37], v[102:103], v[90:91] op_sel:[1,0,0]
	v_cvt_f32_ubyte2_e32 v146, v83
	v_cvt_f32_ubyte3_e32 v147, v83
	v_pk_fma_f32 v[86:87], v[44:45], v[104:105], v[86:87] op_sel:[1,0,0]
	v_cvt_f32_ubyte0_e32 v98, v88
	v_cvt_f32_ubyte1_e32 v99, v88
	v_pk_fma_f32 v[84:85], v[44:45], v[146:147], v[84:85] op_sel:[1,0,0]
	v_and_b32_e32 v68, s0, v204
	v_and_b32_e32 v69, s1, v204
	v_and_b32_e32 v76, s0, v205
	v_and_b32_e32 v77, s1, v205
	v_cvt_f32_ubyte2_e32 v102, v88
	v_cvt_f32_ubyte3_e32 v103, v88
	v_pk_fma_f32 v[80:81], v[36:37], v[98:99], v[80:81] op_sel:[1,0,0]
	v_cvt_f32_ubyte0_e32 v104, v89
	v_cvt_f32_ubyte1_e32 v105, v89
	v_pk_fma_f32 v[78:79], v[36:37], v[102:103], v[78:79] op_sel:[1,0,0]
	v_cvt_f32_ubyte2_e32 v146, v89
	v_cvt_f32_ubyte3_e32 v147, v89
	v_pk_fma_f32 v[70:71], v[44:45], v[104:105], v[70:71] op_sel:[1,0,0]
	v_cvt_f32_ubyte0_e32 v98, v68
	v_cvt_f32_ubyte1_e32 v99, v68
	v_pk_fma_f32 v[62:63], v[44:45], v[146:147], v[62:63] op_sel:[1,0,0]
	v_cvt_f32_ubyte2_e32 v102, v68
	v_cvt_f32_ubyte3_e32 v103, v68
	v_pk_fma_f32 v[92:93], v[38:39], v[98:99], v[92:93] op_sel_hi:[0,1,1]
	v_cvt_f32_ubyte0_e32 v104, v69
	v_cvt_f32_ubyte1_e32 v105, v69
	v_pk_fma_f32 v[90:91], v[38:39], v[102:103], v[90:91] op_sel_hi:[0,1,1]
	v_cvt_f32_ubyte2_e32 v146, v69
	v_cvt_f32_ubyte3_e32 v147, v69
	v_pk_fma_f32 v[86:87], v[46:47], v[104:105], v[86:87] op_sel_hi:[0,1,1]
	v_cvt_f32_ubyte0_e32 v98, v76
	v_cvt_f32_ubyte1_e32 v99, v76
	v_pk_fma_f32 v[84:85], v[46:47], v[146:147], v[84:85] op_sel_hi:[0,1,1]
	v_and_b32_e32 v82, s0, v206
	v_and_b32_e32 v83, s1, v206
	v_and_b32_e32 v88, s0, v207
	v_and_b32_e32 v89, s1, v207
	v_cvt_f32_ubyte2_e32 v102, v76
	v_cvt_f32_ubyte3_e32 v103, v76
	v_pk_fma_f32 v[80:81], v[38:39], v[98:99], v[80:81] op_sel_hi:[0,1,1]
	v_cvt_f32_ubyte0_e32 v104, v77
	v_cvt_f32_ubyte1_e32 v105, v77
	v_pk_fma_f32 v[78:79], v[38:39], v[102:103], v[78:79] op_sel_hi:[0,1,1]
	v_cvt_f32_ubyte2_e32 v146, v77
	v_cvt_f32_ubyte3_e32 v147, v77
	v_pk_fma_f32 v[70:71], v[46:47], v[104:105], v[70:71] op_sel_hi:[0,1,1]
	v_cvt_f32_ubyte0_e32 v98, v82
	v_cvt_f32_ubyte1_e32 v99, v82
	v_pk_fma_f32 v[62:63], v[46:47], v[146:147], v[62:63] op_sel_hi:[0,1,1]
	v_cvt_f32_ubyte2_e32 v102, v82
	v_cvt_f32_ubyte3_e32 v103, v82
	v_pk_fma_f32 v[92:93], v[38:39], v[98:99], v[92:93] op_sel:[1,0,0]
	v_cvt_f32_ubyte0_e32 v104, v83
	v_cvt_f32_ubyte1_e32 v105, v83
	v_pk_fma_f32 v[90:91], v[38:39], v[102:103], v[90:91] op_sel:[1,0,0]
	v_cvt_f32_ubyte2_e32 v146, v83
	v_cvt_f32_ubyte3_e32 v147, v83
	v_pk_fma_f32 v[86:87], v[46:47], v[104:105], v[86:87] op_sel:[1,0,0]
	v_cvt_f32_ubyte0_e32 v98, v88
	v_cvt_f32_ubyte1_e32 v99, v88
	v_pk_fma_f32 v[84:85], v[46:47], v[146:147], v[84:85] op_sel:[1,0,0]
	v_and_b32_e32 v68, s0, v208
	v_and_b32_e32 v69, s1, v208
	v_and_b32_e32 v76, s0, v209
	v_and_b32_e32 v77, s1, v209
	v_cvt_f32_ubyte2_e32 v102, v88
	v_cvt_f32_ubyte3_e32 v103, v88
	v_pk_fma_f32 v[80:81], v[38:39], v[98:99], v[80:81] op_sel:[1,0,0]
	v_cvt_f32_ubyte0_e32 v104, v89
	v_cvt_f32_ubyte1_e32 v105, v89
	v_pk_fma_f32 v[78:79], v[38:39], v[102:103], v[78:79] op_sel:[1,0,0]
	v_cvt_f32_ubyte2_e32 v146, v89
	v_cvt_f32_ubyte3_e32 v147, v89
	v_pk_fma_f32 v[70:71], v[46:47], v[104:105], v[70:71] op_sel:[1,0,0]
	v_cvt_f32_ubyte0_e32 v98, v68
	v_cvt_f32_ubyte1_e32 v99, v68
	v_pk_fma_f32 v[62:63], v[46:47], v[146:147], v[62:63] op_sel:[1,0,0]
	v_cvt_f32_ubyte2_e32 v102, v68
	v_cvt_f32_ubyte3_e32 v103, v68
	v_pk_fma_f32 v[92:93], v[40:41], v[98:99], v[92:93] op_sel_hi:[0,1,1]
	v_cvt_f32_ubyte0_e32 v104, v69
	v_cvt_f32_ubyte1_e32 v105, v69
	v_pk_fma_f32 v[90:91], v[40:41], v[102:103], v[90:91] op_sel_hi:[0,1,1]
	v_cvt_f32_ubyte2_e32 v146, v69
	v_cvt_f32_ubyte3_e32 v147, v69
	v_pk_fma_f32 v[86:87], v[48:49], v[104:105], v[86:87] op_sel_hi:[0,1,1]
	v_cvt_f32_ubyte0_e32 v98, v76
	v_cvt_f32_ubyte1_e32 v99, v76
	v_pk_fma_f32 v[84:85], v[48:49], v[146:147], v[84:85] op_sel_hi:[0,1,1]
	v_and_b32_e32 v82, s0, v210
	v_and_b32_e32 v83, s1, v210
	v_and_b32_e32 v88, s0, v211
	v_and_b32_e32 v89, s1, v211
	v_cvt_f32_ubyte2_e32 v102, v76
	v_cvt_f32_ubyte3_e32 v103, v76
	v_pk_fma_f32 v[80:81], v[40:41], v[98:99], v[80:81] op_sel_hi:[0,1,1]
	v_cvt_f32_ubyte0_e32 v104, v77
	v_cvt_f32_ubyte1_e32 v105, v77
	v_pk_fma_f32 v[78:79], v[40:41], v[102:103], v[78:79] op_sel_hi:[0,1,1]
	v_cvt_f32_ubyte2_e32 v146, v77
	v_cvt_f32_ubyte3_e32 v147, v77
	v_pk_fma_f32 v[70:71], v[48:49], v[104:105], v[70:71] op_sel_hi:[0,1,1]
	v_cvt_f32_ubyte0_e32 v98, v82
	v_cvt_f32_ubyte1_e32 v99, v82
	v_pk_fma_f32 v[62:63], v[48:49], v[146:147], v[62:63] op_sel_hi:[0,1,1]
	v_cvt_f32_ubyte2_e32 v102, v82
	v_cvt_f32_ubyte3_e32 v103, v82
	v_pk_fma_f32 v[92:93], v[40:41], v[98:99], v[92:93] op_sel:[1,0,0]
	v_cvt_f32_ubyte0_e32 v104, v83
	v_cvt_f32_ubyte1_e32 v105, v83
	v_pk_fma_f32 v[90:91], v[40:41], v[102:103], v[90:91] op_sel:[1,0,0]
	v_cvt_f32_ubyte2_e32 v146, v83
	v_cvt_f32_ubyte3_e32 v147, v83
	v_pk_fma_f32 v[86:87], v[48:49], v[104:105], v[86:87] op_sel:[1,0,0]
	v_cvt_f32_ubyte0_e32 v98, v88
	v_cvt_f32_ubyte1_e32 v99, v88
	v_pk_fma_f32 v[84:85], v[48:49], v[146:147], v[84:85] op_sel:[1,0,0]
	v_cvt_f32_ubyte2_e32 v102, v88
	v_cvt_f32_ubyte3_e32 v103, v88
	v_pk_fma_f32 v[80:81], v[40:41], v[98:99], v[80:81] op_sel:[1,0,0]
	v_cvt_f32_ubyte0_e32 v104, v89
	v_cvt_f32_ubyte1_e32 v105, v89
	v_pk_fma_f32 v[78:79], v[40:41], v[102:103], v[78:79] op_sel:[1,0,0]
	v_cvt_f32_ubyte2_e32 v146, v89
	v_cvt_f32_ubyte3_e32 v147, v89
	v_pk_fma_f32 v[70:71], v[48:49], v[104:105], v[70:71] op_sel:[1,0,0]
	v_pk_fma_f32 v[62:63], v[48:49], v[146:147], v[62:63] op_sel:[1,0,0]
	s_waitcnt lgkmcnt(0)
	v_lshl_add_u32 v72, v72, 9, v100
	v_lshl_add_u32 v73, v73, 9, v100
	v_lshl_add_u32 v74, v74, 9, v100
	v_lshl_add_u32 v75, v75, 9, v100
	v_lshl_add_u32 v94, v94, 9, v100
	v_lshl_add_u32 v95, v95, 9, v100
	v_lshl_add_u32 v96, v96, 9, v100
	v_lshl_add_u32 v97, v97, 9, v100
	global_load_dwordx2 v[196:197], v72, s[38:39]
	global_load_dwordx2 v[198:199], v73, s[38:39]
	global_load_dwordx2 v[200:201], v74, s[38:39]
	global_load_dwordx2 v[202:203], v75, s[38:39]
	global_load_dwordx2 v[204:205], v94, s[38:39]
	global_load_dwordx2 v[206:207], v95, s[38:39]
	global_load_dwordx2 v[208:209], v96, s[38:39]
	global_load_dwordx2 v[210:211], v97, s[38:39]
	ds_read_b128 v[72:75], v1 offset:288
	ds_read_b128 v[94:97], v1 offset:304
	ds_read_b128 v[34:37], v1 offset:640
	ds_read_b128 v[38:41], v1 offset:656
	ds_read_b128 v[42:45], v1 offset:1664
	ds_read_b128 v[46:49], v1 offset:1680
	s_waitcnt vmcnt(40)
	v_and_b32_e32 v68, s0, v212
	v_and_b32_e32 v69, s1, v212
	v_and_b32_e32 v76, s0, v213
	v_and_b32_e32 v77, s1, v213
	v_cvt_f32_ubyte0_e32 v98, v68
	v_cvt_f32_ubyte1_e32 v99, v68
	v_cvt_f32_ubyte2_e32 v102, v68
	v_cvt_f32_ubyte3_e32 v103, v68
	v_pk_fma_f32 v[92:93], v[50:51], v[98:99], v[92:93] op_sel_hi:[0,1,1]
	v_cvt_f32_ubyte0_e32 v104, v69
	v_cvt_f32_ubyte1_e32 v105, v69
	v_pk_fma_f32 v[90:91], v[50:51], v[102:103], v[90:91] op_sel_hi:[0,1,1]
	v_cvt_f32_ubyte2_e32 v146, v69
	v_cvt_f32_ubyte3_e32 v147, v69
	v_pk_fma_f32 v[86:87], v[58:59], v[104:105], v[86:87] op_sel_hi:[0,1,1]
	v_cvt_f32_ubyte0_e32 v98, v76
	v_cvt_f32_ubyte1_e32 v99, v76
	v_pk_fma_f32 v[84:85], v[58:59], v[146:147], v[84:85] op_sel_hi:[0,1,1]
	v_and_b32_e32 v82, s0, v214
	v_and_b32_e32 v83, s1, v214
	v_and_b32_e32 v88, s0, v215
	v_and_b32_e32 v89, s1, v215
	v_cvt_f32_ubyte2_e32 v102, v76
	v_cvt_f32_ubyte3_e32 v103, v76
	v_pk_fma_f32 v[80:81], v[50:51], v[98:99], v[80:81] op_sel_hi:[0,1,1]
	v_cvt_f32_ubyte0_e32 v104, v77
	v_cvt_f32_ubyte1_e32 v105, v77
	v_pk_fma_f32 v[78:79], v[50:51], v[102:103], v[78:79] op_sel_hi:[0,1,1]
	v_cvt_f32_ubyte2_e32 v146, v77
	v_cvt_f32_ubyte3_e32 v147, v77
	v_pk_fma_f32 v[70:71], v[58:59], v[104:105], v[70:71] op_sel_hi:[0,1,1]
	v_cvt_f32_ubyte0_e32 v98, v82
	v_cvt_f32_ubyte1_e32 v99, v82
	v_pk_fma_f32 v[62:63], v[58:59], v[146:147], v[62:63] op_sel_hi:[0,1,1]
	v_cvt_f32_ubyte2_e32 v102, v82
	v_cvt_f32_ubyte3_e32 v103, v82
	v_pk_fma_f32 v[92:93], v[50:51], v[98:99], v[92:93] op_sel:[1,0,0]
	v_cvt_f32_ubyte0_e32 v104, v83
	v_cvt_f32_ubyte1_e32 v105, v83
	v_pk_fma_f32 v[90:91], v[50:51], v[102:103], v[90:91] op_sel:[1,0,0]
	v_cvt_f32_ubyte2_e32 v146, v83
	v_cvt_f32_ubyte3_e32 v147, v83
	v_pk_fma_f32 v[86:87], v[58:59], v[104:105], v[86:87] op_sel:[1,0,0]
	v_cvt_f32_ubyte0_e32 v98, v88
	v_cvt_f32_ubyte1_e32 v99, v88
	v_pk_fma_f32 v[84:85], v[58:59], v[146:147], v[84:85] op_sel:[1,0,0]
	v_and_b32_e32 v68, s0, v216
	v_and_b32_e32 v69, s1, v216
	v_and_b32_e32 v76, s0, v217
	v_and_b32_e32 v77, s1, v217
	v_cvt_f32_ubyte2_e32 v102, v88
	v_cvt_f32_ubyte3_e32 v103, v88
	v_pk_fma_f32 v[80:81], v[50:51], v[98:99], v[80:81] op_sel:[1,0,0]
	v_cvt_f32_ubyte0_e32 v104, v89
	v_cvt_f32_ubyte1_e32 v105, v89
	v_pk_fma_f32 v[78:79], v[50:51], v[102:103], v[78:79] op_sel:[1,0,0]
	v_cvt_f32_ubyte2_e32 v146, v89
	v_cvt_f32_ubyte3_e32 v147, v89
	v_pk_fma_f32 v[70:71], v[58:59], v[104:105], v[70:71] op_sel:[1,0,0]
	v_cvt_f32_ubyte0_e32 v98, v68
	v_cvt_f32_ubyte1_e32 v99, v68
	v_pk_fma_f32 v[62:63], v[58:59], v[146:147], v[62:63] op_sel:[1,0,0]
	v_cvt_f32_ubyte2_e32 v102, v68
	v_cvt_f32_ubyte3_e32 v103, v68
	v_pk_fma_f32 v[92:93], v[52:53], v[98:99], v[92:93] op_sel_hi:[0,1,1]
	v_cvt_f32_ubyte0_e32 v104, v69
	v_cvt_f32_ubyte1_e32 v105, v69
	v_pk_fma_f32 v[90:91], v[52:53], v[102:103], v[90:91] op_sel_hi:[0,1,1]
	v_cvt_f32_ubyte2_e32 v146, v69
	v_cvt_f32_ubyte3_e32 v147, v69
	v_pk_fma_f32 v[86:87], v[60:61], v[104:105], v[86:87] op_sel_hi:[0,1,1]
	v_cvt_f32_ubyte0_e32 v98, v76
	v_cvt_f32_ubyte1_e32 v99, v76
	v_pk_fma_f32 v[84:85], v[60:61], v[146:147], v[84:85] op_sel_hi:[0,1,1]
	v_and_b32_e32 v82, s0, v218
	v_and_b32_e32 v83, s1, v218
	v_and_b32_e32 v88, s0, v219
	v_and_b32_e32 v89, s1, v219
	v_cvt_f32_ubyte2_e32 v102, v76
	v_cvt_f32_ubyte3_e32 v103, v76
	v_pk_fma_f32 v[80:81], v[52:53], v[98:99], v[80:81] op_sel_hi:[0,1,1]
	v_cvt_f32_ubyte0_e32 v104, v77
	v_cvt_f32_ubyte1_e32 v105, v77
	v_pk_fma_f32 v[78:79], v[52:53], v[102:103], v[78:79] op_sel_hi:[0,1,1]
	v_cvt_f32_ubyte2_e32 v146, v77
	v_cvt_f32_ubyte3_e32 v147, v77
	v_pk_fma_f32 v[70:71], v[60:61], v[104:105], v[70:71] op_sel_hi:[0,1,1]
	v_cvt_f32_ubyte0_e32 v98, v82
	v_cvt_f32_ubyte1_e32 v99, v82
	v_pk_fma_f32 v[62:63], v[60:61], v[146:147], v[62:63] op_sel_hi:[0,1,1]
	v_cvt_f32_ubyte2_e32 v102, v82
	v_cvt_f32_ubyte3_e32 v103, v82
	v_pk_fma_f32 v[92:93], v[52:53], v[98:99], v[92:93] op_sel:[1,0,0]
	v_cvt_f32_ubyte0_e32 v104, v83
	v_cvt_f32_ubyte1_e32 v105, v83
	v_pk_fma_f32 v[90:91], v[52:53], v[102:103], v[90:91] op_sel:[1,0,0]
	v_cvt_f32_ubyte2_e32 v146, v83
	v_cvt_f32_ubyte3_e32 v147, v83
	v_pk_fma_f32 v[86:87], v[60:61], v[104:105], v[86:87] op_sel:[1,0,0]
	v_cvt_f32_ubyte0_e32 v98, v88
	v_cvt_f32_ubyte1_e32 v99, v88
	v_pk_fma_f32 v[84:85], v[60:61], v[146:147], v[84:85] op_sel:[1,0,0]
	v_and_b32_e32 v68, s0, v220
	v_and_b32_e32 v69, s1, v220
	v_and_b32_e32 v76, s0, v221
	v_and_b32_e32 v77, s1, v221
	v_cvt_f32_ubyte2_e32 v102, v88
	v_cvt_f32_ubyte3_e32 v103, v88
	v_pk_fma_f32 v[80:81], v[52:53], v[98:99], v[80:81] op_sel:[1,0,0]
	v_cvt_f32_ubyte0_e32 v104, v89
	v_cvt_f32_ubyte1_e32 v105, v89
	v_pk_fma_f32 v[78:79], v[52:53], v[102:103], v[78:79] op_sel:[1,0,0]
	v_cvt_f32_ubyte2_e32 v146, v89
	v_cvt_f32_ubyte3_e32 v147, v89
	v_pk_fma_f32 v[70:71], v[60:61], v[104:105], v[70:71] op_sel:[1,0,0]
	v_cvt_f32_ubyte0_e32 v98, v68
	v_cvt_f32_ubyte1_e32 v99, v68
	v_pk_fma_f32 v[62:63], v[60:61], v[146:147], v[62:63] op_sel:[1,0,0]
	v_cvt_f32_ubyte2_e32 v102, v68
	v_cvt_f32_ubyte3_e32 v103, v68
	v_pk_fma_f32 v[92:93], v[54:55], v[98:99], v[92:93] op_sel_hi:[0,1,1]
	v_cvt_f32_ubyte0_e32 v104, v69
	v_cvt_f32_ubyte1_e32 v105, v69
	v_pk_fma_f32 v[90:91], v[54:55], v[102:103], v[90:91] op_sel_hi:[0,1,1]
	v_cvt_f32_ubyte2_e32 v146, v69
	v_cvt_f32_ubyte3_e32 v147, v69
	v_pk_fma_f32 v[86:87], v[64:65], v[104:105], v[86:87] op_sel_hi:[0,1,1]
	v_cvt_f32_ubyte0_e32 v98, v76
	v_cvt_f32_ubyte1_e32 v99, v76
	v_pk_fma_f32 v[84:85], v[64:65], v[146:147], v[84:85] op_sel_hi:[0,1,1]
	v_and_b32_e32 v82, s0, v222
	v_and_b32_e32 v83, s1, v222
	v_and_b32_e32 v88, s0, v223
	v_and_b32_e32 v89, s1, v223
	v_cvt_f32_ubyte2_e32 v102, v76
	v_cvt_f32_ubyte3_e32 v103, v76
	v_pk_fma_f32 v[80:81], v[54:55], v[98:99], v[80:81] op_sel_hi:[0,1,1]
	v_cvt_f32_ubyte0_e32 v104, v77
	v_cvt_f32_ubyte1_e32 v105, v77
	v_pk_fma_f32 v[78:79], v[54:55], v[102:103], v[78:79] op_sel_hi:[0,1,1]
	v_cvt_f32_ubyte2_e32 v146, v77
	v_cvt_f32_ubyte3_e32 v147, v77
	v_pk_fma_f32 v[70:71], v[64:65], v[104:105], v[70:71] op_sel_hi:[0,1,1]
	v_cvt_f32_ubyte0_e32 v98, v82
	v_cvt_f32_ubyte1_e32 v99, v82
	v_pk_fma_f32 v[62:63], v[64:65], v[146:147], v[62:63] op_sel_hi:[0,1,1]
	v_cvt_f32_ubyte2_e32 v102, v82
	v_cvt_f32_ubyte3_e32 v103, v82
	v_pk_fma_f32 v[92:93], v[54:55], v[98:99], v[92:93] op_sel:[1,0,0]
	v_cvt_f32_ubyte0_e32 v104, v83
	v_cvt_f32_ubyte1_e32 v105, v83
	v_pk_fma_f32 v[90:91], v[54:55], v[102:103], v[90:91] op_sel:[1,0,0]
	v_cvt_f32_ubyte2_e32 v146, v83
	v_cvt_f32_ubyte3_e32 v147, v83
	v_pk_fma_f32 v[86:87], v[64:65], v[104:105], v[86:87] op_sel:[1,0,0]
	v_cvt_f32_ubyte0_e32 v98, v88
	v_cvt_f32_ubyte1_e32 v99, v88
	v_pk_fma_f32 v[84:85], v[64:65], v[146:147], v[84:85] op_sel:[1,0,0]
	v_and_b32_e32 v68, s0, v224
	v_and_b32_e32 v69, s1, v224
	v_and_b32_e32 v76, s0, v225
	v_and_b32_e32 v77, s1, v225
	v_cvt_f32_ubyte2_e32 v102, v88
	v_cvt_f32_ubyte3_e32 v103, v88
	v_pk_fma_f32 v[80:81], v[54:55], v[98:99], v[80:81] op_sel:[1,0,0]
	v_cvt_f32_ubyte0_e32 v104, v89
	v_cvt_f32_ubyte1_e32 v105, v89
	v_pk_fma_f32 v[78:79], v[54:55], v[102:103], v[78:79] op_sel:[1,0,0]
	v_cvt_f32_ubyte2_e32 v146, v89
	v_cvt_f32_ubyte3_e32 v147, v89
	v_pk_fma_f32 v[70:71], v[64:65], v[104:105], v[70:71] op_sel:[1,0,0]
	v_cvt_f32_ubyte0_e32 v98, v68
	v_cvt_f32_ubyte1_e32 v99, v68
	v_pk_fma_f32 v[62:63], v[64:65], v[146:147], v[62:63] op_sel:[1,0,0]
	v_cvt_f32_ubyte2_e32 v102, v68
	v_cvt_f32_ubyte3_e32 v103, v68
	v_pk_fma_f32 v[92:93], v[56:57], v[98:99], v[92:93] op_sel_hi:[0,1,1]
	v_cvt_f32_ubyte0_e32 v104, v69
	v_cvt_f32_ubyte1_e32 v105, v69
	v_pk_fma_f32 v[90:91], v[56:57], v[102:103], v[90:91] op_sel_hi:[0,1,1]
	v_cvt_f32_ubyte2_e32 v146, v69
	v_cvt_f32_ubyte3_e32 v147, v69
	v_pk_fma_f32 v[86:87], v[66:67], v[104:105], v[86:87] op_sel_hi:[0,1,1]
	v_cvt_f32_ubyte0_e32 v98, v76
	v_cvt_f32_ubyte1_e32 v99, v76
	v_pk_fma_f32 v[84:85], v[66:67], v[146:147], v[84:85] op_sel_hi:[0,1,1]
	v_and_b32_e32 v82, s0, v226
	v_and_b32_e32 v83, s1, v226
	v_and_b32_e32 v88, s0, v227
	v_and_b32_e32 v89, s1, v227
	v_cvt_f32_ubyte2_e32 v102, v76
	v_cvt_f32_ubyte3_e32 v103, v76
	v_pk_fma_f32 v[80:81], v[56:57], v[98:99], v[80:81] op_sel_hi:[0,1,1]
	v_cvt_f32_ubyte0_e32 v104, v77
	v_cvt_f32_ubyte1_e32 v105, v77
	v_pk_fma_f32 v[78:79], v[56:57], v[102:103], v[78:79] op_sel_hi:[0,1,1]
	v_cvt_f32_ubyte2_e32 v146, v77
	v_cvt_f32_ubyte3_e32 v147, v77
	v_pk_fma_f32 v[70:71], v[66:67], v[104:105], v[70:71] op_sel_hi:[0,1,1]
	v_cvt_f32_ubyte0_e32 v98, v82
	v_cvt_f32_ubyte1_e32 v99, v82
	v_pk_fma_f32 v[62:63], v[66:67], v[146:147], v[62:63] op_sel_hi:[0,1,1]
	v_cvt_f32_ubyte2_e32 v102, v82
	v_cvt_f32_ubyte3_e32 v103, v82
	v_pk_fma_f32 v[92:93], v[56:57], v[98:99], v[92:93] op_sel:[1,0,0]
	v_cvt_f32_ubyte0_e32 v104, v83
	v_cvt_f32_ubyte1_e32 v105, v83
	v_pk_fma_f32 v[90:91], v[56:57], v[102:103], v[90:91] op_sel:[1,0,0]
	v_cvt_f32_ubyte2_e32 v146, v83
	v_cvt_f32_ubyte3_e32 v147, v83
	v_pk_fma_f32 v[86:87], v[66:67], v[104:105], v[86:87] op_sel:[1,0,0]
	v_cvt_f32_ubyte0_e32 v98, v88
	v_cvt_f32_ubyte1_e32 v99, v88
	v_pk_fma_f32 v[84:85], v[66:67], v[146:147], v[84:85] op_sel:[1,0,0]
	v_cvt_f32_ubyte2_e32 v102, v88
	v_cvt_f32_ubyte3_e32 v103, v88
	v_pk_fma_f32 v[80:81], v[56:57], v[98:99], v[80:81] op_sel:[1,0,0]
	v_cvt_f32_ubyte0_e32 v104, v89
	v_cvt_f32_ubyte1_e32 v105, v89
	v_pk_fma_f32 v[78:79], v[56:57], v[102:103], v[78:79] op_sel:[1,0,0]
	v_cvt_f32_ubyte2_e32 v146, v89
	v_cvt_f32_ubyte3_e32 v147, v89
	v_pk_fma_f32 v[70:71], v[66:67], v[104:105], v[70:71] op_sel:[1,0,0]
	v_pk_fma_f32 v[62:63], v[66:67], v[146:147], v[62:63] op_sel:[1,0,0]
	s_waitcnt lgkmcnt(0)
	v_lshl_add_u32 v72, v72, 9, v100
	v_lshl_add_u32 v73, v73, 9, v100
	v_lshl_add_u32 v74, v74, 9, v100
	v_lshl_add_u32 v75, v75, 9, v100
	v_lshl_add_u32 v94, v94, 9, v100
	v_lshl_add_u32 v95, v95, 9, v100
	v_lshl_add_u32 v96, v96, 9, v100
	v_lshl_add_u32 v97, v97, 9, v100
	global_load_dwordx2 v[212:213], v72, s[38:39]
	global_load_dwordx2 v[214:215], v73, s[38:39]
	global_load_dwordx2 v[216:217], v74, s[38:39]
	global_load_dwordx2 v[218:219], v75, s[38:39]
	global_load_dwordx2 v[220:221], v94, s[38:39]
	global_load_dwordx2 v[222:223], v95, s[38:39]
	global_load_dwordx2 v[224:225], v96, s[38:39]
	global_load_dwordx2 v[226:227], v97, s[38:39]
	ds_read_b128 v[72:75], v1 offset:320
	ds_read_b128 v[94:97], v1 offset:336
	ds_read_b128 v[50:53], v1 offset:672
	ds_read_b128 v[54:57], v1 offset:688
	ds_read_b128 v[58:61], v1 offset:1696
	ds_read_b128 v[64:67], v1 offset:1712
	s_waitcnt vmcnt(40)
	v_and_b32_e32 v68, s0, v2
	v_and_b32_e32 v69, s1, v2
	v_and_b32_e32 v76, s0, v3
	v_and_b32_e32 v77, s1, v3
	v_cvt_f32_ubyte0_e32 v98, v68
	v_cvt_f32_ubyte1_e32 v99, v68
	v_cvt_f32_ubyte2_e32 v102, v68
	v_cvt_f32_ubyte3_e32 v103, v68
	v_pk_fma_f32 v[92:93], v[34:35], v[98:99], v[92:93] op_sel_hi:[0,1,1]
	v_cvt_f32_ubyte0_e32 v104, v69
	v_cvt_f32_ubyte1_e32 v105, v69
	v_pk_fma_f32 v[90:91], v[34:35], v[102:103], v[90:91] op_sel_hi:[0,1,1]
	v_cvt_f32_ubyte2_e32 v146, v69
	v_cvt_f32_ubyte3_e32 v147, v69
	v_pk_fma_f32 v[86:87], v[42:43], v[104:105], v[86:87] op_sel_hi:[0,1,1]
	v_cvt_f32_ubyte0_e32 v98, v76
	v_cvt_f32_ubyte1_e32 v99, v76
	v_pk_fma_f32 v[84:85], v[42:43], v[146:147], v[84:85] op_sel_hi:[0,1,1]
	v_and_b32_e32 v82, s0, v4
	v_and_b32_e32 v83, s1, v4
	v_and_b32_e32 v88, s0, v5
	v_and_b32_e32 v89, s1, v5
	v_cvt_f32_ubyte2_e32 v102, v76
	v_cvt_f32_ubyte3_e32 v103, v76
	v_pk_fma_f32 v[80:81], v[34:35], v[98:99], v[80:81] op_sel_hi:[0,1,1]
	v_cvt_f32_ubyte0_e32 v104, v77
	v_cvt_f32_ubyte1_e32 v105, v77
	v_pk_fma_f32 v[78:79], v[34:35], v[102:103], v[78:79] op_sel_hi:[0,1,1]
	v_cvt_f32_ubyte2_e32 v146, v77
	v_cvt_f32_ubyte3_e32 v147, v77
	v_pk_fma_f32 v[70:71], v[42:43], v[104:105], v[70:71] op_sel_hi:[0,1,1]
	v_cvt_f32_ubyte0_e32 v98, v82
	v_cvt_f32_ubyte1_e32 v99, v82
	v_pk_fma_f32 v[62:63], v[42:43], v[146:147], v[62:63] op_sel_hi:[0,1,1]
	v_cvt_f32_ubyte2_e32 v102, v82
	v_cvt_f32_ubyte3_e32 v103, v82
	v_pk_fma_f32 v[92:93], v[34:35], v[98:99], v[92:93] op_sel:[1,0,0]
	v_cvt_f32_ubyte0_e32 v104, v83
	v_cvt_f32_ubyte1_e32 v105, v83
	v_pk_fma_f32 v[90:91], v[34:35], v[102:103], v[90:91] op_sel:[1,0,0]
	v_cvt_f32_ubyte2_e32 v146, v83
	v_cvt_f32_ubyte3_e32 v147, v83
	v_pk_fma_f32 v[86:87], v[42:43], v[104:105], v[86:87] op_sel:[1,0,0]
	v_cvt_f32_ubyte0_e32 v98, v88
	v_cvt_f32_ubyte1_e32 v99, v88
	v_pk_fma_f32 v[84:85], v[42:43], v[146:147], v[84:85] op_sel:[1,0,0]
	v_and_b32_e32 v68, s0, v6
	v_and_b32_e32 v69, s1, v6
	v_and_b32_e32 v76, s0, v7
	v_and_b32_e32 v77, s1, v7
	v_cvt_f32_ubyte2_e32 v102, v88
	v_cvt_f32_ubyte3_e32 v103, v88
	v_pk_fma_f32 v[80:81], v[34:35], v[98:99], v[80:81] op_sel:[1,0,0]
	v_cvt_f32_ubyte0_e32 v104, v89
	v_cvt_f32_ubyte1_e32 v105, v89
	v_pk_fma_f32 v[78:79], v[34:35], v[102:103], v[78:79] op_sel:[1,0,0]
	v_cvt_f32_ubyte2_e32 v146, v89
	v_cvt_f32_ubyte3_e32 v147, v89
	v_pk_fma_f32 v[70:71], v[42:43], v[104:105], v[70:71] op_sel:[1,0,0]
	v_cvt_f32_ubyte0_e32 v98, v68
	v_cvt_f32_ubyte1_e32 v99, v68
	v_pk_fma_f32 v[62:63], v[42:43], v[146:147], v[62:63] op_sel:[1,0,0]
	v_cvt_f32_ubyte2_e32 v102, v68
	v_cvt_f32_ubyte3_e32 v103, v68
	v_pk_fma_f32 v[92:93], v[36:37], v[98:99], v[92:93] op_sel_hi:[0,1,1]
	v_cvt_f32_ubyte0_e32 v104, v69
	v_cvt_f32_ubyte1_e32 v105, v69
	v_pk_fma_f32 v[90:91], v[36:37], v[102:103], v[90:91] op_sel_hi:[0,1,1]
	v_cvt_f32_ubyte2_e32 v146, v69
	v_cvt_f32_ubyte3_e32 v147, v69
	v_pk_fma_f32 v[86:87], v[44:45], v[104:105], v[86:87] op_sel_hi:[0,1,1]
	v_cvt_f32_ubyte0_e32 v98, v76
	v_cvt_f32_ubyte1_e32 v99, v76
	v_pk_fma_f32 v[84:85], v[44:45], v[146:147], v[84:85] op_sel_hi:[0,1,1]
	v_and_b32_e32 v82, s0, v8
	v_and_b32_e32 v83, s1, v8
	v_and_b32_e32 v88, s0, v9
	v_and_b32_e32 v89, s1, v9
	v_cvt_f32_ubyte2_e32 v102, v76
	v_cvt_f32_ubyte3_e32 v103, v76
	v_pk_fma_f32 v[80:81], v[36:37], v[98:99], v[80:81] op_sel_hi:[0,1,1]
	v_cvt_f32_ubyte0_e32 v104, v77
	v_cvt_f32_ubyte1_e32 v105, v77
	v_pk_fma_f32 v[78:79], v[36:37], v[102:103], v[78:79] op_sel_hi:[0,1,1]
	v_cvt_f32_ubyte2_e32 v146, v77
	v_cvt_f32_ubyte3_e32 v147, v77
	v_pk_fma_f32 v[70:71], v[44:45], v[104:105], v[70:71] op_sel_hi:[0,1,1]
	v_cvt_f32_ubyte0_e32 v98, v82
	v_cvt_f32_ubyte1_e32 v99, v82
	v_pk_fma_f32 v[62:63], v[44:45], v[146:147], v[62:63] op_sel_hi:[0,1,1]
	v_cvt_f32_ubyte2_e32 v102, v82
	v_cvt_f32_ubyte3_e32 v103, v82
	v_pk_fma_f32 v[92:93], v[36:37], v[98:99], v[92:93] op_sel:[1,0,0]
	v_cvt_f32_ubyte0_e32 v104, v83
	v_cvt_f32_ubyte1_e32 v105, v83
	v_pk_fma_f32 v[90:91], v[36:37], v[102:103], v[90:91] op_sel:[1,0,0]
	v_cvt_f32_ubyte2_e32 v146, v83
	v_cvt_f32_ubyte3_e32 v147, v83
	v_pk_fma_f32 v[86:87], v[44:45], v[104:105], v[86:87] op_sel:[1,0,0]
	v_cvt_f32_ubyte0_e32 v98, v88
	v_cvt_f32_ubyte1_e32 v99, v88
	v_pk_fma_f32 v[84:85], v[44:45], v[146:147], v[84:85] op_sel:[1,0,0]
	v_and_b32_e32 v68, s0, v10
	v_and_b32_e32 v69, s1, v10
	v_and_b32_e32 v76, s0, v11
	v_and_b32_e32 v77, s1, v11
	v_cvt_f32_ubyte2_e32 v102, v88
	v_cvt_f32_ubyte3_e32 v103, v88
	v_pk_fma_f32 v[80:81], v[36:37], v[98:99], v[80:81] op_sel:[1,0,0]
	v_cvt_f32_ubyte0_e32 v104, v89
	v_cvt_f32_ubyte1_e32 v105, v89
	v_pk_fma_f32 v[78:79], v[36:37], v[102:103], v[78:79] op_sel:[1,0,0]
	v_cvt_f32_ubyte2_e32 v146, v89
	v_cvt_f32_ubyte3_e32 v147, v89
	v_pk_fma_f32 v[70:71], v[44:45], v[104:105], v[70:71] op_sel:[1,0,0]
	v_cvt_f32_ubyte0_e32 v98, v68
	v_cvt_f32_ubyte1_e32 v99, v68
	v_pk_fma_f32 v[62:63], v[44:45], v[146:147], v[62:63] op_sel:[1,0,0]
	v_cvt_f32_ubyte2_e32 v102, v68
	v_cvt_f32_ubyte3_e32 v103, v68
	v_pk_fma_f32 v[92:93], v[38:39], v[98:99], v[92:93] op_sel_hi:[0,1,1]
	v_cvt_f32_ubyte0_e32 v104, v69
	v_cvt_f32_ubyte1_e32 v105, v69
	v_pk_fma_f32 v[90:91], v[38:39], v[102:103], v[90:91] op_sel_hi:[0,1,1]
	v_cvt_f32_ubyte2_e32 v146, v69
	v_cvt_f32_ubyte3_e32 v147, v69
	v_pk_fma_f32 v[86:87], v[46:47], v[104:105], v[86:87] op_sel_hi:[0,1,1]
	v_cvt_f32_ubyte0_e32 v98, v76
	v_cvt_f32_ubyte1_e32 v99, v76
	v_pk_fma_f32 v[84:85], v[46:47], v[146:147], v[84:85] op_sel_hi:[0,1,1]
	v_and_b32_e32 v82, s0, v12
	v_and_b32_e32 v83, s1, v12
	v_and_b32_e32 v88, s0, v13
	v_and_b32_e32 v89, s1, v13
	v_cvt_f32_ubyte2_e32 v102, v76
	v_cvt_f32_ubyte3_e32 v103, v76
	v_pk_fma_f32 v[80:81], v[38:39], v[98:99], v[80:81] op_sel_hi:[0,1,1]
	v_cvt_f32_ubyte0_e32 v104, v77
	v_cvt_f32_ubyte1_e32 v105, v77
	v_pk_fma_f32 v[78:79], v[38:39], v[102:103], v[78:79] op_sel_hi:[0,1,1]
	v_cvt_f32_ubyte2_e32 v146, v77
	v_cvt_f32_ubyte3_e32 v147, v77
	v_pk_fma_f32 v[70:71], v[46:47], v[104:105], v[70:71] op_sel_hi:[0,1,1]
	v_cvt_f32_ubyte0_e32 v98, v82
	v_cvt_f32_ubyte1_e32 v99, v82
	v_pk_fma_f32 v[62:63], v[46:47], v[146:147], v[62:63] op_sel_hi:[0,1,1]
	v_cvt_f32_ubyte2_e32 v102, v82
	v_cvt_f32_ubyte3_e32 v103, v82
	v_pk_fma_f32 v[92:93], v[38:39], v[98:99], v[92:93] op_sel:[1,0,0]
	v_cvt_f32_ubyte0_e32 v104, v83
	v_cvt_f32_ubyte1_e32 v105, v83
	v_pk_fma_f32 v[90:91], v[38:39], v[102:103], v[90:91] op_sel:[1,0,0]
	v_cvt_f32_ubyte2_e32 v146, v83
	v_cvt_f32_ubyte3_e32 v147, v83
	v_pk_fma_f32 v[86:87], v[46:47], v[104:105], v[86:87] op_sel:[1,0,0]
	v_cvt_f32_ubyte0_e32 v98, v88
	v_cvt_f32_ubyte1_e32 v99, v88
	v_pk_fma_f32 v[84:85], v[46:47], v[146:147], v[84:85] op_sel:[1,0,0]
	v_and_b32_e32 v68, s0, v14
	v_and_b32_e32 v69, s1, v14
	v_and_b32_e32 v76, s0, v15
	v_and_b32_e32 v77, s1, v15
	v_cvt_f32_ubyte2_e32 v102, v88
	v_cvt_f32_ubyte3_e32 v103, v88
	v_pk_fma_f32 v[80:81], v[38:39], v[98:99], v[80:81] op_sel:[1,0,0]
	v_cvt_f32_ubyte0_e32 v104, v89
	v_cvt_f32_ubyte1_e32 v105, v89
	v_pk_fma_f32 v[78:79], v[38:39], v[102:103], v[78:79] op_sel:[1,0,0]
	v_cvt_f32_ubyte2_e32 v146, v89
	v_cvt_f32_ubyte3_e32 v147, v89
	v_pk_fma_f32 v[70:71], v[46:47], v[104:105], v[70:71] op_sel:[1,0,0]
	v_cvt_f32_ubyte0_e32 v98, v68
	v_cvt_f32_ubyte1_e32 v99, v68
	v_pk_fma_f32 v[62:63], v[46:47], v[146:147], v[62:63] op_sel:[1,0,0]
	v_cvt_f32_ubyte2_e32 v102, v68
	v_cvt_f32_ubyte3_e32 v103, v68
	v_pk_fma_f32 v[92:93], v[40:41], v[98:99], v[92:93] op_sel_hi:[0,1,1]
	v_cvt_f32_ubyte0_e32 v104, v69
	v_cvt_f32_ubyte1_e32 v105, v69
	v_pk_fma_f32 v[90:91], v[40:41], v[102:103], v[90:91] op_sel_hi:[0,1,1]
	v_cvt_f32_ubyte2_e32 v146, v69
	v_cvt_f32_ubyte3_e32 v147, v69
	v_pk_fma_f32 v[86:87], v[48:49], v[104:105], v[86:87] op_sel_hi:[0,1,1]
	v_cvt_f32_ubyte0_e32 v98, v76
	v_cvt_f32_ubyte1_e32 v99, v76
	v_pk_fma_f32 v[84:85], v[48:49], v[146:147], v[84:85] op_sel_hi:[0,1,1]
	v_and_b32_e32 v82, s0, v16
	v_and_b32_e32 v83, s1, v16
	v_and_b32_e32 v88, s0, v17
	v_and_b32_e32 v89, s1, v17
	v_cvt_f32_ubyte2_e32 v102, v76
	v_cvt_f32_ubyte3_e32 v103, v76
	v_pk_fma_f32 v[80:81], v[40:41], v[98:99], v[80:81] op_sel_hi:[0,1,1]
	v_cvt_f32_ubyte0_e32 v104, v77
	v_cvt_f32_ubyte1_e32 v105, v77
	v_pk_fma_f32 v[78:79], v[40:41], v[102:103], v[78:79] op_sel_hi:[0,1,1]
	v_cvt_f32_ubyte2_e32 v146, v77
	v_cvt_f32_ubyte3_e32 v147, v77
	v_pk_fma_f32 v[70:71], v[48:49], v[104:105], v[70:71] op_sel_hi:[0,1,1]
	v_cvt_f32_ubyte0_e32 v98, v82
	v_cvt_f32_ubyte1_e32 v99, v82
	v_pk_fma_f32 v[62:63], v[48:49], v[146:147], v[62:63] op_sel_hi:[0,1,1]
	v_cvt_f32_ubyte2_e32 v102, v82
	v_cvt_f32_ubyte3_e32 v103, v82
	v_pk_fma_f32 v[92:93], v[40:41], v[98:99], v[92:93] op_sel:[1,0,0]
	v_cvt_f32_ubyte0_e32 v104, v83
	v_cvt_f32_ubyte1_e32 v105, v83
	v_pk_fma_f32 v[90:91], v[40:41], v[102:103], v[90:91] op_sel:[1,0,0]
	v_cvt_f32_ubyte2_e32 v146, v83
	v_cvt_f32_ubyte3_e32 v147, v83
	v_pk_fma_f32 v[86:87], v[48:49], v[104:105], v[86:87] op_sel:[1,0,0]
	v_cvt_f32_ubyte0_e32 v98, v88
	v_cvt_f32_ubyte1_e32 v99, v88
	v_pk_fma_f32 v[84:85], v[48:49], v[146:147], v[84:85] op_sel:[1,0,0]
	v_cvt_f32_ubyte2_e32 v102, v88
	v_cvt_f32_ubyte3_e32 v103, v88
	v_pk_fma_f32 v[80:81], v[40:41], v[98:99], v[80:81] op_sel:[1,0,0]
	v_cvt_f32_ubyte0_e32 v104, v89
	v_cvt_f32_ubyte1_e32 v105, v89
	v_pk_fma_f32 v[78:79], v[40:41], v[102:103], v[78:79] op_sel:[1,0,0]
	v_cvt_f32_ubyte2_e32 v146, v89
	v_cvt_f32_ubyte3_e32 v147, v89
	v_pk_fma_f32 v[70:71], v[48:49], v[104:105], v[70:71] op_sel:[1,0,0]
	v_pk_fma_f32 v[62:63], v[48:49], v[146:147], v[62:63] op_sel:[1,0,0]
	s_waitcnt lgkmcnt(0)
	v_lshl_add_u32 v72, v72, 9, v100
	v_lshl_add_u32 v73, v73, 9, v100
	v_lshl_add_u32 v74, v74, 9, v100
	v_lshl_add_u32 v75, v75, 9, v100
	v_lshl_add_u32 v94, v94, 9, v100
	v_lshl_add_u32 v95, v95, 9, v100
	v_lshl_add_u32 v96, v96, 9, v100
	v_lshl_add_u32 v97, v97, 9, v100
	global_load_dwordx2 v[2:3], v72, s[38:39]
	global_load_dwordx2 v[4:5], v73, s[38:39]
	global_load_dwordx2 v[6:7], v74, s[38:39]
	global_load_dwordx2 v[8:9], v75, s[38:39]
	global_load_dwordx2 v[10:11], v94, s[38:39]
	global_load_dwordx2 v[12:13], v95, s[38:39]
	global_load_dwordx2 v[14:15], v96, s[38:39]
	global_load_dwordx2 v[16:17], v97, s[38:39]
	ds_read_b128 v[72:75], v1 offset:352
	ds_read_b128 v[94:97], v1 offset:368
	ds_read_b128 v[34:37], v1 offset:704
	ds_read_b128 v[38:41], v1 offset:720
	ds_read_b128 v[42:45], v1 offset:1728
	ds_read_b128 v[46:49], v1 offset:1744
	s_waitcnt vmcnt(40)
	v_and_b32_e32 v68, s0, v18
	v_and_b32_e32 v69, s1, v18
	v_and_b32_e32 v76, s0, v19
	v_and_b32_e32 v77, s1, v19
	v_cvt_f32_ubyte0_e32 v98, v68
	v_cvt_f32_ubyte1_e32 v99, v68
	v_cvt_f32_ubyte2_e32 v102, v68
	v_cvt_f32_ubyte3_e32 v103, v68
	v_pk_fma_f32 v[92:93], v[50:51], v[98:99], v[92:93] op_sel_hi:[0,1,1]
	v_cvt_f32_ubyte0_e32 v104, v69
	v_cvt_f32_ubyte1_e32 v105, v69
	v_pk_fma_f32 v[90:91], v[50:51], v[102:103], v[90:91] op_sel_hi:[0,1,1]
	v_cvt_f32_ubyte2_e32 v146, v69
	v_cvt_f32_ubyte3_e32 v147, v69
	v_pk_fma_f32 v[86:87], v[58:59], v[104:105], v[86:87] op_sel_hi:[0,1,1]
	v_cvt_f32_ubyte0_e32 v98, v76
	v_cvt_f32_ubyte1_e32 v99, v76
	v_pk_fma_f32 v[84:85], v[58:59], v[146:147], v[84:85] op_sel_hi:[0,1,1]
	v_and_b32_e32 v82, s0, v20
	v_and_b32_e32 v83, s1, v20
	v_and_b32_e32 v88, s0, v21
	v_and_b32_e32 v89, s1, v21
	v_cvt_f32_ubyte2_e32 v102, v76
	v_cvt_f32_ubyte3_e32 v103, v76
	v_pk_fma_f32 v[80:81], v[50:51], v[98:99], v[80:81] op_sel_hi:[0,1,1]
	v_cvt_f32_ubyte0_e32 v104, v77
	v_cvt_f32_ubyte1_e32 v105, v77
	v_pk_fma_f32 v[78:79], v[50:51], v[102:103], v[78:79] op_sel_hi:[0,1,1]
	v_cvt_f32_ubyte2_e32 v146, v77
	v_cvt_f32_ubyte3_e32 v147, v77
	v_pk_fma_f32 v[70:71], v[58:59], v[104:105], v[70:71] op_sel_hi:[0,1,1]
	v_cvt_f32_ubyte0_e32 v98, v82
	v_cvt_f32_ubyte1_e32 v99, v82
	v_pk_fma_f32 v[62:63], v[58:59], v[146:147], v[62:63] op_sel_hi:[0,1,1]
	v_cvt_f32_ubyte2_e32 v102, v82
	v_cvt_f32_ubyte3_e32 v103, v82
	v_pk_fma_f32 v[92:93], v[50:51], v[98:99], v[92:93] op_sel:[1,0,0]
	v_cvt_f32_ubyte0_e32 v104, v83
	v_cvt_f32_ubyte1_e32 v105, v83
	v_pk_fma_f32 v[90:91], v[50:51], v[102:103], v[90:91] op_sel:[1,0,0]
	v_cvt_f32_ubyte2_e32 v146, v83
	v_cvt_f32_ubyte3_e32 v147, v83
	v_pk_fma_f32 v[86:87], v[58:59], v[104:105], v[86:87] op_sel:[1,0,0]
	v_cvt_f32_ubyte0_e32 v98, v88
	v_cvt_f32_ubyte1_e32 v99, v88
	v_pk_fma_f32 v[84:85], v[58:59], v[146:147], v[84:85] op_sel:[1,0,0]
	v_and_b32_e32 v68, s0, v22
	v_and_b32_e32 v69, s1, v22
	v_and_b32_e32 v76, s0, v23
	v_and_b32_e32 v77, s1, v23
	v_cvt_f32_ubyte2_e32 v102, v88
	v_cvt_f32_ubyte3_e32 v103, v88
	v_pk_fma_f32 v[80:81], v[50:51], v[98:99], v[80:81] op_sel:[1,0,0]
	v_cvt_f32_ubyte0_e32 v104, v89
	v_cvt_f32_ubyte1_e32 v105, v89
	v_pk_fma_f32 v[78:79], v[50:51], v[102:103], v[78:79] op_sel:[1,0,0]
	v_cvt_f32_ubyte2_e32 v146, v89
	v_cvt_f32_ubyte3_e32 v147, v89
	v_pk_fma_f32 v[70:71], v[58:59], v[104:105], v[70:71] op_sel:[1,0,0]
	v_cvt_f32_ubyte0_e32 v98, v68
	v_cvt_f32_ubyte1_e32 v99, v68
	v_pk_fma_f32 v[62:63], v[58:59], v[146:147], v[62:63] op_sel:[1,0,0]
	v_cvt_f32_ubyte2_e32 v102, v68
	v_cvt_f32_ubyte3_e32 v103, v68
	v_pk_fma_f32 v[92:93], v[52:53], v[98:99], v[92:93] op_sel_hi:[0,1,1]
	v_cvt_f32_ubyte0_e32 v104, v69
	v_cvt_f32_ubyte1_e32 v105, v69
	v_pk_fma_f32 v[90:91], v[52:53], v[102:103], v[90:91] op_sel_hi:[0,1,1]
	v_cvt_f32_ubyte2_e32 v146, v69
	v_cvt_f32_ubyte3_e32 v147, v69
	v_pk_fma_f32 v[86:87], v[60:61], v[104:105], v[86:87] op_sel_hi:[0,1,1]
	v_cvt_f32_ubyte0_e32 v98, v76
	v_cvt_f32_ubyte1_e32 v99, v76
	v_pk_fma_f32 v[84:85], v[60:61], v[146:147], v[84:85] op_sel_hi:[0,1,1]
	v_and_b32_e32 v82, s0, v24
	v_and_b32_e32 v83, s1, v24
	v_and_b32_e32 v88, s0, v25
	v_and_b32_e32 v89, s1, v25
	v_cvt_f32_ubyte2_e32 v102, v76
	v_cvt_f32_ubyte3_e32 v103, v76
	v_pk_fma_f32 v[80:81], v[52:53], v[98:99], v[80:81] op_sel_hi:[0,1,1]
	v_cvt_f32_ubyte0_e32 v104, v77
	v_cvt_f32_ubyte1_e32 v105, v77
	v_pk_fma_f32 v[78:79], v[52:53], v[102:103], v[78:79] op_sel_hi:[0,1,1]
	v_cvt_f32_ubyte2_e32 v146, v77
	v_cvt_f32_ubyte3_e32 v147, v77
	v_pk_fma_f32 v[70:71], v[60:61], v[104:105], v[70:71] op_sel_hi:[0,1,1]
	v_cvt_f32_ubyte0_e32 v98, v82
	v_cvt_f32_ubyte1_e32 v99, v82
	v_pk_fma_f32 v[62:63], v[60:61], v[146:147], v[62:63] op_sel_hi:[0,1,1]
	v_cvt_f32_ubyte2_e32 v102, v82
	v_cvt_f32_ubyte3_e32 v103, v82
	v_pk_fma_f32 v[92:93], v[52:53], v[98:99], v[92:93] op_sel:[1,0,0]
	v_cvt_f32_ubyte0_e32 v104, v83
	v_cvt_f32_ubyte1_e32 v105, v83
	v_pk_fma_f32 v[90:91], v[52:53], v[102:103], v[90:91] op_sel:[1,0,0]
	v_cvt_f32_ubyte2_e32 v146, v83
	v_cvt_f32_ubyte3_e32 v147, v83
	v_pk_fma_f32 v[86:87], v[60:61], v[104:105], v[86:87] op_sel:[1,0,0]
	v_cvt_f32_ubyte0_e32 v98, v88
	v_cvt_f32_ubyte1_e32 v99, v88
	v_pk_fma_f32 v[84:85], v[60:61], v[146:147], v[84:85] op_sel:[1,0,0]
	v_and_b32_e32 v68, s0, v26
	v_and_b32_e32 v69, s1, v26
	v_and_b32_e32 v76, s0, v27
	v_and_b32_e32 v77, s1, v27
	v_cvt_f32_ubyte2_e32 v102, v88
	v_cvt_f32_ubyte3_e32 v103, v88
	v_pk_fma_f32 v[80:81], v[52:53], v[98:99], v[80:81] op_sel:[1,0,0]
	v_cvt_f32_ubyte0_e32 v104, v89
	v_cvt_f32_ubyte1_e32 v105, v89
	v_pk_fma_f32 v[78:79], v[52:53], v[102:103], v[78:79] op_sel:[1,0,0]
	v_cvt_f32_ubyte2_e32 v146, v89
	v_cvt_f32_ubyte3_e32 v147, v89
	v_pk_fma_f32 v[70:71], v[60:61], v[104:105], v[70:71] op_sel:[1,0,0]
	v_cvt_f32_ubyte0_e32 v98, v68
	v_cvt_f32_ubyte1_e32 v99, v68
	v_pk_fma_f32 v[62:63], v[60:61], v[146:147], v[62:63] op_sel:[1,0,0]
	v_cvt_f32_ubyte2_e32 v102, v68
	v_cvt_f32_ubyte3_e32 v103, v68
	v_pk_fma_f32 v[92:93], v[54:55], v[98:99], v[92:93] op_sel_hi:[0,1,1]
	v_cvt_f32_ubyte0_e32 v104, v69
	v_cvt_f32_ubyte1_e32 v105, v69
	v_pk_fma_f32 v[90:91], v[54:55], v[102:103], v[90:91] op_sel_hi:[0,1,1]
	v_cvt_f32_ubyte2_e32 v146, v69
	v_cvt_f32_ubyte3_e32 v147, v69
	v_pk_fma_f32 v[86:87], v[64:65], v[104:105], v[86:87] op_sel_hi:[0,1,1]
	v_cvt_f32_ubyte0_e32 v98, v76
	v_cvt_f32_ubyte1_e32 v99, v76
	v_pk_fma_f32 v[84:85], v[64:65], v[146:147], v[84:85] op_sel_hi:[0,1,1]
	v_and_b32_e32 v82, s0, v28
	v_and_b32_e32 v83, s1, v28
	v_and_b32_e32 v88, s0, v29
	v_and_b32_e32 v89, s1, v29
	v_cvt_f32_ubyte2_e32 v102, v76
	v_cvt_f32_ubyte3_e32 v103, v76
	v_pk_fma_f32 v[80:81], v[54:55], v[98:99], v[80:81] op_sel_hi:[0,1,1]
	v_cvt_f32_ubyte0_e32 v104, v77
	v_cvt_f32_ubyte1_e32 v105, v77
	v_pk_fma_f32 v[78:79], v[54:55], v[102:103], v[78:79] op_sel_hi:[0,1,1]
	v_cvt_f32_ubyte2_e32 v146, v77
	v_cvt_f32_ubyte3_e32 v147, v77
	v_pk_fma_f32 v[70:71], v[64:65], v[104:105], v[70:71] op_sel_hi:[0,1,1]
	v_cvt_f32_ubyte0_e32 v98, v82
	v_cvt_f32_ubyte1_e32 v99, v82
	v_pk_fma_f32 v[62:63], v[64:65], v[146:147], v[62:63] op_sel_hi:[0,1,1]
	v_cvt_f32_ubyte2_e32 v102, v82
	v_cvt_f32_ubyte3_e32 v103, v82
	v_pk_fma_f32 v[92:93], v[54:55], v[98:99], v[92:93] op_sel:[1,0,0]
	v_cvt_f32_ubyte0_e32 v104, v83
	v_cvt_f32_ubyte1_e32 v105, v83
	v_pk_fma_f32 v[90:91], v[54:55], v[102:103], v[90:91] op_sel:[1,0,0]
	v_cvt_f32_ubyte2_e32 v146, v83
	v_cvt_f32_ubyte3_e32 v147, v83
	v_pk_fma_f32 v[86:87], v[64:65], v[104:105], v[86:87] op_sel:[1,0,0]
	v_cvt_f32_ubyte0_e32 v98, v88
	v_cvt_f32_ubyte1_e32 v99, v88
	v_pk_fma_f32 v[84:85], v[64:65], v[146:147], v[84:85] op_sel:[1,0,0]
	v_and_b32_e32 v68, s0, v30
	v_and_b32_e32 v69, s1, v30
	v_and_b32_e32 v76, s0, v31
	v_and_b32_e32 v77, s1, v31
	v_cvt_f32_ubyte2_e32 v102, v88
	v_cvt_f32_ubyte3_e32 v103, v88
	v_pk_fma_f32 v[80:81], v[54:55], v[98:99], v[80:81] op_sel:[1,0,0]
	v_cvt_f32_ubyte0_e32 v104, v89
	v_cvt_f32_ubyte1_e32 v105, v89
	v_pk_fma_f32 v[78:79], v[54:55], v[102:103], v[78:79] op_sel:[1,0,0]
	v_cvt_f32_ubyte2_e32 v146, v89
	v_cvt_f32_ubyte3_e32 v147, v89
	v_pk_fma_f32 v[70:71], v[64:65], v[104:105], v[70:71] op_sel:[1,0,0]
	v_cvt_f32_ubyte0_e32 v98, v68
	v_cvt_f32_ubyte1_e32 v99, v68
	v_pk_fma_f32 v[62:63], v[64:65], v[146:147], v[62:63] op_sel:[1,0,0]
	v_cvt_f32_ubyte2_e32 v102, v68
	v_cvt_f32_ubyte3_e32 v103, v68
	v_pk_fma_f32 v[92:93], v[56:57], v[98:99], v[92:93] op_sel_hi:[0,1,1]
	v_cvt_f32_ubyte0_e32 v104, v69
	v_cvt_f32_ubyte1_e32 v105, v69
	v_pk_fma_f32 v[90:91], v[56:57], v[102:103], v[90:91] op_sel_hi:[0,1,1]
	v_cvt_f32_ubyte2_e32 v146, v69
	v_cvt_f32_ubyte3_e32 v147, v69
	v_pk_fma_f32 v[86:87], v[66:67], v[104:105], v[86:87] op_sel_hi:[0,1,1]
	v_cvt_f32_ubyte0_e32 v98, v76
	v_cvt_f32_ubyte1_e32 v99, v76
	v_pk_fma_f32 v[84:85], v[66:67], v[146:147], v[84:85] op_sel_hi:[0,1,1]
	v_and_b32_e32 v82, s0, v32
	v_and_b32_e32 v83, s1, v32
	v_and_b32_e32 v88, s0, v33
	v_and_b32_e32 v89, s1, v33
	v_cvt_f32_ubyte2_e32 v102, v76
	v_cvt_f32_ubyte3_e32 v103, v76
	v_pk_fma_f32 v[80:81], v[56:57], v[98:99], v[80:81] op_sel_hi:[0,1,1]
	v_cvt_f32_ubyte0_e32 v104, v77
	v_cvt_f32_ubyte1_e32 v105, v77
	v_pk_fma_f32 v[78:79], v[56:57], v[102:103], v[78:79] op_sel_hi:[0,1,1]
	v_cvt_f32_ubyte2_e32 v146, v77
	v_cvt_f32_ubyte3_e32 v147, v77
	v_pk_fma_f32 v[70:71], v[66:67], v[104:105], v[70:71] op_sel_hi:[0,1,1]
	v_cvt_f32_ubyte0_e32 v98, v82
	v_cvt_f32_ubyte1_e32 v99, v82
	v_pk_fma_f32 v[62:63], v[66:67], v[146:147], v[62:63] op_sel_hi:[0,1,1]
	v_cvt_f32_ubyte2_e32 v102, v82
	v_cvt_f32_ubyte3_e32 v103, v82
	v_pk_fma_f32 v[92:93], v[56:57], v[98:99], v[92:93] op_sel:[1,0,0]
	v_cvt_f32_ubyte0_e32 v104, v83
	v_cvt_f32_ubyte1_e32 v105, v83
	v_pk_fma_f32 v[90:91], v[56:57], v[102:103], v[90:91] op_sel:[1,0,0]
	v_cvt_f32_ubyte2_e32 v146, v83
	v_cvt_f32_ubyte3_e32 v147, v83
	v_pk_fma_f32 v[86:87], v[66:67], v[104:105], v[86:87] op_sel:[1,0,0]
	v_cvt_f32_ubyte0_e32 v98, v88
	v_cvt_f32_ubyte1_e32 v99, v88
	v_pk_fma_f32 v[84:85], v[66:67], v[146:147], v[84:85] op_sel:[1,0,0]
	v_cvt_f32_ubyte2_e32 v102, v88
	v_cvt_f32_ubyte3_e32 v103, v88
	v_pk_fma_f32 v[80:81], v[56:57], v[98:99], v[80:81] op_sel:[1,0,0]
	v_cvt_f32_ubyte0_e32 v104, v89
	v_cvt_f32_ubyte1_e32 v105, v89
	v_pk_fma_f32 v[78:79], v[56:57], v[102:103], v[78:79] op_sel:[1,0,0]
	v_cvt_f32_ubyte2_e32 v146, v89
	v_cvt_f32_ubyte3_e32 v147, v89
	v_pk_fma_f32 v[70:71], v[66:67], v[104:105], v[70:71] op_sel:[1,0,0]
	v_pk_fma_f32 v[62:63], v[66:67], v[146:147], v[62:63] op_sel:[1,0,0]
	s_waitcnt lgkmcnt(0)
	v_lshl_add_u32 v72, v72, 9, v100
	v_lshl_add_u32 v73, v73, 9, v100
	v_lshl_add_u32 v74, v74, 9, v100
	v_lshl_add_u32 v75, v75, 9, v100
	v_lshl_add_u32 v94, v94, 9, v100
	v_lshl_add_u32 v95, v95, 9, v100
	v_lshl_add_u32 v96, v96, 9, v100
	v_lshl_add_u32 v97, v97, 9, v100
	global_load_dwordx2 v[18:19], v72, s[38:39]
	global_load_dwordx2 v[20:21], v73, s[38:39]
	global_load_dwordx2 v[22:23], v74, s[38:39]
	global_load_dwordx2 v[24:25], v75, s[38:39]
	global_load_dwordx2 v[26:27], v94, s[38:39]
	global_load_dwordx2 v[28:29], v95, s[38:39]
	global_load_dwordx2 v[30:31], v96, s[38:39]
	global_load_dwordx2 v[32:33], v97, s[38:39]
	ds_read_b128 v[72:75], v1 offset:384
	ds_read_b128 v[94:97], v1 offset:400
	ds_read_b128 v[50:53], v1 offset:736
	ds_read_b128 v[54:57], v1 offset:752
	ds_read_b128 v[58:61], v1 offset:1760
	ds_read_b128 v[64:67], v1 offset:1776
	s_waitcnt vmcnt(40)
	v_and_b32_e32 v68, s0, v164
	v_and_b32_e32 v69, s1, v164
	v_and_b32_e32 v76, s0, v165
	v_and_b32_e32 v77, s1, v165
	v_cvt_f32_ubyte0_e32 v98, v68
	v_cvt_f32_ubyte1_e32 v99, v68
	v_cvt_f32_ubyte2_e32 v102, v68
	v_cvt_f32_ubyte3_e32 v103, v68
	v_pk_fma_f32 v[92:93], v[34:35], v[98:99], v[92:93] op_sel_hi:[0,1,1]
	v_cvt_f32_ubyte0_e32 v104, v69
	v_cvt_f32_ubyte1_e32 v105, v69
	v_pk_fma_f32 v[90:91], v[34:35], v[102:103], v[90:91] op_sel_hi:[0,1,1]
	v_cvt_f32_ubyte2_e32 v146, v69
	v_cvt_f32_ubyte3_e32 v147, v69
	v_pk_fma_f32 v[86:87], v[42:43], v[104:105], v[86:87] op_sel_hi:[0,1,1]
	v_cvt_f32_ubyte0_e32 v98, v76
	v_cvt_f32_ubyte1_e32 v99, v76
	v_pk_fma_f32 v[84:85], v[42:43], v[146:147], v[84:85] op_sel_hi:[0,1,1]
	v_and_b32_e32 v82, s0, v166
	v_and_b32_e32 v83, s1, v166
	v_and_b32_e32 v88, s0, v167
	v_and_b32_e32 v89, s1, v167
	v_cvt_f32_ubyte2_e32 v102, v76
	v_cvt_f32_ubyte3_e32 v103, v76
	v_pk_fma_f32 v[80:81], v[34:35], v[98:99], v[80:81] op_sel_hi:[0,1,1]
	v_cvt_f32_ubyte0_e32 v104, v77
	v_cvt_f32_ubyte1_e32 v105, v77
	v_pk_fma_f32 v[78:79], v[34:35], v[102:103], v[78:79] op_sel_hi:[0,1,1]
	v_cvt_f32_ubyte2_e32 v146, v77
	v_cvt_f32_ubyte3_e32 v147, v77
	v_pk_fma_f32 v[70:71], v[42:43], v[104:105], v[70:71] op_sel_hi:[0,1,1]
	v_cvt_f32_ubyte0_e32 v98, v82
	v_cvt_f32_ubyte1_e32 v99, v82
	v_pk_fma_f32 v[62:63], v[42:43], v[146:147], v[62:63] op_sel_hi:[0,1,1]
	v_cvt_f32_ubyte2_e32 v102, v82
	v_cvt_f32_ubyte3_e32 v103, v82
	v_pk_fma_f32 v[92:93], v[34:35], v[98:99], v[92:93] op_sel:[1,0,0]
	v_cvt_f32_ubyte0_e32 v104, v83
	v_cvt_f32_ubyte1_e32 v105, v83
	v_pk_fma_f32 v[90:91], v[34:35], v[102:103], v[90:91] op_sel:[1,0,0]
	v_cvt_f32_ubyte2_e32 v146, v83
	v_cvt_f32_ubyte3_e32 v147, v83
	v_pk_fma_f32 v[86:87], v[42:43], v[104:105], v[86:87] op_sel:[1,0,0]
	v_cvt_f32_ubyte0_e32 v98, v88
	v_cvt_f32_ubyte1_e32 v99, v88
	v_pk_fma_f32 v[84:85], v[42:43], v[146:147], v[84:85] op_sel:[1,0,0]
	v_and_b32_e32 v68, s0, v168
	v_and_b32_e32 v69, s1, v168
	v_and_b32_e32 v76, s0, v169
	v_and_b32_e32 v77, s1, v169
	v_cvt_f32_ubyte2_e32 v102, v88
	v_cvt_f32_ubyte3_e32 v103, v88
	v_pk_fma_f32 v[80:81], v[34:35], v[98:99], v[80:81] op_sel:[1,0,0]
	v_cvt_f32_ubyte0_e32 v104, v89
	v_cvt_f32_ubyte1_e32 v105, v89
	v_pk_fma_f32 v[78:79], v[34:35], v[102:103], v[78:79] op_sel:[1,0,0]
	v_cvt_f32_ubyte2_e32 v146, v89
	v_cvt_f32_ubyte3_e32 v147, v89
	v_pk_fma_f32 v[70:71], v[42:43], v[104:105], v[70:71] op_sel:[1,0,0]
	v_cvt_f32_ubyte0_e32 v98, v68
	v_cvt_f32_ubyte1_e32 v99, v68
	v_pk_fma_f32 v[62:63], v[42:43], v[146:147], v[62:63] op_sel:[1,0,0]
	v_cvt_f32_ubyte2_e32 v102, v68
	v_cvt_f32_ubyte3_e32 v103, v68
	v_pk_fma_f32 v[92:93], v[36:37], v[98:99], v[92:93] op_sel_hi:[0,1,1]
	v_cvt_f32_ubyte0_e32 v104, v69
	v_cvt_f32_ubyte1_e32 v105, v69
	v_pk_fma_f32 v[90:91], v[36:37], v[102:103], v[90:91] op_sel_hi:[0,1,1]
	v_cvt_f32_ubyte2_e32 v146, v69
	v_cvt_f32_ubyte3_e32 v147, v69
	v_pk_fma_f32 v[86:87], v[44:45], v[104:105], v[86:87] op_sel_hi:[0,1,1]
	v_cvt_f32_ubyte0_e32 v98, v76
	v_cvt_f32_ubyte1_e32 v99, v76
	v_pk_fma_f32 v[84:85], v[44:45], v[146:147], v[84:85] op_sel_hi:[0,1,1]
	v_and_b32_e32 v82, s0, v170
	v_and_b32_e32 v83, s1, v170
	v_and_b32_e32 v88, s0, v171
	v_and_b32_e32 v89, s1, v171
	v_cvt_f32_ubyte2_e32 v102, v76
	v_cvt_f32_ubyte3_e32 v103, v76
	v_pk_fma_f32 v[80:81], v[36:37], v[98:99], v[80:81] op_sel_hi:[0,1,1]
	v_cvt_f32_ubyte0_e32 v104, v77
	v_cvt_f32_ubyte1_e32 v105, v77
	v_pk_fma_f32 v[78:79], v[36:37], v[102:103], v[78:79] op_sel_hi:[0,1,1]
	v_cvt_f32_ubyte2_e32 v146, v77
	v_cvt_f32_ubyte3_e32 v147, v77
	v_pk_fma_f32 v[70:71], v[44:45], v[104:105], v[70:71] op_sel_hi:[0,1,1]
	v_cvt_f32_ubyte0_e32 v98, v82
	v_cvt_f32_ubyte1_e32 v99, v82
	v_pk_fma_f32 v[62:63], v[44:45], v[146:147], v[62:63] op_sel_hi:[0,1,1]
	v_cvt_f32_ubyte2_e32 v102, v82
	v_cvt_f32_ubyte3_e32 v103, v82
	v_pk_fma_f32 v[92:93], v[36:37], v[98:99], v[92:93] op_sel:[1,0,0]
	v_cvt_f32_ubyte0_e32 v104, v83
	v_cvt_f32_ubyte1_e32 v105, v83
	v_pk_fma_f32 v[90:91], v[36:37], v[102:103], v[90:91] op_sel:[1,0,0]
	v_cvt_f32_ubyte2_e32 v146, v83
	v_cvt_f32_ubyte3_e32 v147, v83
	v_pk_fma_f32 v[86:87], v[44:45], v[104:105], v[86:87] op_sel:[1,0,0]
	v_cvt_f32_ubyte0_e32 v98, v88
	v_cvt_f32_ubyte1_e32 v99, v88
	v_pk_fma_f32 v[84:85], v[44:45], v[146:147], v[84:85] op_sel:[1,0,0]
	v_and_b32_e32 v68, s0, v172
	v_and_b32_e32 v69, s1, v172
	v_and_b32_e32 v76, s0, v173
	v_and_b32_e32 v77, s1, v173
	v_cvt_f32_ubyte2_e32 v102, v88
	v_cvt_f32_ubyte3_e32 v103, v88
	v_pk_fma_f32 v[80:81], v[36:37], v[98:99], v[80:81] op_sel:[1,0,0]
	v_cvt_f32_ubyte0_e32 v104, v89
	v_cvt_f32_ubyte1_e32 v105, v89
	v_pk_fma_f32 v[78:79], v[36:37], v[102:103], v[78:79] op_sel:[1,0,0]
	v_cvt_f32_ubyte2_e32 v146, v89
	v_cvt_f32_ubyte3_e32 v147, v89
	v_pk_fma_f32 v[70:71], v[44:45], v[104:105], v[70:71] op_sel:[1,0,0]
	v_cvt_f32_ubyte0_e32 v98, v68
	v_cvt_f32_ubyte1_e32 v99, v68
	v_pk_fma_f32 v[62:63], v[44:45], v[146:147], v[62:63] op_sel:[1,0,0]
	v_cvt_f32_ubyte2_e32 v102, v68
	v_cvt_f32_ubyte3_e32 v103, v68
	v_pk_fma_f32 v[92:93], v[38:39], v[98:99], v[92:93] op_sel_hi:[0,1,1]
	v_cvt_f32_ubyte0_e32 v104, v69
	v_cvt_f32_ubyte1_e32 v105, v69
	v_pk_fma_f32 v[90:91], v[38:39], v[102:103], v[90:91] op_sel_hi:[0,1,1]
	v_cvt_f32_ubyte2_e32 v146, v69
	v_cvt_f32_ubyte3_e32 v147, v69
	v_pk_fma_f32 v[86:87], v[46:47], v[104:105], v[86:87] op_sel_hi:[0,1,1]
	v_cvt_f32_ubyte0_e32 v98, v76
	v_cvt_f32_ubyte1_e32 v99, v76
	v_pk_fma_f32 v[84:85], v[46:47], v[146:147], v[84:85] op_sel_hi:[0,1,1]
	v_and_b32_e32 v82, s0, v174
	v_and_b32_e32 v83, s1, v174
	v_and_b32_e32 v88, s0, v175
	v_and_b32_e32 v89, s1, v175
	v_cvt_f32_ubyte2_e32 v102, v76
	v_cvt_f32_ubyte3_e32 v103, v76
	v_pk_fma_f32 v[80:81], v[38:39], v[98:99], v[80:81] op_sel_hi:[0,1,1]
	v_cvt_f32_ubyte0_e32 v104, v77
	v_cvt_f32_ubyte1_e32 v105, v77
	v_pk_fma_f32 v[78:79], v[38:39], v[102:103], v[78:79] op_sel_hi:[0,1,1]
	v_cvt_f32_ubyte2_e32 v146, v77
	v_cvt_f32_ubyte3_e32 v147, v77
	v_pk_fma_f32 v[70:71], v[46:47], v[104:105], v[70:71] op_sel_hi:[0,1,1]
	v_cvt_f32_ubyte0_e32 v98, v82
	v_cvt_f32_ubyte1_e32 v99, v82
	v_pk_fma_f32 v[62:63], v[46:47], v[146:147], v[62:63] op_sel_hi:[0,1,1]
	v_cvt_f32_ubyte2_e32 v102, v82
	v_cvt_f32_ubyte3_e32 v103, v82
	v_pk_fma_f32 v[92:93], v[38:39], v[98:99], v[92:93] op_sel:[1,0,0]
	v_cvt_f32_ubyte0_e32 v104, v83
	v_cvt_f32_ubyte1_e32 v105, v83
	v_pk_fma_f32 v[90:91], v[38:39], v[102:103], v[90:91] op_sel:[1,0,0]
	v_cvt_f32_ubyte2_e32 v146, v83
	v_cvt_f32_ubyte3_e32 v147, v83
	v_pk_fma_f32 v[86:87], v[46:47], v[104:105], v[86:87] op_sel:[1,0,0]
	v_cvt_f32_ubyte0_e32 v98, v88
	v_cvt_f32_ubyte1_e32 v99, v88
	v_pk_fma_f32 v[84:85], v[46:47], v[146:147], v[84:85] op_sel:[1,0,0]
	v_and_b32_e32 v68, s0, v176
	v_and_b32_e32 v69, s1, v176
	v_and_b32_e32 v76, s0, v177
	v_and_b32_e32 v77, s1, v177
	v_cvt_f32_ubyte2_e32 v102, v88
	v_cvt_f32_ubyte3_e32 v103, v88
	v_pk_fma_f32 v[80:81], v[38:39], v[98:99], v[80:81] op_sel:[1,0,0]
	v_cvt_f32_ubyte0_e32 v104, v89
	v_cvt_f32_ubyte1_e32 v105, v89
	v_pk_fma_f32 v[78:79], v[38:39], v[102:103], v[78:79] op_sel:[1,0,0]
	v_cvt_f32_ubyte2_e32 v146, v89
	v_cvt_f32_ubyte3_e32 v147, v89
	v_pk_fma_f32 v[70:71], v[46:47], v[104:105], v[70:71] op_sel:[1,0,0]
	v_cvt_f32_ubyte0_e32 v98, v68
	v_cvt_f32_ubyte1_e32 v99, v68
	v_pk_fma_f32 v[62:63], v[46:47], v[146:147], v[62:63] op_sel:[1,0,0]
	v_cvt_f32_ubyte2_e32 v102, v68
	v_cvt_f32_ubyte3_e32 v103, v68
	v_pk_fma_f32 v[92:93], v[40:41], v[98:99], v[92:93] op_sel_hi:[0,1,1]
	v_cvt_f32_ubyte0_e32 v104, v69
	v_cvt_f32_ubyte1_e32 v105, v69
	v_pk_fma_f32 v[90:91], v[40:41], v[102:103], v[90:91] op_sel_hi:[0,1,1]
	v_cvt_f32_ubyte2_e32 v146, v69
	v_cvt_f32_ubyte3_e32 v147, v69
	v_pk_fma_f32 v[86:87], v[48:49], v[104:105], v[86:87] op_sel_hi:[0,1,1]
	v_cvt_f32_ubyte0_e32 v98, v76
	v_cvt_f32_ubyte1_e32 v99, v76
	v_pk_fma_f32 v[84:85], v[48:49], v[146:147], v[84:85] op_sel_hi:[0,1,1]
	v_and_b32_e32 v82, s0, v178
	v_and_b32_e32 v83, s1, v178
	v_and_b32_e32 v88, s0, v179
	v_and_b32_e32 v89, s1, v179
	v_cvt_f32_ubyte2_e32 v102, v76
	v_cvt_f32_ubyte3_e32 v103, v76
	v_pk_fma_f32 v[80:81], v[40:41], v[98:99], v[80:81] op_sel_hi:[0,1,1]
	v_cvt_f32_ubyte0_e32 v104, v77
	v_cvt_f32_ubyte1_e32 v105, v77
	v_pk_fma_f32 v[78:79], v[40:41], v[102:103], v[78:79] op_sel_hi:[0,1,1]
	v_cvt_f32_ubyte2_e32 v146, v77
	v_cvt_f32_ubyte3_e32 v147, v77
	v_pk_fma_f32 v[70:71], v[48:49], v[104:105], v[70:71] op_sel_hi:[0,1,1]
	v_cvt_f32_ubyte0_e32 v98, v82
	v_cvt_f32_ubyte1_e32 v99, v82
	v_pk_fma_f32 v[62:63], v[48:49], v[146:147], v[62:63] op_sel_hi:[0,1,1]
	v_cvt_f32_ubyte2_e32 v102, v82
	v_cvt_f32_ubyte3_e32 v103, v82
	v_pk_fma_f32 v[92:93], v[40:41], v[98:99], v[92:93] op_sel:[1,0,0]
	v_cvt_f32_ubyte0_e32 v104, v83
	v_cvt_f32_ubyte1_e32 v105, v83
	v_pk_fma_f32 v[90:91], v[40:41], v[102:103], v[90:91] op_sel:[1,0,0]
	v_cvt_f32_ubyte2_e32 v146, v83
	v_cvt_f32_ubyte3_e32 v147, v83
	v_pk_fma_f32 v[86:87], v[48:49], v[104:105], v[86:87] op_sel:[1,0,0]
	v_cvt_f32_ubyte0_e32 v98, v88
	v_cvt_f32_ubyte1_e32 v99, v88
	v_pk_fma_f32 v[84:85], v[48:49], v[146:147], v[84:85] op_sel:[1,0,0]
	v_cvt_f32_ubyte2_e32 v102, v88
	v_cvt_f32_ubyte3_e32 v103, v88
	v_pk_fma_f32 v[80:81], v[40:41], v[98:99], v[80:81] op_sel:[1,0,0]
	v_cvt_f32_ubyte0_e32 v104, v89
	v_cvt_f32_ubyte1_e32 v105, v89
	v_pk_fma_f32 v[78:79], v[40:41], v[102:103], v[78:79] op_sel:[1,0,0]
	v_cvt_f32_ubyte2_e32 v146, v89
	v_cvt_f32_ubyte3_e32 v147, v89
	v_pk_fma_f32 v[70:71], v[48:49], v[104:105], v[70:71] op_sel:[1,0,0]
	v_pk_fma_f32 v[62:63], v[48:49], v[146:147], v[62:63] op_sel:[1,0,0]
	s_waitcnt lgkmcnt(0)
	v_lshl_add_u32 v72, v72, 9, v100
	v_lshl_add_u32 v73, v73, 9, v100
	v_lshl_add_u32 v74, v74, 9, v100
	v_lshl_add_u32 v75, v75, 9, v100
	v_lshl_add_u32 v94, v94, 9, v100
	v_lshl_add_u32 v95, v95, 9, v100
	v_lshl_add_u32 v96, v96, 9, v100
	v_lshl_add_u32 v97, v97, 9, v100
	global_load_dwordx2 v[164:165], v72, s[38:39]
	global_load_dwordx2 v[166:167], v73, s[38:39]
	global_load_dwordx2 v[168:169], v74, s[38:39]
	global_load_dwordx2 v[170:171], v75, s[38:39]
	global_load_dwordx2 v[172:173], v94, s[38:39]
	global_load_dwordx2 v[174:175], v95, s[38:39]
	global_load_dwordx2 v[176:177], v96, s[38:39]
	global_load_dwordx2 v[178:179], v97, s[38:39]
	ds_read_b128 v[72:75], v1 offset:416
	ds_read_b128 v[94:97], v1 offset:432
	ds_read_b128 v[34:37], v1 offset:768
	ds_read_b128 v[38:41], v1 offset:784
	ds_read_b128 v[42:45], v1 offset:1792
	ds_read_b128 v[46:49], v1 offset:1808
	s_waitcnt vmcnt(40)
	v_and_b32_e32 v68, s0, v180
	v_and_b32_e32 v69, s1, v180
	v_and_b32_e32 v76, s0, v181
	v_and_b32_e32 v77, s1, v181
	v_cvt_f32_ubyte0_e32 v98, v68
	v_cvt_f32_ubyte1_e32 v99, v68
	v_cvt_f32_ubyte2_e32 v102, v68
	v_cvt_f32_ubyte3_e32 v103, v68
	v_pk_fma_f32 v[92:93], v[50:51], v[98:99], v[92:93] op_sel_hi:[0,1,1]
	v_cvt_f32_ubyte0_e32 v104, v69
	v_cvt_f32_ubyte1_e32 v105, v69
	v_pk_fma_f32 v[90:91], v[50:51], v[102:103], v[90:91] op_sel_hi:[0,1,1]
	v_cvt_f32_ubyte2_e32 v146, v69
	v_cvt_f32_ubyte3_e32 v147, v69
	v_pk_fma_f32 v[86:87], v[58:59], v[104:105], v[86:87] op_sel_hi:[0,1,1]
	v_cvt_f32_ubyte0_e32 v98, v76
	v_cvt_f32_ubyte1_e32 v99, v76
	v_pk_fma_f32 v[84:85], v[58:59], v[146:147], v[84:85] op_sel_hi:[0,1,1]
	v_and_b32_e32 v82, s0, v182
	v_and_b32_e32 v83, s1, v182
	v_and_b32_e32 v88, s0, v183
	v_and_b32_e32 v89, s1, v183
	v_cvt_f32_ubyte2_e32 v102, v76
	v_cvt_f32_ubyte3_e32 v103, v76
	v_pk_fma_f32 v[80:81], v[50:51], v[98:99], v[80:81] op_sel_hi:[0,1,1]
	v_cvt_f32_ubyte0_e32 v104, v77
	v_cvt_f32_ubyte1_e32 v105, v77
	v_pk_fma_f32 v[78:79], v[50:51], v[102:103], v[78:79] op_sel_hi:[0,1,1]
	v_cvt_f32_ubyte2_e32 v146, v77
	v_cvt_f32_ubyte3_e32 v147, v77
	v_pk_fma_f32 v[70:71], v[58:59], v[104:105], v[70:71] op_sel_hi:[0,1,1]
	v_cvt_f32_ubyte0_e32 v98, v82
	v_cvt_f32_ubyte1_e32 v99, v82
	v_pk_fma_f32 v[62:63], v[58:59], v[146:147], v[62:63] op_sel_hi:[0,1,1]
	v_cvt_f32_ubyte2_e32 v102, v82
	v_cvt_f32_ubyte3_e32 v103, v82
	v_pk_fma_f32 v[92:93], v[50:51], v[98:99], v[92:93] op_sel:[1,0,0]
	v_cvt_f32_ubyte0_e32 v104, v83
	v_cvt_f32_ubyte1_e32 v105, v83
	v_pk_fma_f32 v[90:91], v[50:51], v[102:103], v[90:91] op_sel:[1,0,0]
	v_cvt_f32_ubyte2_e32 v146, v83
	v_cvt_f32_ubyte3_e32 v147, v83
	v_pk_fma_f32 v[86:87], v[58:59], v[104:105], v[86:87] op_sel:[1,0,0]
	v_cvt_f32_ubyte0_e32 v98, v88
	v_cvt_f32_ubyte1_e32 v99, v88
	v_pk_fma_f32 v[84:85], v[58:59], v[146:147], v[84:85] op_sel:[1,0,0]
	v_and_b32_e32 v68, s0, v184
	v_and_b32_e32 v69, s1, v184
	v_and_b32_e32 v76, s0, v185
	v_and_b32_e32 v77, s1, v185
	v_cvt_f32_ubyte2_e32 v102, v88
	v_cvt_f32_ubyte3_e32 v103, v88
	v_pk_fma_f32 v[80:81], v[50:51], v[98:99], v[80:81] op_sel:[1,0,0]
	v_cvt_f32_ubyte0_e32 v104, v89
	v_cvt_f32_ubyte1_e32 v105, v89
	v_pk_fma_f32 v[78:79], v[50:51], v[102:103], v[78:79] op_sel:[1,0,0]
	v_cvt_f32_ubyte2_e32 v146, v89
	v_cvt_f32_ubyte3_e32 v147, v89
	v_pk_fma_f32 v[70:71], v[58:59], v[104:105], v[70:71] op_sel:[1,0,0]
	v_cvt_f32_ubyte0_e32 v98, v68
	v_cvt_f32_ubyte1_e32 v99, v68
	v_pk_fma_f32 v[62:63], v[58:59], v[146:147], v[62:63] op_sel:[1,0,0]
	v_cvt_f32_ubyte2_e32 v102, v68
	v_cvt_f32_ubyte3_e32 v103, v68
	v_pk_fma_f32 v[92:93], v[52:53], v[98:99], v[92:93] op_sel_hi:[0,1,1]
	v_cvt_f32_ubyte0_e32 v104, v69
	v_cvt_f32_ubyte1_e32 v105, v69
	v_pk_fma_f32 v[90:91], v[52:53], v[102:103], v[90:91] op_sel_hi:[0,1,1]
	v_cvt_f32_ubyte2_e32 v146, v69
	v_cvt_f32_ubyte3_e32 v147, v69
	v_pk_fma_f32 v[86:87], v[60:61], v[104:105], v[86:87] op_sel_hi:[0,1,1]
	v_cvt_f32_ubyte0_e32 v98, v76
	v_cvt_f32_ubyte1_e32 v99, v76
	v_pk_fma_f32 v[84:85], v[60:61], v[146:147], v[84:85] op_sel_hi:[0,1,1]
	v_and_b32_e32 v82, s0, v186
	v_and_b32_e32 v83, s1, v186
	v_and_b32_e32 v88, s0, v187
	v_and_b32_e32 v89, s1, v187
	v_cvt_f32_ubyte2_e32 v102, v76
	v_cvt_f32_ubyte3_e32 v103, v76
	v_pk_fma_f32 v[80:81], v[52:53], v[98:99], v[80:81] op_sel_hi:[0,1,1]
	v_cvt_f32_ubyte0_e32 v104, v77
	v_cvt_f32_ubyte1_e32 v105, v77
	v_pk_fma_f32 v[78:79], v[52:53], v[102:103], v[78:79] op_sel_hi:[0,1,1]
	v_cvt_f32_ubyte2_e32 v146, v77
	v_cvt_f32_ubyte3_e32 v147, v77
	v_pk_fma_f32 v[70:71], v[60:61], v[104:105], v[70:71] op_sel_hi:[0,1,1]
	v_cvt_f32_ubyte0_e32 v98, v82
	v_cvt_f32_ubyte1_e32 v99, v82
	v_pk_fma_f32 v[62:63], v[60:61], v[146:147], v[62:63] op_sel_hi:[0,1,1]
	v_cvt_f32_ubyte2_e32 v102, v82
	v_cvt_f32_ubyte3_e32 v103, v82
	v_pk_fma_f32 v[92:93], v[52:53], v[98:99], v[92:93] op_sel:[1,0,0]
	v_cvt_f32_ubyte0_e32 v104, v83
	v_cvt_f32_ubyte1_e32 v105, v83
	v_pk_fma_f32 v[90:91], v[52:53], v[102:103], v[90:91] op_sel:[1,0,0]
	v_cvt_f32_ubyte2_e32 v146, v83
	v_cvt_f32_ubyte3_e32 v147, v83
	v_pk_fma_f32 v[86:87], v[60:61], v[104:105], v[86:87] op_sel:[1,0,0]
	v_cvt_f32_ubyte0_e32 v98, v88
	v_cvt_f32_ubyte1_e32 v99, v88
	v_pk_fma_f32 v[84:85], v[60:61], v[146:147], v[84:85] op_sel:[1,0,0]
	v_and_b32_e32 v68, s0, v188
	v_and_b32_e32 v69, s1, v188
	v_and_b32_e32 v76, s0, v189
	v_and_b32_e32 v77, s1, v189
	v_cvt_f32_ubyte2_e32 v102, v88
	v_cvt_f32_ubyte3_e32 v103, v88
	v_pk_fma_f32 v[80:81], v[52:53], v[98:99], v[80:81] op_sel:[1,0,0]
	v_cvt_f32_ubyte0_e32 v104, v89
	v_cvt_f32_ubyte1_e32 v105, v89
	v_pk_fma_f32 v[78:79], v[52:53], v[102:103], v[78:79] op_sel:[1,0,0]
	v_cvt_f32_ubyte2_e32 v146, v89
	v_cvt_f32_ubyte3_e32 v147, v89
	v_pk_fma_f32 v[70:71], v[60:61], v[104:105], v[70:71] op_sel:[1,0,0]
	v_cvt_f32_ubyte0_e32 v98, v68
	v_cvt_f32_ubyte1_e32 v99, v68
	v_pk_fma_f32 v[62:63], v[60:61], v[146:147], v[62:63] op_sel:[1,0,0]
	v_cvt_f32_ubyte2_e32 v102, v68
	v_cvt_f32_ubyte3_e32 v103, v68
	v_pk_fma_f32 v[92:93], v[54:55], v[98:99], v[92:93] op_sel_hi:[0,1,1]
	v_cvt_f32_ubyte0_e32 v104, v69
	v_cvt_f32_ubyte1_e32 v105, v69
	v_pk_fma_f32 v[90:91], v[54:55], v[102:103], v[90:91] op_sel_hi:[0,1,1]
	v_cvt_f32_ubyte2_e32 v146, v69
	v_cvt_f32_ubyte3_e32 v147, v69
	v_pk_fma_f32 v[86:87], v[64:65], v[104:105], v[86:87] op_sel_hi:[0,1,1]
	v_cvt_f32_ubyte0_e32 v98, v76
	v_cvt_f32_ubyte1_e32 v99, v76
	v_pk_fma_f32 v[84:85], v[64:65], v[146:147], v[84:85] op_sel_hi:[0,1,1]
	v_and_b32_e32 v82, s0, v190
	v_and_b32_e32 v83, s1, v190
	v_and_b32_e32 v88, s0, v191
	v_and_b32_e32 v89, s1, v191
	v_cvt_f32_ubyte2_e32 v102, v76
	v_cvt_f32_ubyte3_e32 v103, v76
	v_pk_fma_f32 v[80:81], v[54:55], v[98:99], v[80:81] op_sel_hi:[0,1,1]
	v_cvt_f32_ubyte0_e32 v104, v77
	v_cvt_f32_ubyte1_e32 v105, v77
	v_pk_fma_f32 v[78:79], v[54:55], v[102:103], v[78:79] op_sel_hi:[0,1,1]
	v_cvt_f32_ubyte2_e32 v146, v77
	v_cvt_f32_ubyte3_e32 v147, v77
	v_pk_fma_f32 v[70:71], v[64:65], v[104:105], v[70:71] op_sel_hi:[0,1,1]
	v_cvt_f32_ubyte0_e32 v98, v82
	v_cvt_f32_ubyte1_e32 v99, v82
	v_pk_fma_f32 v[62:63], v[64:65], v[146:147], v[62:63] op_sel_hi:[0,1,1]
	v_cvt_f32_ubyte2_e32 v102, v82
	v_cvt_f32_ubyte3_e32 v103, v82
	v_pk_fma_f32 v[92:93], v[54:55], v[98:99], v[92:93] op_sel:[1,0,0]
	v_cvt_f32_ubyte0_e32 v104, v83
	v_cvt_f32_ubyte1_e32 v105, v83
	v_pk_fma_f32 v[90:91], v[54:55], v[102:103], v[90:91] op_sel:[1,0,0]
	v_cvt_f32_ubyte2_e32 v146, v83
	v_cvt_f32_ubyte3_e32 v147, v83
	v_pk_fma_f32 v[86:87], v[64:65], v[104:105], v[86:87] op_sel:[1,0,0]
	v_cvt_f32_ubyte0_e32 v98, v88
	v_cvt_f32_ubyte1_e32 v99, v88
	v_pk_fma_f32 v[84:85], v[64:65], v[146:147], v[84:85] op_sel:[1,0,0]
	v_and_b32_e32 v68, s0, v192
	v_and_b32_e32 v69, s1, v192
	v_and_b32_e32 v76, s0, v193
	v_and_b32_e32 v77, s1, v193
	v_cvt_f32_ubyte2_e32 v102, v88
	v_cvt_f32_ubyte3_e32 v103, v88
	v_pk_fma_f32 v[80:81], v[54:55], v[98:99], v[80:81] op_sel:[1,0,0]
	v_cvt_f32_ubyte0_e32 v104, v89
	v_cvt_f32_ubyte1_e32 v105, v89
	v_pk_fma_f32 v[78:79], v[54:55], v[102:103], v[78:79] op_sel:[1,0,0]
	v_cvt_f32_ubyte2_e32 v146, v89
	v_cvt_f32_ubyte3_e32 v147, v89
	v_pk_fma_f32 v[70:71], v[64:65], v[104:105], v[70:71] op_sel:[1,0,0]
	v_cvt_f32_ubyte0_e32 v98, v68
	v_cvt_f32_ubyte1_e32 v99, v68
	v_pk_fma_f32 v[62:63], v[64:65], v[146:147], v[62:63] op_sel:[1,0,0]
	v_cvt_f32_ubyte2_e32 v102, v68
	v_cvt_f32_ubyte3_e32 v103, v68
	v_pk_fma_f32 v[92:93], v[56:57], v[98:99], v[92:93] op_sel_hi:[0,1,1]
	v_cvt_f32_ubyte0_e32 v104, v69
	v_cvt_f32_ubyte1_e32 v105, v69
	v_pk_fma_f32 v[90:91], v[56:57], v[102:103], v[90:91] op_sel_hi:[0,1,1]
	v_cvt_f32_ubyte2_e32 v146, v69
	v_cvt_f32_ubyte3_e32 v147, v69
	v_pk_fma_f32 v[86:87], v[66:67], v[104:105], v[86:87] op_sel_hi:[0,1,1]
	v_cvt_f32_ubyte0_e32 v98, v76
	v_cvt_f32_ubyte1_e32 v99, v76
	v_pk_fma_f32 v[84:85], v[66:67], v[146:147], v[84:85] op_sel_hi:[0,1,1]
	v_and_b32_e32 v82, s0, v194
	v_and_b32_e32 v83, s1, v194
	v_and_b32_e32 v88, s0, v195
	v_and_b32_e32 v89, s1, v195
	v_cvt_f32_ubyte2_e32 v102, v76
	v_cvt_f32_ubyte3_e32 v103, v76
	v_pk_fma_f32 v[80:81], v[56:57], v[98:99], v[80:81] op_sel_hi:[0,1,1]
	v_cvt_f32_ubyte0_e32 v104, v77
	v_cvt_f32_ubyte1_e32 v105, v77
	v_pk_fma_f32 v[78:79], v[56:57], v[102:103], v[78:79] op_sel_hi:[0,1,1]
	v_cvt_f32_ubyte2_e32 v146, v77
	v_cvt_f32_ubyte3_e32 v147, v77
	v_pk_fma_f32 v[70:71], v[66:67], v[104:105], v[70:71] op_sel_hi:[0,1,1]
	v_cvt_f32_ubyte0_e32 v98, v82
	v_cvt_f32_ubyte1_e32 v99, v82
	v_pk_fma_f32 v[62:63], v[66:67], v[146:147], v[62:63] op_sel_hi:[0,1,1]
	v_cvt_f32_ubyte2_e32 v102, v82
	v_cvt_f32_ubyte3_e32 v103, v82
	v_pk_fma_f32 v[92:93], v[56:57], v[98:99], v[92:93] op_sel:[1,0,0]
	v_cvt_f32_ubyte0_e32 v104, v83
	v_cvt_f32_ubyte1_e32 v105, v83
	v_pk_fma_f32 v[90:91], v[56:57], v[102:103], v[90:91] op_sel:[1,0,0]
	v_cvt_f32_ubyte2_e32 v146, v83
	v_cvt_f32_ubyte3_e32 v147, v83
	v_pk_fma_f32 v[86:87], v[66:67], v[104:105], v[86:87] op_sel:[1,0,0]
	v_cvt_f32_ubyte0_e32 v98, v88
	v_cvt_f32_ubyte1_e32 v99, v88
	v_pk_fma_f32 v[84:85], v[66:67], v[146:147], v[84:85] op_sel:[1,0,0]
	v_cvt_f32_ubyte2_e32 v102, v88
	v_cvt_f32_ubyte3_e32 v103, v88
	v_pk_fma_f32 v[80:81], v[56:57], v[98:99], v[80:81] op_sel:[1,0,0]
	v_cvt_f32_ubyte0_e32 v104, v89
	v_cvt_f32_ubyte1_e32 v105, v89
	v_pk_fma_f32 v[78:79], v[56:57], v[102:103], v[78:79] op_sel:[1,0,0]
	v_cvt_f32_ubyte2_e32 v146, v89
	v_cvt_f32_ubyte3_e32 v147, v89
	v_pk_fma_f32 v[70:71], v[66:67], v[104:105], v[70:71] op_sel:[1,0,0]
	v_pk_fma_f32 v[62:63], v[66:67], v[146:147], v[62:63] op_sel:[1,0,0]
	s_waitcnt lgkmcnt(0)
	v_lshl_add_u32 v72, v72, 9, v100
	v_lshl_add_u32 v73, v73, 9, v100
	v_lshl_add_u32 v74, v74, 9, v100
	v_lshl_add_u32 v75, v75, 9, v100
	v_lshl_add_u32 v94, v94, 9, v100
	v_lshl_add_u32 v95, v95, 9, v100
	v_lshl_add_u32 v96, v96, 9, v100
	v_lshl_add_u32 v97, v97, 9, v100
	global_load_dwordx2 v[180:181], v72, s[38:39]
	global_load_dwordx2 v[182:183], v73, s[38:39]
	global_load_dwordx2 v[184:185], v74, s[38:39]
	global_load_dwordx2 v[186:187], v75, s[38:39]
	global_load_dwordx2 v[188:189], v94, s[38:39]
	global_load_dwordx2 v[190:191], v95, s[38:39]
	global_load_dwordx2 v[192:193], v96, s[38:39]
	global_load_dwordx2 v[194:195], v97, s[38:39]
	ds_read_b128 v[72:75], v1 offset:448
	ds_read_b128 v[94:97], v1 offset:464
	ds_read_b128 v[50:53], v1 offset:800
	ds_read_b128 v[54:57], v1 offset:816
	ds_read_b128 v[58:61], v1 offset:1824
	ds_read_b128 v[64:67], v1 offset:1840
	s_waitcnt vmcnt(40)
	v_and_b32_e32 v68, s0, v196
	v_and_b32_e32 v69, s1, v196
	v_and_b32_e32 v76, s0, v197
	v_and_b32_e32 v77, s1, v197
	v_cvt_f32_ubyte0_e32 v98, v68
	v_cvt_f32_ubyte1_e32 v99, v68
	v_cvt_f32_ubyte2_e32 v102, v68
	v_cvt_f32_ubyte3_e32 v103, v68
	v_pk_fma_f32 v[92:93], v[34:35], v[98:99], v[92:93] op_sel_hi:[0,1,1]
	v_cvt_f32_ubyte0_e32 v104, v69
	v_cvt_f32_ubyte1_e32 v105, v69
	v_pk_fma_f32 v[90:91], v[34:35], v[102:103], v[90:91] op_sel_hi:[0,1,1]
	v_cvt_f32_ubyte2_e32 v146, v69
	v_cvt_f32_ubyte3_e32 v147, v69
	v_pk_fma_f32 v[86:87], v[42:43], v[104:105], v[86:87] op_sel_hi:[0,1,1]
	v_cvt_f32_ubyte0_e32 v98, v76
	v_cvt_f32_ubyte1_e32 v99, v76
	v_pk_fma_f32 v[84:85], v[42:43], v[146:147], v[84:85] op_sel_hi:[0,1,1]
	v_and_b32_e32 v82, s0, v198
	v_and_b32_e32 v83, s1, v198
	v_and_b32_e32 v88, s0, v199
	v_and_b32_e32 v89, s1, v199
	v_cvt_f32_ubyte2_e32 v102, v76
	v_cvt_f32_ubyte3_e32 v103, v76
	v_pk_fma_f32 v[80:81], v[34:35], v[98:99], v[80:81] op_sel_hi:[0,1,1]
	v_cvt_f32_ubyte0_e32 v104, v77
	v_cvt_f32_ubyte1_e32 v105, v77
	v_pk_fma_f32 v[78:79], v[34:35], v[102:103], v[78:79] op_sel_hi:[0,1,1]
	v_cvt_f32_ubyte2_e32 v146, v77
	v_cvt_f32_ubyte3_e32 v147, v77
	v_pk_fma_f32 v[70:71], v[42:43], v[104:105], v[70:71] op_sel_hi:[0,1,1]
	v_cvt_f32_ubyte0_e32 v98, v82
	v_cvt_f32_ubyte1_e32 v99, v82
	v_pk_fma_f32 v[62:63], v[42:43], v[146:147], v[62:63] op_sel_hi:[0,1,1]
	v_cvt_f32_ubyte2_e32 v102, v82
	v_cvt_f32_ubyte3_e32 v103, v82
	v_pk_fma_f32 v[92:93], v[34:35], v[98:99], v[92:93] op_sel:[1,0,0]
	v_cvt_f32_ubyte0_e32 v104, v83
	v_cvt_f32_ubyte1_e32 v105, v83
	v_pk_fma_f32 v[90:91], v[34:35], v[102:103], v[90:91] op_sel:[1,0,0]
	v_cvt_f32_ubyte2_e32 v146, v83
	v_cvt_f32_ubyte3_e32 v147, v83
	v_pk_fma_f32 v[86:87], v[42:43], v[104:105], v[86:87] op_sel:[1,0,0]
	v_cvt_f32_ubyte0_e32 v98, v88
	v_cvt_f32_ubyte1_e32 v99, v88
	v_pk_fma_f32 v[84:85], v[42:43], v[146:147], v[84:85] op_sel:[1,0,0]
	v_and_b32_e32 v68, s0, v200
	v_and_b32_e32 v69, s1, v200
	v_and_b32_e32 v76, s0, v201
	v_and_b32_e32 v77, s1, v201
	v_cvt_f32_ubyte2_e32 v102, v88
	v_cvt_f32_ubyte3_e32 v103, v88
	v_pk_fma_f32 v[80:81], v[34:35], v[98:99], v[80:81] op_sel:[1,0,0]
	v_cvt_f32_ubyte0_e32 v104, v89
	v_cvt_f32_ubyte1_e32 v105, v89
	v_pk_fma_f32 v[78:79], v[34:35], v[102:103], v[78:79] op_sel:[1,0,0]
	v_cvt_f32_ubyte2_e32 v146, v89
	v_cvt_f32_ubyte3_e32 v147, v89
	v_pk_fma_f32 v[70:71], v[42:43], v[104:105], v[70:71] op_sel:[1,0,0]
	v_cvt_f32_ubyte0_e32 v98, v68
	v_cvt_f32_ubyte1_e32 v99, v68
	v_pk_fma_f32 v[62:63], v[42:43], v[146:147], v[62:63] op_sel:[1,0,0]
	v_cvt_f32_ubyte2_e32 v102, v68
	v_cvt_f32_ubyte3_e32 v103, v68
	v_pk_fma_f32 v[92:93], v[36:37], v[98:99], v[92:93] op_sel_hi:[0,1,1]
	v_cvt_f32_ubyte0_e32 v104, v69
	v_cvt_f32_ubyte1_e32 v105, v69
	v_pk_fma_f32 v[90:91], v[36:37], v[102:103], v[90:91] op_sel_hi:[0,1,1]
	v_cvt_f32_ubyte2_e32 v146, v69
	v_cvt_f32_ubyte3_e32 v147, v69
	v_pk_fma_f32 v[86:87], v[44:45], v[104:105], v[86:87] op_sel_hi:[0,1,1]
	v_cvt_f32_ubyte0_e32 v98, v76
	v_cvt_f32_ubyte1_e32 v99, v76
	v_pk_fma_f32 v[84:85], v[44:45], v[146:147], v[84:85] op_sel_hi:[0,1,1]
	v_and_b32_e32 v82, s0, v202
	v_and_b32_e32 v83, s1, v202
	v_and_b32_e32 v88, s0, v203
	v_and_b32_e32 v89, s1, v203
	v_cvt_f32_ubyte2_e32 v102, v76
	v_cvt_f32_ubyte3_e32 v103, v76
	v_pk_fma_f32 v[80:81], v[36:37], v[98:99], v[80:81] op_sel_hi:[0,1,1]
	v_cvt_f32_ubyte0_e32 v104, v77
	v_cvt_f32_ubyte1_e32 v105, v77
	v_pk_fma_f32 v[78:79], v[36:37], v[102:103], v[78:79] op_sel_hi:[0,1,1]
	v_cvt_f32_ubyte2_e32 v146, v77
	v_cvt_f32_ubyte3_e32 v147, v77
	v_pk_fma_f32 v[70:71], v[44:45], v[104:105], v[70:71] op_sel_hi:[0,1,1]
	v_cvt_f32_ubyte0_e32 v98, v82
	v_cvt_f32_ubyte1_e32 v99, v82
	v_pk_fma_f32 v[62:63], v[44:45], v[146:147], v[62:63] op_sel_hi:[0,1,1]
	v_cvt_f32_ubyte2_e32 v102, v82
	v_cvt_f32_ubyte3_e32 v103, v82
	v_pk_fma_f32 v[92:93], v[36:37], v[98:99], v[92:93] op_sel:[1,0,0]
	v_cvt_f32_ubyte0_e32 v104, v83
	v_cvt_f32_ubyte1_e32 v105, v83
	v_pk_fma_f32 v[90:91], v[36:37], v[102:103], v[90:91] op_sel:[1,0,0]
	v_cvt_f32_ubyte2_e32 v146, v83
	v_cvt_f32_ubyte3_e32 v147, v83
	v_pk_fma_f32 v[86:87], v[44:45], v[104:105], v[86:87] op_sel:[1,0,0]
	v_cvt_f32_ubyte0_e32 v98, v88
	v_cvt_f32_ubyte1_e32 v99, v88
	v_pk_fma_f32 v[84:85], v[44:45], v[146:147], v[84:85] op_sel:[1,0,0]
	v_and_b32_e32 v68, s0, v204
	v_and_b32_e32 v69, s1, v204
	v_and_b32_e32 v76, s0, v205
	v_and_b32_e32 v77, s1, v205
	v_cvt_f32_ubyte2_e32 v102, v88
	v_cvt_f32_ubyte3_e32 v103, v88
	v_pk_fma_f32 v[80:81], v[36:37], v[98:99], v[80:81] op_sel:[1,0,0]
	v_cvt_f32_ubyte0_e32 v104, v89
	v_cvt_f32_ubyte1_e32 v105, v89
	v_pk_fma_f32 v[78:79], v[36:37], v[102:103], v[78:79] op_sel:[1,0,0]
	v_cvt_f32_ubyte2_e32 v146, v89
	v_cvt_f32_ubyte3_e32 v147, v89
	v_pk_fma_f32 v[70:71], v[44:45], v[104:105], v[70:71] op_sel:[1,0,0]
	v_cvt_f32_ubyte0_e32 v98, v68
	v_cvt_f32_ubyte1_e32 v99, v68
	v_pk_fma_f32 v[62:63], v[44:45], v[146:147], v[62:63] op_sel:[1,0,0]
	v_cvt_f32_ubyte2_e32 v102, v68
	v_cvt_f32_ubyte3_e32 v103, v68
	v_pk_fma_f32 v[92:93], v[38:39], v[98:99], v[92:93] op_sel_hi:[0,1,1]
	v_cvt_f32_ubyte0_e32 v104, v69
	v_cvt_f32_ubyte1_e32 v105, v69
	v_pk_fma_f32 v[90:91], v[38:39], v[102:103], v[90:91] op_sel_hi:[0,1,1]
	v_cvt_f32_ubyte2_e32 v146, v69
	v_cvt_f32_ubyte3_e32 v147, v69
	v_pk_fma_f32 v[86:87], v[46:47], v[104:105], v[86:87] op_sel_hi:[0,1,1]
	v_cvt_f32_ubyte0_e32 v98, v76
	v_cvt_f32_ubyte1_e32 v99, v76
	v_pk_fma_f32 v[84:85], v[46:47], v[146:147], v[84:85] op_sel_hi:[0,1,1]
	v_and_b32_e32 v82, s0, v206
	v_and_b32_e32 v83, s1, v206
	v_and_b32_e32 v88, s0, v207
	v_and_b32_e32 v89, s1, v207
	v_cvt_f32_ubyte2_e32 v102, v76
	v_cvt_f32_ubyte3_e32 v103, v76
	v_pk_fma_f32 v[80:81], v[38:39], v[98:99], v[80:81] op_sel_hi:[0,1,1]
	v_cvt_f32_ubyte0_e32 v104, v77
	v_cvt_f32_ubyte1_e32 v105, v77
	v_pk_fma_f32 v[78:79], v[38:39], v[102:103], v[78:79] op_sel_hi:[0,1,1]
	v_cvt_f32_ubyte2_e32 v146, v77
	v_cvt_f32_ubyte3_e32 v147, v77
	v_pk_fma_f32 v[70:71], v[46:47], v[104:105], v[70:71] op_sel_hi:[0,1,1]
	v_cvt_f32_ubyte0_e32 v98, v82
	v_cvt_f32_ubyte1_e32 v99, v82
	v_pk_fma_f32 v[62:63], v[46:47], v[146:147], v[62:63] op_sel_hi:[0,1,1]
	v_cvt_f32_ubyte2_e32 v102, v82
	v_cvt_f32_ubyte3_e32 v103, v82
	v_pk_fma_f32 v[92:93], v[38:39], v[98:99], v[92:93] op_sel:[1,0,0]
	v_cvt_f32_ubyte0_e32 v104, v83
	v_cvt_f32_ubyte1_e32 v105, v83
	v_pk_fma_f32 v[90:91], v[38:39], v[102:103], v[90:91] op_sel:[1,0,0]
	v_cvt_f32_ubyte2_e32 v146, v83
	v_cvt_f32_ubyte3_e32 v147, v83
	v_pk_fma_f32 v[86:87], v[46:47], v[104:105], v[86:87] op_sel:[1,0,0]
	v_cvt_f32_ubyte0_e32 v98, v88
	v_cvt_f32_ubyte1_e32 v99, v88
	v_pk_fma_f32 v[84:85], v[46:47], v[146:147], v[84:85] op_sel:[1,0,0]
	v_and_b32_e32 v68, s0, v208
	v_and_b32_e32 v69, s1, v208
	v_and_b32_e32 v76, s0, v209
	v_and_b32_e32 v77, s1, v209
	v_cvt_f32_ubyte2_e32 v102, v88
	v_cvt_f32_ubyte3_e32 v103, v88
	v_pk_fma_f32 v[80:81], v[38:39], v[98:99], v[80:81] op_sel:[1,0,0]
	v_cvt_f32_ubyte0_e32 v104, v89
	v_cvt_f32_ubyte1_e32 v105, v89
	v_pk_fma_f32 v[78:79], v[38:39], v[102:103], v[78:79] op_sel:[1,0,0]
	v_cvt_f32_ubyte2_e32 v146, v89
	v_cvt_f32_ubyte3_e32 v147, v89
	v_pk_fma_f32 v[70:71], v[46:47], v[104:105], v[70:71] op_sel:[1,0,0]
	v_cvt_f32_ubyte0_e32 v98, v68
	v_cvt_f32_ubyte1_e32 v99, v68
	v_pk_fma_f32 v[62:63], v[46:47], v[146:147], v[62:63] op_sel:[1,0,0]
	v_cvt_f32_ubyte2_e32 v102, v68
	v_cvt_f32_ubyte3_e32 v103, v68
	v_pk_fma_f32 v[92:93], v[40:41], v[98:99], v[92:93] op_sel_hi:[0,1,1]
	v_cvt_f32_ubyte0_e32 v104, v69
	v_cvt_f32_ubyte1_e32 v105, v69
	v_pk_fma_f32 v[90:91], v[40:41], v[102:103], v[90:91] op_sel_hi:[0,1,1]
	v_cvt_f32_ubyte2_e32 v146, v69
	v_cvt_f32_ubyte3_e32 v147, v69
	v_pk_fma_f32 v[86:87], v[48:49], v[104:105], v[86:87] op_sel_hi:[0,1,1]
	v_cvt_f32_ubyte0_e32 v98, v76
	v_cvt_f32_ubyte1_e32 v99, v76
	v_pk_fma_f32 v[84:85], v[48:49], v[146:147], v[84:85] op_sel_hi:[0,1,1]
	v_and_b32_e32 v82, s0, v210
	v_and_b32_e32 v83, s1, v210
	v_and_b32_e32 v88, s0, v211
	v_and_b32_e32 v89, s1, v211
	v_cvt_f32_ubyte2_e32 v102, v76
	v_cvt_f32_ubyte3_e32 v103, v76
	v_pk_fma_f32 v[80:81], v[40:41], v[98:99], v[80:81] op_sel_hi:[0,1,1]
	v_cvt_f32_ubyte0_e32 v104, v77
	v_cvt_f32_ubyte1_e32 v105, v77
	v_pk_fma_f32 v[78:79], v[40:41], v[102:103], v[78:79] op_sel_hi:[0,1,1]
	v_cvt_f32_ubyte2_e32 v146, v77
	v_cvt_f32_ubyte3_e32 v147, v77
	v_pk_fma_f32 v[70:71], v[48:49], v[104:105], v[70:71] op_sel_hi:[0,1,1]
	v_cvt_f32_ubyte0_e32 v98, v82
	v_cvt_f32_ubyte1_e32 v99, v82
	v_pk_fma_f32 v[62:63], v[48:49], v[146:147], v[62:63] op_sel_hi:[0,1,1]
	v_cvt_f32_ubyte2_e32 v102, v82
	v_cvt_f32_ubyte3_e32 v103, v82
	v_pk_fma_f32 v[92:93], v[40:41], v[98:99], v[92:93] op_sel:[1,0,0]
	v_cvt_f32_ubyte0_e32 v104, v83
	v_cvt_f32_ubyte1_e32 v105, v83
	v_pk_fma_f32 v[90:91], v[40:41], v[102:103], v[90:91] op_sel:[1,0,0]
	v_cvt_f32_ubyte2_e32 v146, v83
	v_cvt_f32_ubyte3_e32 v147, v83
	v_pk_fma_f32 v[86:87], v[48:49], v[104:105], v[86:87] op_sel:[1,0,0]
	v_cvt_f32_ubyte0_e32 v98, v88
	v_cvt_f32_ubyte1_e32 v99, v88
	v_pk_fma_f32 v[84:85], v[48:49], v[146:147], v[84:85] op_sel:[1,0,0]
	v_cvt_f32_ubyte2_e32 v102, v88
	v_cvt_f32_ubyte3_e32 v103, v88
	v_pk_fma_f32 v[80:81], v[40:41], v[98:99], v[80:81] op_sel:[1,0,0]
	v_cvt_f32_ubyte0_e32 v104, v89
	v_cvt_f32_ubyte1_e32 v105, v89
	v_pk_fma_f32 v[78:79], v[40:41], v[102:103], v[78:79] op_sel:[1,0,0]
	v_cvt_f32_ubyte2_e32 v146, v89
	v_cvt_f32_ubyte3_e32 v147, v89
	v_pk_fma_f32 v[70:71], v[48:49], v[104:105], v[70:71] op_sel:[1,0,0]
	v_pk_fma_f32 v[62:63], v[48:49], v[146:147], v[62:63] op_sel:[1,0,0]
	s_waitcnt lgkmcnt(0)
	v_lshl_add_u32 v72, v72, 9, v100
	v_lshl_add_u32 v73, v73, 9, v100
	v_lshl_add_u32 v74, v74, 9, v100
	v_lshl_add_u32 v75, v75, 9, v100
	v_lshl_add_u32 v94, v94, 9, v100
	v_lshl_add_u32 v95, v95, 9, v100
	v_lshl_add_u32 v96, v96, 9, v100
	v_lshl_add_u32 v97, v97, 9, v100
	global_load_dwordx2 v[196:197], v72, s[38:39]
	global_load_dwordx2 v[198:199], v73, s[38:39]
	global_load_dwordx2 v[200:201], v74, s[38:39]
	global_load_dwordx2 v[202:203], v75, s[38:39]
	global_load_dwordx2 v[204:205], v94, s[38:39]
	global_load_dwordx2 v[206:207], v95, s[38:39]
	global_load_dwordx2 v[208:209], v96, s[38:39]
	global_load_dwordx2 v[210:211], v97, s[38:39]
	ds_read_b128 v[72:75], v1 offset:480
	ds_read_b128 v[94:97], v1 offset:496
	ds_read_b128 v[34:37], v1 offset:832
	ds_read_b128 v[38:41], v1 offset:848
	ds_read_b128 v[42:45], v1 offset:1856
	ds_read_b128 v[46:49], v1 offset:1872
	s_waitcnt vmcnt(40)
	v_and_b32_e32 v68, s0, v212
	v_and_b32_e32 v69, s1, v212
	v_and_b32_e32 v76, s0, v213
	v_and_b32_e32 v77, s1, v213
	v_cvt_f32_ubyte0_e32 v98, v68
	v_cvt_f32_ubyte1_e32 v99, v68
	v_cvt_f32_ubyte2_e32 v102, v68
	v_cvt_f32_ubyte3_e32 v103, v68
	v_pk_fma_f32 v[92:93], v[50:51], v[98:99], v[92:93] op_sel_hi:[0,1,1]
	v_cvt_f32_ubyte0_e32 v104, v69
	v_cvt_f32_ubyte1_e32 v105, v69
	v_pk_fma_f32 v[90:91], v[50:51], v[102:103], v[90:91] op_sel_hi:[0,1,1]
	v_cvt_f32_ubyte2_e32 v146, v69
	v_cvt_f32_ubyte3_e32 v147, v69
	v_pk_fma_f32 v[86:87], v[58:59], v[104:105], v[86:87] op_sel_hi:[0,1,1]
	v_cvt_f32_ubyte0_e32 v98, v76
	v_cvt_f32_ubyte1_e32 v99, v76
	v_pk_fma_f32 v[84:85], v[58:59], v[146:147], v[84:85] op_sel_hi:[0,1,1]
	v_and_b32_e32 v82, s0, v214
	v_and_b32_e32 v83, s1, v214
	v_and_b32_e32 v88, s0, v215
	v_and_b32_e32 v89, s1, v215
	v_cvt_f32_ubyte2_e32 v102, v76
	v_cvt_f32_ubyte3_e32 v103, v76
	v_pk_fma_f32 v[80:81], v[50:51], v[98:99], v[80:81] op_sel_hi:[0,1,1]
	v_cvt_f32_ubyte0_e32 v104, v77
	v_cvt_f32_ubyte1_e32 v105, v77
	v_pk_fma_f32 v[78:79], v[50:51], v[102:103], v[78:79] op_sel_hi:[0,1,1]
	v_cvt_f32_ubyte2_e32 v146, v77
	v_cvt_f32_ubyte3_e32 v147, v77
	v_pk_fma_f32 v[70:71], v[58:59], v[104:105], v[70:71] op_sel_hi:[0,1,1]
	v_cvt_f32_ubyte0_e32 v98, v82
	v_cvt_f32_ubyte1_e32 v99, v82
	v_pk_fma_f32 v[62:63], v[58:59], v[146:147], v[62:63] op_sel_hi:[0,1,1]
	v_cvt_f32_ubyte2_e32 v102, v82
	v_cvt_f32_ubyte3_e32 v103, v82
	v_pk_fma_f32 v[92:93], v[50:51], v[98:99], v[92:93] op_sel:[1,0,0]
	v_cvt_f32_ubyte0_e32 v104, v83
	v_cvt_f32_ubyte1_e32 v105, v83
	v_pk_fma_f32 v[90:91], v[50:51], v[102:103], v[90:91] op_sel:[1,0,0]
	v_cvt_f32_ubyte2_e32 v146, v83
	v_cvt_f32_ubyte3_e32 v147, v83
	v_pk_fma_f32 v[86:87], v[58:59], v[104:105], v[86:87] op_sel:[1,0,0]
	v_cvt_f32_ubyte0_e32 v98, v88
	v_cvt_f32_ubyte1_e32 v99, v88
	v_pk_fma_f32 v[84:85], v[58:59], v[146:147], v[84:85] op_sel:[1,0,0]
	v_and_b32_e32 v68, s0, v216
	v_and_b32_e32 v69, s1, v216
	v_and_b32_e32 v76, s0, v217
	v_and_b32_e32 v77, s1, v217
	v_cvt_f32_ubyte2_e32 v102, v88
	v_cvt_f32_ubyte3_e32 v103, v88
	v_pk_fma_f32 v[80:81], v[50:51], v[98:99], v[80:81] op_sel:[1,0,0]
	v_cvt_f32_ubyte0_e32 v104, v89
	v_cvt_f32_ubyte1_e32 v105, v89
	v_pk_fma_f32 v[78:79], v[50:51], v[102:103], v[78:79] op_sel:[1,0,0]
	v_cvt_f32_ubyte2_e32 v146, v89
	v_cvt_f32_ubyte3_e32 v147, v89
	v_pk_fma_f32 v[70:71], v[58:59], v[104:105], v[70:71] op_sel:[1,0,0]
	v_cvt_f32_ubyte0_e32 v98, v68
	v_cvt_f32_ubyte1_e32 v99, v68
	v_pk_fma_f32 v[62:63], v[58:59], v[146:147], v[62:63] op_sel:[1,0,0]
	v_cvt_f32_ubyte2_e32 v102, v68
	v_cvt_f32_ubyte3_e32 v103, v68
	v_pk_fma_f32 v[92:93], v[52:53], v[98:99], v[92:93] op_sel_hi:[0,1,1]
	v_cvt_f32_ubyte0_e32 v104, v69
	v_cvt_f32_ubyte1_e32 v105, v69
	v_pk_fma_f32 v[90:91], v[52:53], v[102:103], v[90:91] op_sel_hi:[0,1,1]
	v_cvt_f32_ubyte2_e32 v146, v69
	v_cvt_f32_ubyte3_e32 v147, v69
	v_pk_fma_f32 v[86:87], v[60:61], v[104:105], v[86:87] op_sel_hi:[0,1,1]
	v_cvt_f32_ubyte0_e32 v98, v76
	v_cvt_f32_ubyte1_e32 v99, v76
	v_pk_fma_f32 v[84:85], v[60:61], v[146:147], v[84:85] op_sel_hi:[0,1,1]
	v_and_b32_e32 v82, s0, v218
	v_and_b32_e32 v83, s1, v218
	v_and_b32_e32 v88, s0, v219
	v_and_b32_e32 v89, s1, v219
	v_cvt_f32_ubyte2_e32 v102, v76
	v_cvt_f32_ubyte3_e32 v103, v76
	v_pk_fma_f32 v[80:81], v[52:53], v[98:99], v[80:81] op_sel_hi:[0,1,1]
	v_cvt_f32_ubyte0_e32 v104, v77
	v_cvt_f32_ubyte1_e32 v105, v77
	v_pk_fma_f32 v[78:79], v[52:53], v[102:103], v[78:79] op_sel_hi:[0,1,1]
	v_cvt_f32_ubyte2_e32 v146, v77
	v_cvt_f32_ubyte3_e32 v147, v77
	v_pk_fma_f32 v[70:71], v[60:61], v[104:105], v[70:71] op_sel_hi:[0,1,1]
	v_cvt_f32_ubyte0_e32 v98, v82
	v_cvt_f32_ubyte1_e32 v99, v82
	v_pk_fma_f32 v[62:63], v[60:61], v[146:147], v[62:63] op_sel_hi:[0,1,1]
	v_cvt_f32_ubyte2_e32 v102, v82
	v_cvt_f32_ubyte3_e32 v103, v82
	v_pk_fma_f32 v[92:93], v[52:53], v[98:99], v[92:93] op_sel:[1,0,0]
	v_cvt_f32_ubyte0_e32 v104, v83
	v_cvt_f32_ubyte1_e32 v105, v83
	v_pk_fma_f32 v[90:91], v[52:53], v[102:103], v[90:91] op_sel:[1,0,0]
	v_cvt_f32_ubyte2_e32 v146, v83
	v_cvt_f32_ubyte3_e32 v147, v83
	v_pk_fma_f32 v[86:87], v[60:61], v[104:105], v[86:87] op_sel:[1,0,0]
	v_cvt_f32_ubyte0_e32 v98, v88
	v_cvt_f32_ubyte1_e32 v99, v88
	v_pk_fma_f32 v[84:85], v[60:61], v[146:147], v[84:85] op_sel:[1,0,0]
	v_and_b32_e32 v68, s0, v220
	v_and_b32_e32 v69, s1, v220
	v_and_b32_e32 v76, s0, v221
	v_and_b32_e32 v77, s1, v221
	v_cvt_f32_ubyte2_e32 v102, v88
	v_cvt_f32_ubyte3_e32 v103, v88
	v_pk_fma_f32 v[80:81], v[52:53], v[98:99], v[80:81] op_sel:[1,0,0]
	v_cvt_f32_ubyte0_e32 v104, v89
	v_cvt_f32_ubyte1_e32 v105, v89
	v_pk_fma_f32 v[78:79], v[52:53], v[102:103], v[78:79] op_sel:[1,0,0]
	v_cvt_f32_ubyte2_e32 v146, v89
	v_cvt_f32_ubyte3_e32 v147, v89
	v_pk_fma_f32 v[70:71], v[60:61], v[104:105], v[70:71] op_sel:[1,0,0]
	v_cvt_f32_ubyte0_e32 v98, v68
	v_cvt_f32_ubyte1_e32 v99, v68
	v_pk_fma_f32 v[62:63], v[60:61], v[146:147], v[62:63] op_sel:[1,0,0]
	v_cvt_f32_ubyte2_e32 v102, v68
	v_cvt_f32_ubyte3_e32 v103, v68
	v_pk_fma_f32 v[92:93], v[54:55], v[98:99], v[92:93] op_sel_hi:[0,1,1]
	v_cvt_f32_ubyte0_e32 v104, v69
	v_cvt_f32_ubyte1_e32 v105, v69
	v_pk_fma_f32 v[90:91], v[54:55], v[102:103], v[90:91] op_sel_hi:[0,1,1]
	v_cvt_f32_ubyte2_e32 v146, v69
	v_cvt_f32_ubyte3_e32 v147, v69
	v_pk_fma_f32 v[86:87], v[64:65], v[104:105], v[86:87] op_sel_hi:[0,1,1]
	v_cvt_f32_ubyte0_e32 v98, v76
	v_cvt_f32_ubyte1_e32 v99, v76
	v_pk_fma_f32 v[84:85], v[64:65], v[146:147], v[84:85] op_sel_hi:[0,1,1]
	v_and_b32_e32 v82, s0, v222
	v_and_b32_e32 v83, s1, v222
	v_and_b32_e32 v88, s0, v223
	v_and_b32_e32 v89, s1, v223
	v_cvt_f32_ubyte2_e32 v102, v76
	v_cvt_f32_ubyte3_e32 v103, v76
	v_pk_fma_f32 v[80:81], v[54:55], v[98:99], v[80:81] op_sel_hi:[0,1,1]
	v_cvt_f32_ubyte0_e32 v104, v77
	v_cvt_f32_ubyte1_e32 v105, v77
	v_pk_fma_f32 v[78:79], v[54:55], v[102:103], v[78:79] op_sel_hi:[0,1,1]
	v_cvt_f32_ubyte2_e32 v146, v77
	v_cvt_f32_ubyte3_e32 v147, v77
	v_pk_fma_f32 v[70:71], v[64:65], v[104:105], v[70:71] op_sel_hi:[0,1,1]
	v_cvt_f32_ubyte0_e32 v98, v82
	v_cvt_f32_ubyte1_e32 v99, v82
	v_pk_fma_f32 v[62:63], v[64:65], v[146:147], v[62:63] op_sel_hi:[0,1,1]
	v_cvt_f32_ubyte2_e32 v102, v82
	v_cvt_f32_ubyte3_e32 v103, v82
	v_pk_fma_f32 v[92:93], v[54:55], v[98:99], v[92:93] op_sel:[1,0,0]
	v_cvt_f32_ubyte0_e32 v104, v83
	v_cvt_f32_ubyte1_e32 v105, v83
	v_pk_fma_f32 v[90:91], v[54:55], v[102:103], v[90:91] op_sel:[1,0,0]
	v_cvt_f32_ubyte2_e32 v146, v83
	v_cvt_f32_ubyte3_e32 v147, v83
	v_pk_fma_f32 v[86:87], v[64:65], v[104:105], v[86:87] op_sel:[1,0,0]
	v_cvt_f32_ubyte0_e32 v98, v88
	v_cvt_f32_ubyte1_e32 v99, v88
	v_pk_fma_f32 v[84:85], v[64:65], v[146:147], v[84:85] op_sel:[1,0,0]
	v_and_b32_e32 v68, s0, v224
	v_and_b32_e32 v69, s1, v224
	v_and_b32_e32 v76, s0, v225
	v_and_b32_e32 v77, s1, v225
	v_cvt_f32_ubyte2_e32 v102, v88
	v_cvt_f32_ubyte3_e32 v103, v88
	v_pk_fma_f32 v[80:81], v[54:55], v[98:99], v[80:81] op_sel:[1,0,0]
	v_cvt_f32_ubyte0_e32 v104, v89
	v_cvt_f32_ubyte1_e32 v105, v89
	v_pk_fma_f32 v[78:79], v[54:55], v[102:103], v[78:79] op_sel:[1,0,0]
	v_cvt_f32_ubyte2_e32 v146, v89
	v_cvt_f32_ubyte3_e32 v147, v89
	v_pk_fma_f32 v[70:71], v[64:65], v[104:105], v[70:71] op_sel:[1,0,0]
	v_cvt_f32_ubyte0_e32 v98, v68
	v_cvt_f32_ubyte1_e32 v99, v68
	v_pk_fma_f32 v[62:63], v[64:65], v[146:147], v[62:63] op_sel:[1,0,0]
	v_cvt_f32_ubyte2_e32 v102, v68
	v_cvt_f32_ubyte3_e32 v103, v68
	v_pk_fma_f32 v[92:93], v[56:57], v[98:99], v[92:93] op_sel_hi:[0,1,1]
	v_cvt_f32_ubyte0_e32 v104, v69
	v_cvt_f32_ubyte1_e32 v105, v69
	v_pk_fma_f32 v[90:91], v[56:57], v[102:103], v[90:91] op_sel_hi:[0,1,1]
	v_cvt_f32_ubyte2_e32 v146, v69
	v_cvt_f32_ubyte3_e32 v147, v69
	v_pk_fma_f32 v[86:87], v[66:67], v[104:105], v[86:87] op_sel_hi:[0,1,1]
	v_cvt_f32_ubyte0_e32 v98, v76
	v_cvt_f32_ubyte1_e32 v99, v76
	v_pk_fma_f32 v[84:85], v[66:67], v[146:147], v[84:85] op_sel_hi:[0,1,1]
	v_and_b32_e32 v82, s0, v226
	v_and_b32_e32 v83, s1, v226
	v_and_b32_e32 v88, s0, v227
	v_and_b32_e32 v89, s1, v227
	v_cvt_f32_ubyte2_e32 v102, v76
	v_cvt_f32_ubyte3_e32 v103, v76
	v_pk_fma_f32 v[80:81], v[56:57], v[98:99], v[80:81] op_sel_hi:[0,1,1]
	v_cvt_f32_ubyte0_e32 v104, v77
	v_cvt_f32_ubyte1_e32 v105, v77
	v_pk_fma_f32 v[78:79], v[56:57], v[102:103], v[78:79] op_sel_hi:[0,1,1]
	v_cvt_f32_ubyte2_e32 v146, v77
	v_cvt_f32_ubyte3_e32 v147, v77
	v_pk_fma_f32 v[70:71], v[66:67], v[104:105], v[70:71] op_sel_hi:[0,1,1]
	v_cvt_f32_ubyte0_e32 v98, v82
	v_cvt_f32_ubyte1_e32 v99, v82
	v_pk_fma_f32 v[62:63], v[66:67], v[146:147], v[62:63] op_sel_hi:[0,1,1]
	v_cvt_f32_ubyte2_e32 v102, v82
	v_cvt_f32_ubyte3_e32 v103, v82
	v_pk_fma_f32 v[92:93], v[56:57], v[98:99], v[92:93] op_sel:[1,0,0]
	v_cvt_f32_ubyte0_e32 v104, v83
	v_cvt_f32_ubyte1_e32 v105, v83
	v_pk_fma_f32 v[90:91], v[56:57], v[102:103], v[90:91] op_sel:[1,0,0]
	v_cvt_f32_ubyte2_e32 v146, v83
	v_cvt_f32_ubyte3_e32 v147, v83
	v_pk_fma_f32 v[86:87], v[66:67], v[104:105], v[86:87] op_sel:[1,0,0]
	v_cvt_f32_ubyte0_e32 v98, v88
	v_cvt_f32_ubyte1_e32 v99, v88
	v_pk_fma_f32 v[84:85], v[66:67], v[146:147], v[84:85] op_sel:[1,0,0]
	v_cvt_f32_ubyte2_e32 v102, v88
	v_cvt_f32_ubyte3_e32 v103, v88
	v_pk_fma_f32 v[80:81], v[56:57], v[98:99], v[80:81] op_sel:[1,0,0]
	v_cvt_f32_ubyte0_e32 v104, v89
	v_cvt_f32_ubyte1_e32 v105, v89
	v_pk_fma_f32 v[78:79], v[56:57], v[102:103], v[78:79] op_sel:[1,0,0]
	v_cvt_f32_ubyte2_e32 v146, v89
	v_cvt_f32_ubyte3_e32 v147, v89
	v_pk_fma_f32 v[70:71], v[66:67], v[104:105], v[70:71] op_sel:[1,0,0]
	v_pk_fma_f32 v[62:63], v[66:67], v[146:147], v[62:63] op_sel:[1,0,0]
	s_waitcnt lgkmcnt(0)
	v_lshl_add_u32 v72, v72, 9, v100
	v_lshl_add_u32 v73, v73, 9, v100
	v_lshl_add_u32 v74, v74, 9, v100
	v_lshl_add_u32 v75, v75, 9, v100
	v_lshl_add_u32 v94, v94, 9, v100
	v_lshl_add_u32 v95, v95, 9, v100
	v_lshl_add_u32 v96, v96, 9, v100
	v_lshl_add_u32 v97, v97, 9, v100
	global_load_dwordx2 v[212:213], v72, s[38:39]
	global_load_dwordx2 v[214:215], v73, s[38:39]
	global_load_dwordx2 v[216:217], v74, s[38:39]
	global_load_dwordx2 v[218:219], v75, s[38:39]
	global_load_dwordx2 v[220:221], v94, s[38:39]
	global_load_dwordx2 v[222:223], v95, s[38:39]
	global_load_dwordx2 v[224:225], v96, s[38:39]
	global_load_dwordx2 v[226:227], v97, s[38:39]
	ds_read_b128 v[50:53], v1 offset:864
	ds_read_b128 v[54:57], v1 offset:880
	ds_read_b128 v[58:61], v1 offset:1888
	ds_read_b128 v[64:67], v1 offset:1904
	s_waitcnt vmcnt(40)
	v_and_b32_e32 v68, s0, v2
	v_and_b32_e32 v69, s1, v2
	v_and_b32_e32 v76, s0, v3
	v_and_b32_e32 v77, s1, v3
	v_cvt_f32_ubyte0_e32 v98, v68
	v_cvt_f32_ubyte1_e32 v99, v68
	v_cvt_f32_ubyte2_e32 v102, v68
	v_cvt_f32_ubyte3_e32 v103, v68
	v_pk_fma_f32 v[92:93], v[34:35], v[98:99], v[92:93] op_sel_hi:[0,1,1]
	v_cvt_f32_ubyte0_e32 v104, v69
	v_cvt_f32_ubyte1_e32 v105, v69
	v_pk_fma_f32 v[90:91], v[34:35], v[102:103], v[90:91] op_sel_hi:[0,1,1]
	v_cvt_f32_ubyte2_e32 v146, v69
	v_cvt_f32_ubyte3_e32 v147, v69
	v_pk_fma_f32 v[86:87], v[42:43], v[104:105], v[86:87] op_sel_hi:[0,1,1]
	v_cvt_f32_ubyte0_e32 v98, v76
	v_cvt_f32_ubyte1_e32 v99, v76
	v_pk_fma_f32 v[84:85], v[42:43], v[146:147], v[84:85] op_sel_hi:[0,1,1]
	v_and_b32_e32 v82, s0, v4
	v_and_b32_e32 v83, s1, v4
	v_and_b32_e32 v88, s0, v5
	v_and_b32_e32 v89, s1, v5
	v_cvt_f32_ubyte2_e32 v102, v76
	v_cvt_f32_ubyte3_e32 v103, v76
	v_pk_fma_f32 v[80:81], v[34:35], v[98:99], v[80:81] op_sel_hi:[0,1,1]
	v_cvt_f32_ubyte0_e32 v104, v77
	v_cvt_f32_ubyte1_e32 v105, v77
	v_pk_fma_f32 v[78:79], v[34:35], v[102:103], v[78:79] op_sel_hi:[0,1,1]
	v_cvt_f32_ubyte2_e32 v146, v77
	v_cvt_f32_ubyte3_e32 v147, v77
	v_pk_fma_f32 v[70:71], v[42:43], v[104:105], v[70:71] op_sel_hi:[0,1,1]
	v_cvt_f32_ubyte0_e32 v98, v82
	v_cvt_f32_ubyte1_e32 v99, v82
	v_pk_fma_f32 v[62:63], v[42:43], v[146:147], v[62:63] op_sel_hi:[0,1,1]
	v_cvt_f32_ubyte2_e32 v102, v82
	v_cvt_f32_ubyte3_e32 v103, v82
	v_pk_fma_f32 v[92:93], v[34:35], v[98:99], v[92:93] op_sel:[1,0,0]
	v_cvt_f32_ubyte0_e32 v104, v83
	v_cvt_f32_ubyte1_e32 v105, v83
	v_pk_fma_f32 v[90:91], v[34:35], v[102:103], v[90:91] op_sel:[1,0,0]
	v_cvt_f32_ubyte2_e32 v146, v83
	v_cvt_f32_ubyte3_e32 v147, v83
	v_pk_fma_f32 v[86:87], v[42:43], v[104:105], v[86:87] op_sel:[1,0,0]
	v_cvt_f32_ubyte0_e32 v98, v88
	v_cvt_f32_ubyte1_e32 v99, v88
	v_pk_fma_f32 v[84:85], v[42:43], v[146:147], v[84:85] op_sel:[1,0,0]
	v_and_b32_e32 v68, s0, v6
	v_and_b32_e32 v69, s1, v6
	v_and_b32_e32 v76, s0, v7
	v_and_b32_e32 v77, s1, v7
	v_cvt_f32_ubyte2_e32 v102, v88
	v_cvt_f32_ubyte3_e32 v103, v88
	v_pk_fma_f32 v[80:81], v[34:35], v[98:99], v[80:81] op_sel:[1,0,0]
	v_cvt_f32_ubyte0_e32 v104, v89
	v_cvt_f32_ubyte1_e32 v105, v89
	v_pk_fma_f32 v[78:79], v[34:35], v[102:103], v[78:79] op_sel:[1,0,0]
	v_cvt_f32_ubyte2_e32 v146, v89
	v_cvt_f32_ubyte3_e32 v147, v89
	v_pk_fma_f32 v[70:71], v[42:43], v[104:105], v[70:71] op_sel:[1,0,0]
	v_cvt_f32_ubyte0_e32 v98, v68
	v_cvt_f32_ubyte1_e32 v99, v68
	v_pk_fma_f32 v[62:63], v[42:43], v[146:147], v[62:63] op_sel:[1,0,0]
	v_cvt_f32_ubyte2_e32 v102, v68
	v_cvt_f32_ubyte3_e32 v103, v68
	v_pk_fma_f32 v[92:93], v[36:37], v[98:99], v[92:93] op_sel_hi:[0,1,1]
	v_cvt_f32_ubyte0_e32 v104, v69
	v_cvt_f32_ubyte1_e32 v105, v69
	v_pk_fma_f32 v[90:91], v[36:37], v[102:103], v[90:91] op_sel_hi:[0,1,1]
	v_cvt_f32_ubyte2_e32 v146, v69
	v_cvt_f32_ubyte3_e32 v147, v69
	v_pk_fma_f32 v[86:87], v[44:45], v[104:105], v[86:87] op_sel_hi:[0,1,1]
	v_cvt_f32_ubyte0_e32 v98, v76
	v_cvt_f32_ubyte1_e32 v99, v76
	v_pk_fma_f32 v[84:85], v[44:45], v[146:147], v[84:85] op_sel_hi:[0,1,1]
	v_and_b32_e32 v82, s0, v8
	v_and_b32_e32 v83, s1, v8
	v_and_b32_e32 v88, s0, v9
	v_and_b32_e32 v89, s1, v9
	v_cvt_f32_ubyte2_e32 v102, v76
	v_cvt_f32_ubyte3_e32 v103, v76
	v_pk_fma_f32 v[80:81], v[36:37], v[98:99], v[80:81] op_sel_hi:[0,1,1]
	v_cvt_f32_ubyte0_e32 v104, v77
	v_cvt_f32_ubyte1_e32 v105, v77
	v_pk_fma_f32 v[78:79], v[36:37], v[102:103], v[78:79] op_sel_hi:[0,1,1]
	v_cvt_f32_ubyte2_e32 v146, v77
	v_cvt_f32_ubyte3_e32 v147, v77
	v_pk_fma_f32 v[70:71], v[44:45], v[104:105], v[70:71] op_sel_hi:[0,1,1]
	v_cvt_f32_ubyte0_e32 v98, v82
	v_cvt_f32_ubyte1_e32 v99, v82
	v_pk_fma_f32 v[62:63], v[44:45], v[146:147], v[62:63] op_sel_hi:[0,1,1]
	v_cvt_f32_ubyte2_e32 v102, v82
	v_cvt_f32_ubyte3_e32 v103, v82
	v_pk_fma_f32 v[92:93], v[36:37], v[98:99], v[92:93] op_sel:[1,0,0]
	v_cvt_f32_ubyte0_e32 v104, v83
	v_cvt_f32_ubyte1_e32 v105, v83
	v_pk_fma_f32 v[90:91], v[36:37], v[102:103], v[90:91] op_sel:[1,0,0]
	v_cvt_f32_ubyte2_e32 v146, v83
	v_cvt_f32_ubyte3_e32 v147, v83
	v_pk_fma_f32 v[86:87], v[44:45], v[104:105], v[86:87] op_sel:[1,0,0]
	v_cvt_f32_ubyte0_e32 v98, v88
	v_cvt_f32_ubyte1_e32 v99, v88
	v_pk_fma_f32 v[84:85], v[44:45], v[146:147], v[84:85] op_sel:[1,0,0]
	v_and_b32_e32 v68, s0, v10
	v_and_b32_e32 v69, s1, v10
	v_and_b32_e32 v76, s0, v11
	v_and_b32_e32 v77, s1, v11
	v_cvt_f32_ubyte2_e32 v102, v88
	v_cvt_f32_ubyte3_e32 v103, v88
	v_pk_fma_f32 v[80:81], v[36:37], v[98:99], v[80:81] op_sel:[1,0,0]
	v_cvt_f32_ubyte0_e32 v104, v89
	v_cvt_f32_ubyte1_e32 v105, v89
	v_pk_fma_f32 v[78:79], v[36:37], v[102:103], v[78:79] op_sel:[1,0,0]
	v_cvt_f32_ubyte2_e32 v146, v89
	v_cvt_f32_ubyte3_e32 v147, v89
	v_pk_fma_f32 v[70:71], v[44:45], v[104:105], v[70:71] op_sel:[1,0,0]
	v_cvt_f32_ubyte0_e32 v98, v68
	v_cvt_f32_ubyte1_e32 v99, v68
	v_pk_fma_f32 v[62:63], v[44:45], v[146:147], v[62:63] op_sel:[1,0,0]
	v_cvt_f32_ubyte2_e32 v102, v68
	v_cvt_f32_ubyte3_e32 v103, v68
	v_pk_fma_f32 v[92:93], v[38:39], v[98:99], v[92:93] op_sel_hi:[0,1,1]
	v_cvt_f32_ubyte0_e32 v104, v69
	v_cvt_f32_ubyte1_e32 v105, v69
	v_pk_fma_f32 v[90:91], v[38:39], v[102:103], v[90:91] op_sel_hi:[0,1,1]
	v_cvt_f32_ubyte2_e32 v146, v69
	v_cvt_f32_ubyte3_e32 v147, v69
	v_pk_fma_f32 v[86:87], v[46:47], v[104:105], v[86:87] op_sel_hi:[0,1,1]
	v_cvt_f32_ubyte0_e32 v98, v76
	v_cvt_f32_ubyte1_e32 v99, v76
	v_pk_fma_f32 v[84:85], v[46:47], v[146:147], v[84:85] op_sel_hi:[0,1,1]
	v_and_b32_e32 v82, s0, v12
	v_and_b32_e32 v83, s1, v12
	v_and_b32_e32 v88, s0, v13
	v_and_b32_e32 v89, s1, v13
	v_cvt_f32_ubyte2_e32 v102, v76
	v_cvt_f32_ubyte3_e32 v103, v76
	v_pk_fma_f32 v[80:81], v[38:39], v[98:99], v[80:81] op_sel_hi:[0,1,1]
	v_cvt_f32_ubyte0_e32 v104, v77
	v_cvt_f32_ubyte1_e32 v105, v77
	v_pk_fma_f32 v[78:79], v[38:39], v[102:103], v[78:79] op_sel_hi:[0,1,1]
	v_cvt_f32_ubyte2_e32 v146, v77
	v_cvt_f32_ubyte3_e32 v147, v77
	v_pk_fma_f32 v[70:71], v[46:47], v[104:105], v[70:71] op_sel_hi:[0,1,1]
	v_cvt_f32_ubyte0_e32 v98, v82
	v_cvt_f32_ubyte1_e32 v99, v82
	v_pk_fma_f32 v[62:63], v[46:47], v[146:147], v[62:63] op_sel_hi:[0,1,1]
	v_cvt_f32_ubyte2_e32 v102, v82
	v_cvt_f32_ubyte3_e32 v103, v82
	v_pk_fma_f32 v[92:93], v[38:39], v[98:99], v[92:93] op_sel:[1,0,0]
	v_cvt_f32_ubyte0_e32 v104, v83
	v_cvt_f32_ubyte1_e32 v105, v83
	v_pk_fma_f32 v[90:91], v[38:39], v[102:103], v[90:91] op_sel:[1,0,0]
	v_cvt_f32_ubyte2_e32 v146, v83
	v_cvt_f32_ubyte3_e32 v147, v83
	v_pk_fma_f32 v[86:87], v[46:47], v[104:105], v[86:87] op_sel:[1,0,0]
	v_cvt_f32_ubyte0_e32 v98, v88
	v_cvt_f32_ubyte1_e32 v99, v88
	v_pk_fma_f32 v[84:85], v[46:47], v[146:147], v[84:85] op_sel:[1,0,0]
	v_and_b32_e32 v68, s0, v14
	v_and_b32_e32 v69, s1, v14
	v_and_b32_e32 v76, s0, v15
	v_and_b32_e32 v77, s1, v15
	v_cvt_f32_ubyte2_e32 v102, v88
	v_cvt_f32_ubyte3_e32 v103, v88
	v_pk_fma_f32 v[80:81], v[38:39], v[98:99], v[80:81] op_sel:[1,0,0]
	v_cvt_f32_ubyte0_e32 v104, v89
	v_cvt_f32_ubyte1_e32 v105, v89
	v_pk_fma_f32 v[78:79], v[38:39], v[102:103], v[78:79] op_sel:[1,0,0]
	v_cvt_f32_ubyte2_e32 v146, v89
	v_cvt_f32_ubyte3_e32 v147, v89
	v_pk_fma_f32 v[70:71], v[46:47], v[104:105], v[70:71] op_sel:[1,0,0]
	v_cvt_f32_ubyte0_e32 v98, v68
	v_cvt_f32_ubyte1_e32 v99, v68
	v_pk_fma_f32 v[62:63], v[46:47], v[146:147], v[62:63] op_sel:[1,0,0]
	v_cvt_f32_ubyte2_e32 v102, v68
	v_cvt_f32_ubyte3_e32 v103, v68
	v_pk_fma_f32 v[92:93], v[40:41], v[98:99], v[92:93] op_sel_hi:[0,1,1]
	v_cvt_f32_ubyte0_e32 v104, v69
	v_cvt_f32_ubyte1_e32 v105, v69
	v_pk_fma_f32 v[90:91], v[40:41], v[102:103], v[90:91] op_sel_hi:[0,1,1]
	v_cvt_f32_ubyte2_e32 v146, v69
	v_cvt_f32_ubyte3_e32 v147, v69
	v_pk_fma_f32 v[86:87], v[48:49], v[104:105], v[86:87] op_sel_hi:[0,1,1]
	v_cvt_f32_ubyte0_e32 v98, v76
	v_cvt_f32_ubyte1_e32 v99, v76
	v_pk_fma_f32 v[84:85], v[48:49], v[146:147], v[84:85] op_sel_hi:[0,1,1]
	v_and_b32_e32 v82, s0, v16
	v_and_b32_e32 v83, s1, v16
	v_and_b32_e32 v88, s0, v17
	v_and_b32_e32 v89, s1, v17
	v_cvt_f32_ubyte2_e32 v102, v76
	v_cvt_f32_ubyte3_e32 v103, v76
	v_pk_fma_f32 v[80:81], v[40:41], v[98:99], v[80:81] op_sel_hi:[0,1,1]
	v_cvt_f32_ubyte0_e32 v104, v77
	v_cvt_f32_ubyte1_e32 v105, v77
	v_pk_fma_f32 v[78:79], v[40:41], v[102:103], v[78:79] op_sel_hi:[0,1,1]
	v_cvt_f32_ubyte2_e32 v146, v77
	v_cvt_f32_ubyte3_e32 v147, v77
	v_pk_fma_f32 v[70:71], v[48:49], v[104:105], v[70:71] op_sel_hi:[0,1,1]
	v_cvt_f32_ubyte0_e32 v98, v82
	v_cvt_f32_ubyte1_e32 v99, v82
	v_pk_fma_f32 v[62:63], v[48:49], v[146:147], v[62:63] op_sel_hi:[0,1,1]
	v_cvt_f32_ubyte2_e32 v102, v82
	v_cvt_f32_ubyte3_e32 v103, v82
	v_pk_fma_f32 v[92:93], v[40:41], v[98:99], v[92:93] op_sel:[1,0,0]
	v_cvt_f32_ubyte0_e32 v104, v83
	v_cvt_f32_ubyte1_e32 v105, v83
	v_pk_fma_f32 v[90:91], v[40:41], v[102:103], v[90:91] op_sel:[1,0,0]
	v_cvt_f32_ubyte2_e32 v146, v83
	v_cvt_f32_ubyte3_e32 v147, v83
	v_pk_fma_f32 v[86:87], v[48:49], v[104:105], v[86:87] op_sel:[1,0,0]
	v_cvt_f32_ubyte0_e32 v98, v88
	v_cvt_f32_ubyte1_e32 v99, v88
	v_pk_fma_f32 v[84:85], v[48:49], v[146:147], v[84:85] op_sel:[1,0,0]
	v_cvt_f32_ubyte2_e32 v102, v88
	v_cvt_f32_ubyte3_e32 v103, v88
	v_pk_fma_f32 v[80:81], v[40:41], v[98:99], v[80:81] op_sel:[1,0,0]
	v_cvt_f32_ubyte0_e32 v104, v89
	v_cvt_f32_ubyte1_e32 v105, v89
	v_pk_fma_f32 v[78:79], v[40:41], v[102:103], v[78:79] op_sel:[1,0,0]
	v_cvt_f32_ubyte2_e32 v146, v89
	v_cvt_f32_ubyte3_e32 v147, v89
	v_pk_fma_f32 v[70:71], v[48:49], v[104:105], v[70:71] op_sel:[1,0,0]
	v_pk_fma_f32 v[62:63], v[48:49], v[146:147], v[62:63] op_sel:[1,0,0]
	s_waitcnt lgkmcnt(0)
	ds_read_b128 v[34:37], v1 offset:896
	ds_read_b128 v[38:41], v1 offset:912
	ds_read_b128 v[42:45], v1 offset:1920
	ds_read_b128 v[46:49], v1 offset:1936
	s_waitcnt vmcnt(32)
	v_and_b32_e32 v68, s0, v18
	v_and_b32_e32 v69, s1, v18
	v_and_b32_e32 v76, s0, v19
	v_and_b32_e32 v77, s1, v19
	v_cvt_f32_ubyte0_e32 v98, v68
	v_cvt_f32_ubyte1_e32 v99, v68
	v_cvt_f32_ubyte2_e32 v102, v68
	v_cvt_f32_ubyte3_e32 v103, v68
	v_pk_fma_f32 v[92:93], v[50:51], v[98:99], v[92:93] op_sel_hi:[0,1,1]
	v_cvt_f32_ubyte0_e32 v104, v69
	v_cvt_f32_ubyte1_e32 v105, v69
	v_pk_fma_f32 v[90:91], v[50:51], v[102:103], v[90:91] op_sel_hi:[0,1,1]
	v_cvt_f32_ubyte2_e32 v146, v69
	v_cvt_f32_ubyte3_e32 v147, v69
	v_pk_fma_f32 v[86:87], v[58:59], v[104:105], v[86:87] op_sel_hi:[0,1,1]
	v_cvt_f32_ubyte0_e32 v98, v76
	v_cvt_f32_ubyte1_e32 v99, v76
	v_pk_fma_f32 v[84:85], v[58:59], v[146:147], v[84:85] op_sel_hi:[0,1,1]
	v_and_b32_e32 v82, s0, v20
	v_and_b32_e32 v83, s1, v20
	v_and_b32_e32 v88, s0, v21
	v_and_b32_e32 v89, s1, v21
	v_cvt_f32_ubyte2_e32 v102, v76
	v_cvt_f32_ubyte3_e32 v103, v76
	v_pk_fma_f32 v[80:81], v[50:51], v[98:99], v[80:81] op_sel_hi:[0,1,1]
	v_cvt_f32_ubyte0_e32 v104, v77
	v_cvt_f32_ubyte1_e32 v105, v77
	v_pk_fma_f32 v[78:79], v[50:51], v[102:103], v[78:79] op_sel_hi:[0,1,1]
	v_cvt_f32_ubyte2_e32 v146, v77
	v_cvt_f32_ubyte3_e32 v147, v77
	v_pk_fma_f32 v[70:71], v[58:59], v[104:105], v[70:71] op_sel_hi:[0,1,1]
	v_cvt_f32_ubyte0_e32 v98, v82
	v_cvt_f32_ubyte1_e32 v99, v82
	v_pk_fma_f32 v[62:63], v[58:59], v[146:147], v[62:63] op_sel_hi:[0,1,1]
	v_cvt_f32_ubyte2_e32 v102, v82
	v_cvt_f32_ubyte3_e32 v103, v82
	v_pk_fma_f32 v[92:93], v[50:51], v[98:99], v[92:93] op_sel:[1,0,0]
	v_cvt_f32_ubyte0_e32 v104, v83
	v_cvt_f32_ubyte1_e32 v105, v83
	v_pk_fma_f32 v[90:91], v[50:51], v[102:103], v[90:91] op_sel:[1,0,0]
	v_cvt_f32_ubyte2_e32 v146, v83
	v_cvt_f32_ubyte3_e32 v147, v83
	v_pk_fma_f32 v[86:87], v[58:59], v[104:105], v[86:87] op_sel:[1,0,0]
	v_cvt_f32_ubyte0_e32 v98, v88
	v_cvt_f32_ubyte1_e32 v99, v88
	v_pk_fma_f32 v[84:85], v[58:59], v[146:147], v[84:85] op_sel:[1,0,0]
	v_and_b32_e32 v68, s0, v22
	v_and_b32_e32 v69, s1, v22
	v_and_b32_e32 v76, s0, v23
	v_and_b32_e32 v77, s1, v23
	v_cvt_f32_ubyte2_e32 v102, v88
	v_cvt_f32_ubyte3_e32 v103, v88
	v_pk_fma_f32 v[80:81], v[50:51], v[98:99], v[80:81] op_sel:[1,0,0]
	v_cvt_f32_ubyte0_e32 v104, v89
	v_cvt_f32_ubyte1_e32 v105, v89
	v_pk_fma_f32 v[78:79], v[50:51], v[102:103], v[78:79] op_sel:[1,0,0]
	v_cvt_f32_ubyte2_e32 v146, v89
	v_cvt_f32_ubyte3_e32 v147, v89
	v_pk_fma_f32 v[70:71], v[58:59], v[104:105], v[70:71] op_sel:[1,0,0]
	v_cvt_f32_ubyte0_e32 v98, v68
	v_cvt_f32_ubyte1_e32 v99, v68
	v_pk_fma_f32 v[62:63], v[58:59], v[146:147], v[62:63] op_sel:[1,0,0]
	v_cvt_f32_ubyte2_e32 v102, v68
	v_cvt_f32_ubyte3_e32 v103, v68
	v_pk_fma_f32 v[92:93], v[52:53], v[98:99], v[92:93] op_sel_hi:[0,1,1]
	v_cvt_f32_ubyte0_e32 v104, v69
	v_cvt_f32_ubyte1_e32 v105, v69
	v_pk_fma_f32 v[90:91], v[52:53], v[102:103], v[90:91] op_sel_hi:[0,1,1]
	v_cvt_f32_ubyte2_e32 v146, v69
	v_cvt_f32_ubyte3_e32 v147, v69
	v_pk_fma_f32 v[86:87], v[60:61], v[104:105], v[86:87] op_sel_hi:[0,1,1]
	v_cvt_f32_ubyte0_e32 v98, v76
	v_cvt_f32_ubyte1_e32 v99, v76
	v_pk_fma_f32 v[84:85], v[60:61], v[146:147], v[84:85] op_sel_hi:[0,1,1]
	v_and_b32_e32 v82, s0, v24
	v_and_b32_e32 v83, s1, v24
	v_and_b32_e32 v88, s0, v25
	v_and_b32_e32 v89, s1, v25
	v_cvt_f32_ubyte2_e32 v102, v76
	v_cvt_f32_ubyte3_e32 v103, v76
	v_pk_fma_f32 v[80:81], v[52:53], v[98:99], v[80:81] op_sel_hi:[0,1,1]
	v_cvt_f32_ubyte0_e32 v104, v77
	v_cvt_f32_ubyte1_e32 v105, v77
	v_pk_fma_f32 v[78:79], v[52:53], v[102:103], v[78:79] op_sel_hi:[0,1,1]
	v_cvt_f32_ubyte2_e32 v146, v77
	v_cvt_f32_ubyte3_e32 v147, v77
	v_pk_fma_f32 v[70:71], v[60:61], v[104:105], v[70:71] op_sel_hi:[0,1,1]
	v_cvt_f32_ubyte0_e32 v98, v82
	v_cvt_f32_ubyte1_e32 v99, v82
	v_pk_fma_f32 v[62:63], v[60:61], v[146:147], v[62:63] op_sel_hi:[0,1,1]
	v_cvt_f32_ubyte2_e32 v102, v82
	v_cvt_f32_ubyte3_e32 v103, v82
	v_pk_fma_f32 v[92:93], v[52:53], v[98:99], v[92:93] op_sel:[1,0,0]
	v_cvt_f32_ubyte0_e32 v104, v83
	v_cvt_f32_ubyte1_e32 v105, v83
	v_pk_fma_f32 v[90:91], v[52:53], v[102:103], v[90:91] op_sel:[1,0,0]
	v_cvt_f32_ubyte2_e32 v146, v83
	v_cvt_f32_ubyte3_e32 v147, v83
	v_pk_fma_f32 v[86:87], v[60:61], v[104:105], v[86:87] op_sel:[1,0,0]
	v_cvt_f32_ubyte0_e32 v98, v88
	v_cvt_f32_ubyte1_e32 v99, v88
	v_pk_fma_f32 v[84:85], v[60:61], v[146:147], v[84:85] op_sel:[1,0,0]
	v_and_b32_e32 v68, s0, v26
	v_and_b32_e32 v69, s1, v26
	v_and_b32_e32 v76, s0, v27
	v_and_b32_e32 v77, s1, v27
	v_cvt_f32_ubyte2_e32 v102, v88
	v_cvt_f32_ubyte3_e32 v103, v88
	v_pk_fma_f32 v[80:81], v[52:53], v[98:99], v[80:81] op_sel:[1,0,0]
	v_cvt_f32_ubyte0_e32 v104, v89
	v_cvt_f32_ubyte1_e32 v105, v89
	v_pk_fma_f32 v[78:79], v[52:53], v[102:103], v[78:79] op_sel:[1,0,0]
	v_cvt_f32_ubyte2_e32 v146, v89
	v_cvt_f32_ubyte3_e32 v147, v89
	v_pk_fma_f32 v[70:71], v[60:61], v[104:105], v[70:71] op_sel:[1,0,0]
	v_cvt_f32_ubyte0_e32 v98, v68
	v_cvt_f32_ubyte1_e32 v99, v68
	v_pk_fma_f32 v[62:63], v[60:61], v[146:147], v[62:63] op_sel:[1,0,0]
	v_cvt_f32_ubyte2_e32 v102, v68
	v_cvt_f32_ubyte3_e32 v103, v68
	v_pk_fma_f32 v[92:93], v[54:55], v[98:99], v[92:93] op_sel_hi:[0,1,1]
	v_cvt_f32_ubyte0_e32 v104, v69
	v_cvt_f32_ubyte1_e32 v105, v69
	v_pk_fma_f32 v[90:91], v[54:55], v[102:103], v[90:91] op_sel_hi:[0,1,1]
	v_cvt_f32_ubyte2_e32 v146, v69
	v_cvt_f32_ubyte3_e32 v147, v69
	v_pk_fma_f32 v[86:87], v[64:65], v[104:105], v[86:87] op_sel_hi:[0,1,1]
	v_cvt_f32_ubyte0_e32 v98, v76
	v_cvt_f32_ubyte1_e32 v99, v76
	v_pk_fma_f32 v[84:85], v[64:65], v[146:147], v[84:85] op_sel_hi:[0,1,1]
	v_and_b32_e32 v82, s0, v28
	v_and_b32_e32 v83, s1, v28
	v_and_b32_e32 v88, s0, v29
	v_and_b32_e32 v89, s1, v29
	v_cvt_f32_ubyte2_e32 v102, v76
	v_cvt_f32_ubyte3_e32 v103, v76
	v_pk_fma_f32 v[80:81], v[54:55], v[98:99], v[80:81] op_sel_hi:[0,1,1]
	v_cvt_f32_ubyte0_e32 v104, v77
	v_cvt_f32_ubyte1_e32 v105, v77
	v_pk_fma_f32 v[78:79], v[54:55], v[102:103], v[78:79] op_sel_hi:[0,1,1]
	v_cvt_f32_ubyte2_e32 v146, v77
	v_cvt_f32_ubyte3_e32 v147, v77
	v_pk_fma_f32 v[70:71], v[64:65], v[104:105], v[70:71] op_sel_hi:[0,1,1]
	v_cvt_f32_ubyte0_e32 v98, v82
	v_cvt_f32_ubyte1_e32 v99, v82
	v_pk_fma_f32 v[62:63], v[64:65], v[146:147], v[62:63] op_sel_hi:[0,1,1]
	v_cvt_f32_ubyte2_e32 v102, v82
	v_cvt_f32_ubyte3_e32 v103, v82
	v_pk_fma_f32 v[92:93], v[54:55], v[98:99], v[92:93] op_sel:[1,0,0]
	v_cvt_f32_ubyte0_e32 v104, v83
	v_cvt_f32_ubyte1_e32 v105, v83
	v_pk_fma_f32 v[90:91], v[54:55], v[102:103], v[90:91] op_sel:[1,0,0]
	v_cvt_f32_ubyte2_e32 v146, v83
	v_cvt_f32_ubyte3_e32 v147, v83
	v_pk_fma_f32 v[86:87], v[64:65], v[104:105], v[86:87] op_sel:[1,0,0]
	v_cvt_f32_ubyte0_e32 v98, v88
	v_cvt_f32_ubyte1_e32 v99, v88
	v_pk_fma_f32 v[84:85], v[64:65], v[146:147], v[84:85] op_sel:[1,0,0]
	v_and_b32_e32 v68, s0, v30
	v_and_b32_e32 v69, s1, v30
	v_and_b32_e32 v76, s0, v31
	v_and_b32_e32 v77, s1, v31
	v_cvt_f32_ubyte2_e32 v102, v88
	v_cvt_f32_ubyte3_e32 v103, v88
	v_pk_fma_f32 v[80:81], v[54:55], v[98:99], v[80:81] op_sel:[1,0,0]
	v_cvt_f32_ubyte0_e32 v104, v89
	v_cvt_f32_ubyte1_e32 v105, v89
	v_pk_fma_f32 v[78:79], v[54:55], v[102:103], v[78:79] op_sel:[1,0,0]
	v_cvt_f32_ubyte2_e32 v146, v89
	v_cvt_f32_ubyte3_e32 v147, v89
	v_pk_fma_f32 v[70:71], v[64:65], v[104:105], v[70:71] op_sel:[1,0,0]
	v_cvt_f32_ubyte0_e32 v98, v68
	v_cvt_f32_ubyte1_e32 v99, v68
	v_pk_fma_f32 v[62:63], v[64:65], v[146:147], v[62:63] op_sel:[1,0,0]
	v_cvt_f32_ubyte2_e32 v102, v68
	v_cvt_f32_ubyte3_e32 v103, v68
	v_pk_fma_f32 v[92:93], v[56:57], v[98:99], v[92:93] op_sel_hi:[0,1,1]
	v_cvt_f32_ubyte0_e32 v104, v69
	v_cvt_f32_ubyte1_e32 v105, v69
	v_pk_fma_f32 v[90:91], v[56:57], v[102:103], v[90:91] op_sel_hi:[0,1,1]
	v_cvt_f32_ubyte2_e32 v146, v69
	v_cvt_f32_ubyte3_e32 v147, v69
	v_pk_fma_f32 v[86:87], v[66:67], v[104:105], v[86:87] op_sel_hi:[0,1,1]
	v_cvt_f32_ubyte0_e32 v98, v76
	v_cvt_f32_ubyte1_e32 v99, v76
	v_pk_fma_f32 v[84:85], v[66:67], v[146:147], v[84:85] op_sel_hi:[0,1,1]
	v_and_b32_e32 v82, s0, v32
	v_and_b32_e32 v83, s1, v32
	v_and_b32_e32 v88, s0, v33
	v_and_b32_e32 v89, s1, v33
	v_cvt_f32_ubyte2_e32 v102, v76
	v_cvt_f32_ubyte3_e32 v103, v76
	v_pk_fma_f32 v[80:81], v[56:57], v[98:99], v[80:81] op_sel_hi:[0,1,1]
	v_cvt_f32_ubyte0_e32 v104, v77
	v_cvt_f32_ubyte1_e32 v105, v77
	v_pk_fma_f32 v[78:79], v[56:57], v[102:103], v[78:79] op_sel_hi:[0,1,1]
	v_cvt_f32_ubyte2_e32 v146, v77
	v_cvt_f32_ubyte3_e32 v147, v77
	v_pk_fma_f32 v[70:71], v[66:67], v[104:105], v[70:71] op_sel_hi:[0,1,1]
	v_cvt_f32_ubyte0_e32 v98, v82
	v_cvt_f32_ubyte1_e32 v99, v82
	v_pk_fma_f32 v[62:63], v[66:67], v[146:147], v[62:63] op_sel_hi:[0,1,1]
	v_cvt_f32_ubyte2_e32 v102, v82
	v_cvt_f32_ubyte3_e32 v103, v82
	v_pk_fma_f32 v[92:93], v[56:57], v[98:99], v[92:93] op_sel:[1,0,0]
	v_cvt_f32_ubyte0_e32 v104, v83
	v_cvt_f32_ubyte1_e32 v105, v83
	v_pk_fma_f32 v[90:91], v[56:57], v[102:103], v[90:91] op_sel:[1,0,0]
	v_cvt_f32_ubyte2_e32 v146, v83
	v_cvt_f32_ubyte3_e32 v147, v83
	v_pk_fma_f32 v[86:87], v[66:67], v[104:105], v[86:87] op_sel:[1,0,0]
	v_cvt_f32_ubyte0_e32 v98, v88
	v_cvt_f32_ubyte1_e32 v99, v88
	v_pk_fma_f32 v[84:85], v[66:67], v[146:147], v[84:85] op_sel:[1,0,0]
	v_cvt_f32_ubyte2_e32 v102, v88
	v_cvt_f32_ubyte3_e32 v103, v88
	v_pk_fma_f32 v[80:81], v[56:57], v[98:99], v[80:81] op_sel:[1,0,0]
	v_cvt_f32_ubyte0_e32 v104, v89
	v_cvt_f32_ubyte1_e32 v105, v89
	v_pk_fma_f32 v[78:79], v[56:57], v[102:103], v[78:79] op_sel:[1,0,0]
	v_cvt_f32_ubyte2_e32 v146, v89
	v_cvt_f32_ubyte3_e32 v147, v89
	v_pk_fma_f32 v[70:71], v[66:67], v[104:105], v[70:71] op_sel:[1,0,0]
	v_pk_fma_f32 v[62:63], v[66:67], v[146:147], v[62:63] op_sel:[1,0,0]
	s_waitcnt lgkmcnt(0)
	ds_read_b128 v[50:53], v1 offset:928
	ds_read_b128 v[54:57], v1 offset:944
	ds_read_b128 v[58:61], v1 offset:1952
	ds_read_b128 v[64:67], v1 offset:1968
	s_waitcnt vmcnt(24)
	v_and_b32_e32 v68, s0, v164
	v_and_b32_e32 v69, s1, v164
	v_and_b32_e32 v76, s0, v165
	v_and_b32_e32 v77, s1, v165
	v_cvt_f32_ubyte0_e32 v98, v68
	v_cvt_f32_ubyte1_e32 v99, v68
	v_cvt_f32_ubyte2_e32 v102, v68
	v_cvt_f32_ubyte3_e32 v103, v68
	v_pk_fma_f32 v[92:93], v[34:35], v[98:99], v[92:93] op_sel_hi:[0,1,1]
	v_cvt_f32_ubyte0_e32 v104, v69
	v_cvt_f32_ubyte1_e32 v105, v69
	v_pk_fma_f32 v[90:91], v[34:35], v[102:103], v[90:91] op_sel_hi:[0,1,1]
	v_cvt_f32_ubyte2_e32 v146, v69
	v_cvt_f32_ubyte3_e32 v147, v69
	v_pk_fma_f32 v[86:87], v[42:43], v[104:105], v[86:87] op_sel_hi:[0,1,1]
	v_cvt_f32_ubyte0_e32 v98, v76
	v_cvt_f32_ubyte1_e32 v99, v76
	v_pk_fma_f32 v[84:85], v[42:43], v[146:147], v[84:85] op_sel_hi:[0,1,1]
	v_and_b32_e32 v82, s0, v166
	v_and_b32_e32 v83, s1, v166
	v_and_b32_e32 v88, s0, v167
	v_and_b32_e32 v89, s1, v167
	v_cvt_f32_ubyte2_e32 v102, v76
	v_cvt_f32_ubyte3_e32 v103, v76
	v_pk_fma_f32 v[80:81], v[34:35], v[98:99], v[80:81] op_sel_hi:[0,1,1]
	v_cvt_f32_ubyte0_e32 v104, v77
	v_cvt_f32_ubyte1_e32 v105, v77
	v_pk_fma_f32 v[78:79], v[34:35], v[102:103], v[78:79] op_sel_hi:[0,1,1]
	v_cvt_f32_ubyte2_e32 v146, v77
	v_cvt_f32_ubyte3_e32 v147, v77
	v_pk_fma_f32 v[70:71], v[42:43], v[104:105], v[70:71] op_sel_hi:[0,1,1]
	v_cvt_f32_ubyte0_e32 v98, v82
	v_cvt_f32_ubyte1_e32 v99, v82
	v_pk_fma_f32 v[62:63], v[42:43], v[146:147], v[62:63] op_sel_hi:[0,1,1]
	v_cvt_f32_ubyte2_e32 v102, v82
	v_cvt_f32_ubyte3_e32 v103, v82
	v_pk_fma_f32 v[92:93], v[34:35], v[98:99], v[92:93] op_sel:[1,0,0]
	v_cvt_f32_ubyte0_e32 v104, v83
	v_cvt_f32_ubyte1_e32 v105, v83
	v_pk_fma_f32 v[90:91], v[34:35], v[102:103], v[90:91] op_sel:[1,0,0]
	v_cvt_f32_ubyte2_e32 v146, v83
	v_cvt_f32_ubyte3_e32 v147, v83
	v_pk_fma_f32 v[86:87], v[42:43], v[104:105], v[86:87] op_sel:[1,0,0]
	v_cvt_f32_ubyte0_e32 v98, v88
	v_cvt_f32_ubyte1_e32 v99, v88
	v_pk_fma_f32 v[84:85], v[42:43], v[146:147], v[84:85] op_sel:[1,0,0]
	v_and_b32_e32 v68, s0, v168
	v_and_b32_e32 v69, s1, v168
	v_and_b32_e32 v76, s0, v169
	v_and_b32_e32 v77, s1, v169
	v_cvt_f32_ubyte2_e32 v102, v88
	v_cvt_f32_ubyte3_e32 v103, v88
	v_pk_fma_f32 v[80:81], v[34:35], v[98:99], v[80:81] op_sel:[1,0,0]
	v_cvt_f32_ubyte0_e32 v104, v89
	v_cvt_f32_ubyte1_e32 v105, v89
	v_pk_fma_f32 v[78:79], v[34:35], v[102:103], v[78:79] op_sel:[1,0,0]
	v_cvt_f32_ubyte2_e32 v146, v89
	v_cvt_f32_ubyte3_e32 v147, v89
	v_pk_fma_f32 v[70:71], v[42:43], v[104:105], v[70:71] op_sel:[1,0,0]
	v_cvt_f32_ubyte0_e32 v98, v68
	v_cvt_f32_ubyte1_e32 v99, v68
	v_pk_fma_f32 v[62:63], v[42:43], v[146:147], v[62:63] op_sel:[1,0,0]
	v_cvt_f32_ubyte2_e32 v102, v68
	v_cvt_f32_ubyte3_e32 v103, v68
	v_pk_fma_f32 v[92:93], v[36:37], v[98:99], v[92:93] op_sel_hi:[0,1,1]
	v_cvt_f32_ubyte0_e32 v104, v69
	v_cvt_f32_ubyte1_e32 v105, v69
	v_pk_fma_f32 v[90:91], v[36:37], v[102:103], v[90:91] op_sel_hi:[0,1,1]
	v_cvt_f32_ubyte2_e32 v146, v69
	v_cvt_f32_ubyte3_e32 v147, v69
	v_pk_fma_f32 v[86:87], v[44:45], v[104:105], v[86:87] op_sel_hi:[0,1,1]
	v_cvt_f32_ubyte0_e32 v98, v76
	v_cvt_f32_ubyte1_e32 v99, v76
	v_pk_fma_f32 v[84:85], v[44:45], v[146:147], v[84:85] op_sel_hi:[0,1,1]
	v_and_b32_e32 v82, s0, v170
	v_and_b32_e32 v83, s1, v170
	v_and_b32_e32 v88, s0, v171
	v_and_b32_e32 v89, s1, v171
	v_cvt_f32_ubyte2_e32 v102, v76
	v_cvt_f32_ubyte3_e32 v103, v76
	v_pk_fma_f32 v[80:81], v[36:37], v[98:99], v[80:81] op_sel_hi:[0,1,1]
	v_cvt_f32_ubyte0_e32 v104, v77
	v_cvt_f32_ubyte1_e32 v105, v77
	v_pk_fma_f32 v[78:79], v[36:37], v[102:103], v[78:79] op_sel_hi:[0,1,1]
	v_cvt_f32_ubyte2_e32 v146, v77
	v_cvt_f32_ubyte3_e32 v147, v77
	v_pk_fma_f32 v[70:71], v[44:45], v[104:105], v[70:71] op_sel_hi:[0,1,1]
	v_cvt_f32_ubyte0_e32 v98, v82
	v_cvt_f32_ubyte1_e32 v99, v82
	v_pk_fma_f32 v[62:63], v[44:45], v[146:147], v[62:63] op_sel_hi:[0,1,1]
	v_cvt_f32_ubyte2_e32 v102, v82
	v_cvt_f32_ubyte3_e32 v103, v82
	v_pk_fma_f32 v[92:93], v[36:37], v[98:99], v[92:93] op_sel:[1,0,0]
	v_cvt_f32_ubyte0_e32 v104, v83
	v_cvt_f32_ubyte1_e32 v105, v83
	v_pk_fma_f32 v[90:91], v[36:37], v[102:103], v[90:91] op_sel:[1,0,0]
	v_cvt_f32_ubyte2_e32 v146, v83
	v_cvt_f32_ubyte3_e32 v147, v83
	v_pk_fma_f32 v[86:87], v[44:45], v[104:105], v[86:87] op_sel:[1,0,0]
	v_cvt_f32_ubyte0_e32 v98, v88
	v_cvt_f32_ubyte1_e32 v99, v88
	v_pk_fma_f32 v[84:85], v[44:45], v[146:147], v[84:85] op_sel:[1,0,0]
	v_and_b32_e32 v68, s0, v172
	v_and_b32_e32 v69, s1, v172
	v_and_b32_e32 v76, s0, v173
	v_and_b32_e32 v77, s1, v173
	v_cvt_f32_ubyte2_e32 v102, v88
	v_cvt_f32_ubyte3_e32 v103, v88
	v_pk_fma_f32 v[80:81], v[36:37], v[98:99], v[80:81] op_sel:[1,0,0]
	v_cvt_f32_ubyte0_e32 v104, v89
	v_cvt_f32_ubyte1_e32 v105, v89
	v_pk_fma_f32 v[78:79], v[36:37], v[102:103], v[78:79] op_sel:[1,0,0]
	v_cvt_f32_ubyte2_e32 v146, v89
	v_cvt_f32_ubyte3_e32 v147, v89
	v_pk_fma_f32 v[70:71], v[44:45], v[104:105], v[70:71] op_sel:[1,0,0]
	v_cvt_f32_ubyte0_e32 v98, v68
	v_cvt_f32_ubyte1_e32 v99, v68
	v_pk_fma_f32 v[62:63], v[44:45], v[146:147], v[62:63] op_sel:[1,0,0]
	v_cvt_f32_ubyte2_e32 v102, v68
	v_cvt_f32_ubyte3_e32 v103, v68
	v_pk_fma_f32 v[92:93], v[38:39], v[98:99], v[92:93] op_sel_hi:[0,1,1]
	v_cvt_f32_ubyte0_e32 v104, v69
	v_cvt_f32_ubyte1_e32 v105, v69
	v_pk_fma_f32 v[90:91], v[38:39], v[102:103], v[90:91] op_sel_hi:[0,1,1]
	v_cvt_f32_ubyte2_e32 v146, v69
	v_cvt_f32_ubyte3_e32 v147, v69
	v_pk_fma_f32 v[86:87], v[46:47], v[104:105], v[86:87] op_sel_hi:[0,1,1]
	v_cvt_f32_ubyte0_e32 v98, v76
	v_cvt_f32_ubyte1_e32 v99, v76
	v_pk_fma_f32 v[84:85], v[46:47], v[146:147], v[84:85] op_sel_hi:[0,1,1]
	v_and_b32_e32 v82, s0, v174
	v_and_b32_e32 v83, s1, v174
	v_and_b32_e32 v88, s0, v175
	v_and_b32_e32 v89, s1, v175
	v_cvt_f32_ubyte2_e32 v102, v76
	v_cvt_f32_ubyte3_e32 v103, v76
	v_pk_fma_f32 v[80:81], v[38:39], v[98:99], v[80:81] op_sel_hi:[0,1,1]
	v_cvt_f32_ubyte0_e32 v104, v77
	v_cvt_f32_ubyte1_e32 v105, v77
	v_pk_fma_f32 v[78:79], v[38:39], v[102:103], v[78:79] op_sel_hi:[0,1,1]
	v_cvt_f32_ubyte2_e32 v146, v77
	v_cvt_f32_ubyte3_e32 v147, v77
	v_pk_fma_f32 v[70:71], v[46:47], v[104:105], v[70:71] op_sel_hi:[0,1,1]
	v_cvt_f32_ubyte0_e32 v98, v82
	v_cvt_f32_ubyte1_e32 v99, v82
	v_pk_fma_f32 v[62:63], v[46:47], v[146:147], v[62:63] op_sel_hi:[0,1,1]
	v_cvt_f32_ubyte2_e32 v102, v82
	v_cvt_f32_ubyte3_e32 v103, v82
	v_pk_fma_f32 v[92:93], v[38:39], v[98:99], v[92:93] op_sel:[1,0,0]
	v_cvt_f32_ubyte0_e32 v104, v83
	v_cvt_f32_ubyte1_e32 v105, v83
	v_pk_fma_f32 v[90:91], v[38:39], v[102:103], v[90:91] op_sel:[1,0,0]
	v_cvt_f32_ubyte2_e32 v146, v83
	v_cvt_f32_ubyte3_e32 v147, v83
	v_pk_fma_f32 v[86:87], v[46:47], v[104:105], v[86:87] op_sel:[1,0,0]
	v_cvt_f32_ubyte0_e32 v98, v88
	v_cvt_f32_ubyte1_e32 v99, v88
	v_pk_fma_f32 v[84:85], v[46:47], v[146:147], v[84:85] op_sel:[1,0,0]
	v_and_b32_e32 v68, s0, v176
	v_and_b32_e32 v69, s1, v176
	v_and_b32_e32 v76, s0, v177
	v_and_b32_e32 v77, s1, v177
	v_cvt_f32_ubyte2_e32 v102, v88
	v_cvt_f32_ubyte3_e32 v103, v88
	v_pk_fma_f32 v[80:81], v[38:39], v[98:99], v[80:81] op_sel:[1,0,0]
	v_cvt_f32_ubyte0_e32 v104, v89
	v_cvt_f32_ubyte1_e32 v105, v89
	v_pk_fma_f32 v[78:79], v[38:39], v[102:103], v[78:79] op_sel:[1,0,0]
	v_cvt_f32_ubyte2_e32 v146, v89
	v_cvt_f32_ubyte3_e32 v147, v89
	v_pk_fma_f32 v[70:71], v[46:47], v[104:105], v[70:71] op_sel:[1,0,0]
	v_cvt_f32_ubyte0_e32 v98, v68
	v_cvt_f32_ubyte1_e32 v99, v68
	v_pk_fma_f32 v[62:63], v[46:47], v[146:147], v[62:63] op_sel:[1,0,0]
	v_cvt_f32_ubyte2_e32 v102, v68
	v_cvt_f32_ubyte3_e32 v103, v68
	v_pk_fma_f32 v[92:93], v[40:41], v[98:99], v[92:93] op_sel_hi:[0,1,1]
	v_cvt_f32_ubyte0_e32 v104, v69
	v_cvt_f32_ubyte1_e32 v105, v69
	v_pk_fma_f32 v[90:91], v[40:41], v[102:103], v[90:91] op_sel_hi:[0,1,1]
	v_cvt_f32_ubyte2_e32 v146, v69
	v_cvt_f32_ubyte3_e32 v147, v69
	v_pk_fma_f32 v[86:87], v[48:49], v[104:105], v[86:87] op_sel_hi:[0,1,1]
	v_cvt_f32_ubyte0_e32 v98, v76
	v_cvt_f32_ubyte1_e32 v99, v76
	v_pk_fma_f32 v[84:85], v[48:49], v[146:147], v[84:85] op_sel_hi:[0,1,1]
	v_and_b32_e32 v82, s0, v178
	v_and_b32_e32 v83, s1, v178
	v_and_b32_e32 v88, s0, v179
	v_and_b32_e32 v89, s1, v179
	v_cvt_f32_ubyte2_e32 v102, v76
	v_cvt_f32_ubyte3_e32 v103, v76
	v_pk_fma_f32 v[80:81], v[40:41], v[98:99], v[80:81] op_sel_hi:[0,1,1]
	v_cvt_f32_ubyte0_e32 v104, v77
	v_cvt_f32_ubyte1_e32 v105, v77
	v_pk_fma_f32 v[78:79], v[40:41], v[102:103], v[78:79] op_sel_hi:[0,1,1]
	v_cvt_f32_ubyte2_e32 v146, v77
	v_cvt_f32_ubyte3_e32 v147, v77
	v_pk_fma_f32 v[70:71], v[48:49], v[104:105], v[70:71] op_sel_hi:[0,1,1]
	v_cvt_f32_ubyte0_e32 v98, v82
	v_cvt_f32_ubyte1_e32 v99, v82
	v_pk_fma_f32 v[62:63], v[48:49], v[146:147], v[62:63] op_sel_hi:[0,1,1]
	v_cvt_f32_ubyte2_e32 v102, v82
	v_cvt_f32_ubyte3_e32 v103, v82
	v_pk_fma_f32 v[92:93], v[40:41], v[98:99], v[92:93] op_sel:[1,0,0]
	v_cvt_f32_ubyte0_e32 v104, v83
	v_cvt_f32_ubyte1_e32 v105, v83
	v_pk_fma_f32 v[90:91], v[40:41], v[102:103], v[90:91] op_sel:[1,0,0]
	v_cvt_f32_ubyte2_e32 v146, v83
	v_cvt_f32_ubyte3_e32 v147, v83
	v_pk_fma_f32 v[86:87], v[48:49], v[104:105], v[86:87] op_sel:[1,0,0]
	v_cvt_f32_ubyte0_e32 v98, v88
	v_cvt_f32_ubyte1_e32 v99, v88
	v_pk_fma_f32 v[84:85], v[48:49], v[146:147], v[84:85] op_sel:[1,0,0]
	v_cvt_f32_ubyte2_e32 v102, v88
	v_cvt_f32_ubyte3_e32 v103, v88
	v_pk_fma_f32 v[80:81], v[40:41], v[98:99], v[80:81] op_sel:[1,0,0]
	v_cvt_f32_ubyte0_e32 v104, v89
	v_cvt_f32_ubyte1_e32 v105, v89
	v_pk_fma_f32 v[78:79], v[40:41], v[102:103], v[78:79] op_sel:[1,0,0]
	v_cvt_f32_ubyte2_e32 v146, v89
	v_cvt_f32_ubyte3_e32 v147, v89
	v_pk_fma_f32 v[70:71], v[48:49], v[104:105], v[70:71] op_sel:[1,0,0]
	v_pk_fma_f32 v[62:63], v[48:49], v[146:147], v[62:63] op_sel:[1,0,0]
	s_waitcnt lgkmcnt(0)
	ds_read_b128 v[34:37], v1 offset:960
	ds_read_b128 v[38:41], v1 offset:976
	ds_read_b128 v[42:45], v1 offset:1984
	ds_read_b128 v[46:49], v1 offset:2000
	s_waitcnt vmcnt(16)
	v_and_b32_e32 v68, s0, v180
	v_and_b32_e32 v69, s1, v180
	v_and_b32_e32 v76, s0, v181
	v_and_b32_e32 v77, s1, v181
	v_cvt_f32_ubyte0_e32 v98, v68
	v_cvt_f32_ubyte1_e32 v99, v68
	v_cvt_f32_ubyte2_e32 v102, v68
	v_cvt_f32_ubyte3_e32 v103, v68
	v_pk_fma_f32 v[92:93], v[50:51], v[98:99], v[92:93] op_sel_hi:[0,1,1]
	v_cvt_f32_ubyte0_e32 v104, v69
	v_cvt_f32_ubyte1_e32 v105, v69
	v_pk_fma_f32 v[90:91], v[50:51], v[102:103], v[90:91] op_sel_hi:[0,1,1]
	v_cvt_f32_ubyte2_e32 v146, v69
	v_cvt_f32_ubyte3_e32 v147, v69
	v_pk_fma_f32 v[86:87], v[58:59], v[104:105], v[86:87] op_sel_hi:[0,1,1]
	v_cvt_f32_ubyte0_e32 v98, v76
	v_cvt_f32_ubyte1_e32 v99, v76
	v_pk_fma_f32 v[84:85], v[58:59], v[146:147], v[84:85] op_sel_hi:[0,1,1]
	v_and_b32_e32 v82, s0, v182
	v_and_b32_e32 v83, s1, v182
	v_and_b32_e32 v88, s0, v183
	v_and_b32_e32 v89, s1, v183
	v_cvt_f32_ubyte2_e32 v102, v76
	v_cvt_f32_ubyte3_e32 v103, v76
	v_pk_fma_f32 v[80:81], v[50:51], v[98:99], v[80:81] op_sel_hi:[0,1,1]
	v_cvt_f32_ubyte0_e32 v104, v77
	v_cvt_f32_ubyte1_e32 v105, v77
	v_pk_fma_f32 v[78:79], v[50:51], v[102:103], v[78:79] op_sel_hi:[0,1,1]
	v_cvt_f32_ubyte2_e32 v146, v77
	v_cvt_f32_ubyte3_e32 v147, v77
	v_pk_fma_f32 v[70:71], v[58:59], v[104:105], v[70:71] op_sel_hi:[0,1,1]
	v_cvt_f32_ubyte0_e32 v98, v82
	v_cvt_f32_ubyte1_e32 v99, v82
	v_pk_fma_f32 v[62:63], v[58:59], v[146:147], v[62:63] op_sel_hi:[0,1,1]
	v_cvt_f32_ubyte2_e32 v102, v82
	v_cvt_f32_ubyte3_e32 v103, v82
	v_pk_fma_f32 v[92:93], v[50:51], v[98:99], v[92:93] op_sel:[1,0,0]
	v_cvt_f32_ubyte0_e32 v104, v83
	v_cvt_f32_ubyte1_e32 v105, v83
	v_pk_fma_f32 v[90:91], v[50:51], v[102:103], v[90:91] op_sel:[1,0,0]
	v_cvt_f32_ubyte2_e32 v146, v83
	v_cvt_f32_ubyte3_e32 v147, v83
	v_pk_fma_f32 v[86:87], v[58:59], v[104:105], v[86:87] op_sel:[1,0,0]
	v_cvt_f32_ubyte0_e32 v98, v88
	v_cvt_f32_ubyte1_e32 v99, v88
	v_pk_fma_f32 v[84:85], v[58:59], v[146:147], v[84:85] op_sel:[1,0,0]
	v_and_b32_e32 v68, s0, v184
	v_and_b32_e32 v69, s1, v184
	v_and_b32_e32 v76, s0, v185
	v_and_b32_e32 v77, s1, v185
	v_cvt_f32_ubyte2_e32 v102, v88
	v_cvt_f32_ubyte3_e32 v103, v88
	v_pk_fma_f32 v[80:81], v[50:51], v[98:99], v[80:81] op_sel:[1,0,0]
	v_cvt_f32_ubyte0_e32 v104, v89
	v_cvt_f32_ubyte1_e32 v105, v89
	v_pk_fma_f32 v[78:79], v[50:51], v[102:103], v[78:79] op_sel:[1,0,0]
	v_cvt_f32_ubyte2_e32 v146, v89
	v_cvt_f32_ubyte3_e32 v147, v89
	v_pk_fma_f32 v[70:71], v[58:59], v[104:105], v[70:71] op_sel:[1,0,0]
	v_cvt_f32_ubyte0_e32 v98, v68
	v_cvt_f32_ubyte1_e32 v99, v68
	v_pk_fma_f32 v[62:63], v[58:59], v[146:147], v[62:63] op_sel:[1,0,0]
	v_cvt_f32_ubyte2_e32 v102, v68
	v_cvt_f32_ubyte3_e32 v103, v68
	v_pk_fma_f32 v[92:93], v[52:53], v[98:99], v[92:93] op_sel_hi:[0,1,1]
	v_cvt_f32_ubyte0_e32 v104, v69
	v_cvt_f32_ubyte1_e32 v105, v69
	v_pk_fma_f32 v[90:91], v[52:53], v[102:103], v[90:91] op_sel_hi:[0,1,1]
	v_cvt_f32_ubyte2_e32 v146, v69
	v_cvt_f32_ubyte3_e32 v147, v69
	v_pk_fma_f32 v[86:87], v[60:61], v[104:105], v[86:87] op_sel_hi:[0,1,1]
	v_cvt_f32_ubyte0_e32 v98, v76
	v_cvt_f32_ubyte1_e32 v99, v76
	v_pk_fma_f32 v[84:85], v[60:61], v[146:147], v[84:85] op_sel_hi:[0,1,1]
	v_and_b32_e32 v82, s0, v186
	v_and_b32_e32 v83, s1, v186
	v_and_b32_e32 v88, s0, v187
	v_and_b32_e32 v89, s1, v187
	v_cvt_f32_ubyte2_e32 v102, v76
	v_cvt_f32_ubyte3_e32 v103, v76
	v_pk_fma_f32 v[80:81], v[52:53], v[98:99], v[80:81] op_sel_hi:[0,1,1]
	v_cvt_f32_ubyte0_e32 v104, v77
	v_cvt_f32_ubyte1_e32 v105, v77
	v_pk_fma_f32 v[78:79], v[52:53], v[102:103], v[78:79] op_sel_hi:[0,1,1]
	v_cvt_f32_ubyte2_e32 v146, v77
	v_cvt_f32_ubyte3_e32 v147, v77
	v_pk_fma_f32 v[70:71], v[60:61], v[104:105], v[70:71] op_sel_hi:[0,1,1]
	v_cvt_f32_ubyte0_e32 v98, v82
	v_cvt_f32_ubyte1_e32 v99, v82
	v_pk_fma_f32 v[62:63], v[60:61], v[146:147], v[62:63] op_sel_hi:[0,1,1]
	v_cvt_f32_ubyte2_e32 v102, v82
	v_cvt_f32_ubyte3_e32 v103, v82
	v_pk_fma_f32 v[92:93], v[52:53], v[98:99], v[92:93] op_sel:[1,0,0]
	v_cvt_f32_ubyte0_e32 v104, v83
	v_cvt_f32_ubyte1_e32 v105, v83
	v_pk_fma_f32 v[90:91], v[52:53], v[102:103], v[90:91] op_sel:[1,0,0]
	v_cvt_f32_ubyte2_e32 v146, v83
	v_cvt_f32_ubyte3_e32 v147, v83
	v_pk_fma_f32 v[86:87], v[60:61], v[104:105], v[86:87] op_sel:[1,0,0]
	v_cvt_f32_ubyte0_e32 v98, v88
	v_cvt_f32_ubyte1_e32 v99, v88
	v_pk_fma_f32 v[84:85], v[60:61], v[146:147], v[84:85] op_sel:[1,0,0]
	v_and_b32_e32 v68, s0, v188
	v_and_b32_e32 v69, s1, v188
	v_and_b32_e32 v76, s0, v189
	v_and_b32_e32 v77, s1, v189
	v_cvt_f32_ubyte2_e32 v102, v88
	v_cvt_f32_ubyte3_e32 v103, v88
	v_pk_fma_f32 v[80:81], v[52:53], v[98:99], v[80:81] op_sel:[1,0,0]
	v_cvt_f32_ubyte0_e32 v104, v89
	v_cvt_f32_ubyte1_e32 v105, v89
	v_pk_fma_f32 v[78:79], v[52:53], v[102:103], v[78:79] op_sel:[1,0,0]
	v_cvt_f32_ubyte2_e32 v146, v89
	v_cvt_f32_ubyte3_e32 v147, v89
	v_pk_fma_f32 v[70:71], v[60:61], v[104:105], v[70:71] op_sel:[1,0,0]
	v_cvt_f32_ubyte0_e32 v98, v68
	v_cvt_f32_ubyte1_e32 v99, v68
	v_pk_fma_f32 v[62:63], v[60:61], v[146:147], v[62:63] op_sel:[1,0,0]
	v_cvt_f32_ubyte2_e32 v102, v68
	v_cvt_f32_ubyte3_e32 v103, v68
	v_pk_fma_f32 v[92:93], v[54:55], v[98:99], v[92:93] op_sel_hi:[0,1,1]
	v_cvt_f32_ubyte0_e32 v104, v69
	v_cvt_f32_ubyte1_e32 v105, v69
	v_pk_fma_f32 v[90:91], v[54:55], v[102:103], v[90:91] op_sel_hi:[0,1,1]
	v_cvt_f32_ubyte2_e32 v146, v69
	v_cvt_f32_ubyte3_e32 v147, v69
	v_pk_fma_f32 v[86:87], v[64:65], v[104:105], v[86:87] op_sel_hi:[0,1,1]
	v_cvt_f32_ubyte0_e32 v98, v76
	v_cvt_f32_ubyte1_e32 v99, v76
	v_pk_fma_f32 v[84:85], v[64:65], v[146:147], v[84:85] op_sel_hi:[0,1,1]
	v_and_b32_e32 v82, s0, v190
	v_and_b32_e32 v83, s1, v190
	v_and_b32_e32 v88, s0, v191
	v_and_b32_e32 v89, s1, v191
	v_cvt_f32_ubyte2_e32 v102, v76
	v_cvt_f32_ubyte3_e32 v103, v76
	v_pk_fma_f32 v[80:81], v[54:55], v[98:99], v[80:81] op_sel_hi:[0,1,1]
	v_cvt_f32_ubyte0_e32 v104, v77
	v_cvt_f32_ubyte1_e32 v105, v77
	v_pk_fma_f32 v[78:79], v[54:55], v[102:103], v[78:79] op_sel_hi:[0,1,1]
	v_cvt_f32_ubyte2_e32 v146, v77
	v_cvt_f32_ubyte3_e32 v147, v77
	v_pk_fma_f32 v[70:71], v[64:65], v[104:105], v[70:71] op_sel_hi:[0,1,1]
	v_cvt_f32_ubyte0_e32 v98, v82
	v_cvt_f32_ubyte1_e32 v99, v82
	v_pk_fma_f32 v[62:63], v[64:65], v[146:147], v[62:63] op_sel_hi:[0,1,1]
	v_cvt_f32_ubyte2_e32 v102, v82
	v_cvt_f32_ubyte3_e32 v103, v82
	v_pk_fma_f32 v[92:93], v[54:55], v[98:99], v[92:93] op_sel:[1,0,0]
	v_cvt_f32_ubyte0_e32 v104, v83
	v_cvt_f32_ubyte1_e32 v105, v83
	v_pk_fma_f32 v[90:91], v[54:55], v[102:103], v[90:91] op_sel:[1,0,0]
	v_cvt_f32_ubyte2_e32 v146, v83
	v_cvt_f32_ubyte3_e32 v147, v83
	v_pk_fma_f32 v[86:87], v[64:65], v[104:105], v[86:87] op_sel:[1,0,0]
	v_cvt_f32_ubyte0_e32 v98, v88
	v_cvt_f32_ubyte1_e32 v99, v88
	v_pk_fma_f32 v[84:85], v[64:65], v[146:147], v[84:85] op_sel:[1,0,0]
	v_and_b32_e32 v68, s0, v192
	v_and_b32_e32 v69, s1, v192
	v_and_b32_e32 v76, s0, v193
	v_and_b32_e32 v77, s1, v193
	v_cvt_f32_ubyte2_e32 v102, v88
	v_cvt_f32_ubyte3_e32 v103, v88
	v_pk_fma_f32 v[80:81], v[54:55], v[98:99], v[80:81] op_sel:[1,0,0]
	v_cvt_f32_ubyte0_e32 v104, v89
	v_cvt_f32_ubyte1_e32 v105, v89
	v_pk_fma_f32 v[78:79], v[54:55], v[102:103], v[78:79] op_sel:[1,0,0]
	v_cvt_f32_ubyte2_e32 v146, v89
	v_cvt_f32_ubyte3_e32 v147, v89
	v_pk_fma_f32 v[70:71], v[64:65], v[104:105], v[70:71] op_sel:[1,0,0]
	v_cvt_f32_ubyte0_e32 v98, v68
	v_cvt_f32_ubyte1_e32 v99, v68
	v_pk_fma_f32 v[62:63], v[64:65], v[146:147], v[62:63] op_sel:[1,0,0]
	v_cvt_f32_ubyte2_e32 v102, v68
	v_cvt_f32_ubyte3_e32 v103, v68
	v_pk_fma_f32 v[92:93], v[56:57], v[98:99], v[92:93] op_sel_hi:[0,1,1]
	v_cvt_f32_ubyte0_e32 v104, v69
	v_cvt_f32_ubyte1_e32 v105, v69
	v_pk_fma_f32 v[90:91], v[56:57], v[102:103], v[90:91] op_sel_hi:[0,1,1]
	v_cvt_f32_ubyte2_e32 v146, v69
	v_cvt_f32_ubyte3_e32 v147, v69
	v_pk_fma_f32 v[86:87], v[66:67], v[104:105], v[86:87] op_sel_hi:[0,1,1]
	v_cvt_f32_ubyte0_e32 v98, v76
	v_cvt_f32_ubyte1_e32 v99, v76
	v_pk_fma_f32 v[84:85], v[66:67], v[146:147], v[84:85] op_sel_hi:[0,1,1]
	v_and_b32_e32 v82, s0, v194
	v_and_b32_e32 v83, s1, v194
	v_and_b32_e32 v88, s0, v195
	v_and_b32_e32 v89, s1, v195
	v_cvt_f32_ubyte2_e32 v102, v76
	v_cvt_f32_ubyte3_e32 v103, v76
	v_pk_fma_f32 v[80:81], v[56:57], v[98:99], v[80:81] op_sel_hi:[0,1,1]
	v_cvt_f32_ubyte0_e32 v104, v77
	v_cvt_f32_ubyte1_e32 v105, v77
	v_pk_fma_f32 v[78:79], v[56:57], v[102:103], v[78:79] op_sel_hi:[0,1,1]
	v_cvt_f32_ubyte2_e32 v146, v77
	v_cvt_f32_ubyte3_e32 v147, v77
	v_pk_fma_f32 v[70:71], v[66:67], v[104:105], v[70:71] op_sel_hi:[0,1,1]
	v_cvt_f32_ubyte0_e32 v98, v82
	v_cvt_f32_ubyte1_e32 v99, v82
	v_pk_fma_f32 v[62:63], v[66:67], v[146:147], v[62:63] op_sel_hi:[0,1,1]
	v_cvt_f32_ubyte2_e32 v102, v82
	v_cvt_f32_ubyte3_e32 v103, v82
	v_pk_fma_f32 v[92:93], v[56:57], v[98:99], v[92:93] op_sel:[1,0,0]
	v_cvt_f32_ubyte0_e32 v104, v83
	v_cvt_f32_ubyte1_e32 v105, v83
	v_pk_fma_f32 v[90:91], v[56:57], v[102:103], v[90:91] op_sel:[1,0,0]
	v_cvt_f32_ubyte2_e32 v146, v83
	v_cvt_f32_ubyte3_e32 v147, v83
	v_pk_fma_f32 v[86:87], v[66:67], v[104:105], v[86:87] op_sel:[1,0,0]
	v_cvt_f32_ubyte0_e32 v98, v88
	v_cvt_f32_ubyte1_e32 v99, v88
	v_pk_fma_f32 v[84:85], v[66:67], v[146:147], v[84:85] op_sel:[1,0,0]
	v_cvt_f32_ubyte2_e32 v102, v88
	v_cvt_f32_ubyte3_e32 v103, v88
	v_pk_fma_f32 v[80:81], v[56:57], v[98:99], v[80:81] op_sel:[1,0,0]
	v_cvt_f32_ubyte0_e32 v104, v89
	v_cvt_f32_ubyte1_e32 v105, v89
	v_pk_fma_f32 v[78:79], v[56:57], v[102:103], v[78:79] op_sel:[1,0,0]
	v_cvt_f32_ubyte2_e32 v146, v89
	v_cvt_f32_ubyte3_e32 v147, v89
	v_pk_fma_f32 v[70:71], v[66:67], v[104:105], v[70:71] op_sel:[1,0,0]
	v_pk_fma_f32 v[62:63], v[66:67], v[146:147], v[62:63] op_sel:[1,0,0]
	s_waitcnt lgkmcnt(0)
	ds_read_b128 v[50:53], v1 offset:992
	ds_read_b128 v[54:57], v1 offset:1008
	ds_read_b128 v[58:61], v1 offset:2016
	ds_read_b128 v[64:67], v1 offset:2032
	s_waitcnt vmcnt(8)
	v_and_b32_e32 v68, s0, v196
	v_and_b32_e32 v69, s1, v196
	v_and_b32_e32 v76, s0, v197
	v_and_b32_e32 v77, s1, v197
	v_cvt_f32_ubyte0_e32 v98, v68
	v_cvt_f32_ubyte1_e32 v99, v68
	v_cvt_f32_ubyte2_e32 v102, v68
	v_cvt_f32_ubyte3_e32 v103, v68
	v_pk_fma_f32 v[92:93], v[34:35], v[98:99], v[92:93] op_sel_hi:[0,1,1]
	v_cvt_f32_ubyte0_e32 v104, v69
	v_cvt_f32_ubyte1_e32 v105, v69
	v_pk_fma_f32 v[90:91], v[34:35], v[102:103], v[90:91] op_sel_hi:[0,1,1]
	v_cvt_f32_ubyte2_e32 v146, v69
	v_cvt_f32_ubyte3_e32 v147, v69
	v_pk_fma_f32 v[86:87], v[42:43], v[104:105], v[86:87] op_sel_hi:[0,1,1]
	v_cvt_f32_ubyte0_e32 v98, v76
	v_cvt_f32_ubyte1_e32 v99, v76
	v_pk_fma_f32 v[84:85], v[42:43], v[146:147], v[84:85] op_sel_hi:[0,1,1]
	v_and_b32_e32 v82, s0, v198
	v_and_b32_e32 v83, s1, v198
	v_and_b32_e32 v88, s0, v199
	v_and_b32_e32 v89, s1, v199
	v_cvt_f32_ubyte2_e32 v102, v76
	v_cvt_f32_ubyte3_e32 v103, v76
	v_pk_fma_f32 v[80:81], v[34:35], v[98:99], v[80:81] op_sel_hi:[0,1,1]
	v_cvt_f32_ubyte0_e32 v104, v77
	v_cvt_f32_ubyte1_e32 v105, v77
	v_pk_fma_f32 v[78:79], v[34:35], v[102:103], v[78:79] op_sel_hi:[0,1,1]
	v_cvt_f32_ubyte2_e32 v146, v77
	v_cvt_f32_ubyte3_e32 v147, v77
	v_pk_fma_f32 v[70:71], v[42:43], v[104:105], v[70:71] op_sel_hi:[0,1,1]
	v_cvt_f32_ubyte0_e32 v98, v82
	v_cvt_f32_ubyte1_e32 v99, v82
	v_pk_fma_f32 v[62:63], v[42:43], v[146:147], v[62:63] op_sel_hi:[0,1,1]
	v_cvt_f32_ubyte2_e32 v102, v82
	v_cvt_f32_ubyte3_e32 v103, v82
	v_pk_fma_f32 v[92:93], v[34:35], v[98:99], v[92:93] op_sel:[1,0,0]
	v_cvt_f32_ubyte0_e32 v104, v83
	v_cvt_f32_ubyte1_e32 v105, v83
	v_pk_fma_f32 v[90:91], v[34:35], v[102:103], v[90:91] op_sel:[1,0,0]
	v_cvt_f32_ubyte2_e32 v146, v83
	v_cvt_f32_ubyte3_e32 v147, v83
	v_pk_fma_f32 v[86:87], v[42:43], v[104:105], v[86:87] op_sel:[1,0,0]
	v_cvt_f32_ubyte0_e32 v98, v88
	v_cvt_f32_ubyte1_e32 v99, v88
	v_pk_fma_f32 v[84:85], v[42:43], v[146:147], v[84:85] op_sel:[1,0,0]
	v_and_b32_e32 v68, s0, v200
	v_and_b32_e32 v69, s1, v200
	v_and_b32_e32 v76, s0, v201
	v_and_b32_e32 v77, s1, v201
	v_cvt_f32_ubyte2_e32 v102, v88
	v_cvt_f32_ubyte3_e32 v103, v88
	v_pk_fma_f32 v[80:81], v[34:35], v[98:99], v[80:81] op_sel:[1,0,0]
	v_cvt_f32_ubyte0_e32 v104, v89
	v_cvt_f32_ubyte1_e32 v105, v89
	v_pk_fma_f32 v[78:79], v[34:35], v[102:103], v[78:79] op_sel:[1,0,0]
	v_cvt_f32_ubyte2_e32 v146, v89
	v_cvt_f32_ubyte3_e32 v147, v89
	v_pk_fma_f32 v[70:71], v[42:43], v[104:105], v[70:71] op_sel:[1,0,0]
	v_cvt_f32_ubyte0_e32 v98, v68
	v_cvt_f32_ubyte1_e32 v99, v68
	v_pk_fma_f32 v[62:63], v[42:43], v[146:147], v[62:63] op_sel:[1,0,0]
	v_cvt_f32_ubyte2_e32 v102, v68
	v_cvt_f32_ubyte3_e32 v103, v68
	v_pk_fma_f32 v[92:93], v[36:37], v[98:99], v[92:93] op_sel_hi:[0,1,1]
	v_cvt_f32_ubyte0_e32 v104, v69
	v_cvt_f32_ubyte1_e32 v105, v69
	v_pk_fma_f32 v[90:91], v[36:37], v[102:103], v[90:91] op_sel_hi:[0,1,1]
	v_cvt_f32_ubyte2_e32 v146, v69
	v_cvt_f32_ubyte3_e32 v147, v69
	v_pk_fma_f32 v[86:87], v[44:45], v[104:105], v[86:87] op_sel_hi:[0,1,1]
	v_cvt_f32_ubyte0_e32 v98, v76
	v_cvt_f32_ubyte1_e32 v99, v76
	v_pk_fma_f32 v[84:85], v[44:45], v[146:147], v[84:85] op_sel_hi:[0,1,1]
	v_and_b32_e32 v82, s0, v202
	v_and_b32_e32 v83, s1, v202
	v_and_b32_e32 v88, s0, v203
	v_and_b32_e32 v89, s1, v203
	v_cvt_f32_ubyte2_e32 v102, v76
	v_cvt_f32_ubyte3_e32 v103, v76
	v_pk_fma_f32 v[80:81], v[36:37], v[98:99], v[80:81] op_sel_hi:[0,1,1]
	v_cvt_f32_ubyte0_e32 v104, v77
	v_cvt_f32_ubyte1_e32 v105, v77
	v_pk_fma_f32 v[78:79], v[36:37], v[102:103], v[78:79] op_sel_hi:[0,1,1]
	v_cvt_f32_ubyte2_e32 v146, v77
	v_cvt_f32_ubyte3_e32 v147, v77
	v_pk_fma_f32 v[70:71], v[44:45], v[104:105], v[70:71] op_sel_hi:[0,1,1]
	v_cvt_f32_ubyte0_e32 v98, v82
	v_cvt_f32_ubyte1_e32 v99, v82
	v_pk_fma_f32 v[62:63], v[44:45], v[146:147], v[62:63] op_sel_hi:[0,1,1]
	v_cvt_f32_ubyte2_e32 v102, v82
	v_cvt_f32_ubyte3_e32 v103, v82
	v_pk_fma_f32 v[92:93], v[36:37], v[98:99], v[92:93] op_sel:[1,0,0]
	v_cvt_f32_ubyte0_e32 v104, v83
	v_cvt_f32_ubyte1_e32 v105, v83
	v_pk_fma_f32 v[90:91], v[36:37], v[102:103], v[90:91] op_sel:[1,0,0]
	v_cvt_f32_ubyte2_e32 v146, v83
	v_cvt_f32_ubyte3_e32 v147, v83
	v_pk_fma_f32 v[86:87], v[44:45], v[104:105], v[86:87] op_sel:[1,0,0]
	v_cvt_f32_ubyte0_e32 v98, v88
	v_cvt_f32_ubyte1_e32 v99, v88
	v_pk_fma_f32 v[84:85], v[44:45], v[146:147], v[84:85] op_sel:[1,0,0]
	v_and_b32_e32 v68, s0, v204
	v_and_b32_e32 v69, s1, v204
	v_and_b32_e32 v76, s0, v205
	v_and_b32_e32 v77, s1, v205
	v_cvt_f32_ubyte2_e32 v102, v88
	v_cvt_f32_ubyte3_e32 v103, v88
	v_pk_fma_f32 v[80:81], v[36:37], v[98:99], v[80:81] op_sel:[1,0,0]
	v_cvt_f32_ubyte0_e32 v104, v89
	v_cvt_f32_ubyte1_e32 v105, v89
	v_pk_fma_f32 v[78:79], v[36:37], v[102:103], v[78:79] op_sel:[1,0,0]
	v_cvt_f32_ubyte2_e32 v146, v89
	v_cvt_f32_ubyte3_e32 v147, v89
	v_pk_fma_f32 v[70:71], v[44:45], v[104:105], v[70:71] op_sel:[1,0,0]
	v_cvt_f32_ubyte0_e32 v98, v68
	v_cvt_f32_ubyte1_e32 v99, v68
	v_pk_fma_f32 v[62:63], v[44:45], v[146:147], v[62:63] op_sel:[1,0,0]
	v_cvt_f32_ubyte2_e32 v102, v68
	v_cvt_f32_ubyte3_e32 v103, v68
	v_pk_fma_f32 v[92:93], v[38:39], v[98:99], v[92:93] op_sel_hi:[0,1,1]
	v_cvt_f32_ubyte0_e32 v104, v69
	v_cvt_f32_ubyte1_e32 v105, v69
	v_pk_fma_f32 v[90:91], v[38:39], v[102:103], v[90:91] op_sel_hi:[0,1,1]
	v_cvt_f32_ubyte2_e32 v146, v69
	v_cvt_f32_ubyte3_e32 v147, v69
	v_pk_fma_f32 v[86:87], v[46:47], v[104:105], v[86:87] op_sel_hi:[0,1,1]
	v_cvt_f32_ubyte0_e32 v98, v76
	v_cvt_f32_ubyte1_e32 v99, v76
	v_pk_fma_f32 v[84:85], v[46:47], v[146:147], v[84:85] op_sel_hi:[0,1,1]
	v_and_b32_e32 v82, s0, v206
	v_and_b32_e32 v83, s1, v206
	v_and_b32_e32 v88, s0, v207
	v_and_b32_e32 v89, s1, v207
	v_cvt_f32_ubyte2_e32 v102, v76
	v_cvt_f32_ubyte3_e32 v103, v76
	v_pk_fma_f32 v[80:81], v[38:39], v[98:99], v[80:81] op_sel_hi:[0,1,1]
	v_cvt_f32_ubyte0_e32 v104, v77
	v_cvt_f32_ubyte1_e32 v105, v77
	v_pk_fma_f32 v[78:79], v[38:39], v[102:103], v[78:79] op_sel_hi:[0,1,1]
	v_cvt_f32_ubyte2_e32 v146, v77
	v_cvt_f32_ubyte3_e32 v147, v77
	v_pk_fma_f32 v[70:71], v[46:47], v[104:105], v[70:71] op_sel_hi:[0,1,1]
	v_cvt_f32_ubyte0_e32 v98, v82
	v_cvt_f32_ubyte1_e32 v99, v82
	v_pk_fma_f32 v[62:63], v[46:47], v[146:147], v[62:63] op_sel_hi:[0,1,1]
	v_cvt_f32_ubyte2_e32 v102, v82
	v_cvt_f32_ubyte3_e32 v103, v82
	v_pk_fma_f32 v[92:93], v[38:39], v[98:99], v[92:93] op_sel:[1,0,0]
	v_cvt_f32_ubyte0_e32 v104, v83
	v_cvt_f32_ubyte1_e32 v105, v83
	v_pk_fma_f32 v[90:91], v[38:39], v[102:103], v[90:91] op_sel:[1,0,0]
	v_cvt_f32_ubyte2_e32 v146, v83
	v_cvt_f32_ubyte3_e32 v147, v83
	v_pk_fma_f32 v[86:87], v[46:47], v[104:105], v[86:87] op_sel:[1,0,0]
	v_cvt_f32_ubyte0_e32 v98, v88
	v_cvt_f32_ubyte1_e32 v99, v88
	v_pk_fma_f32 v[84:85], v[46:47], v[146:147], v[84:85] op_sel:[1,0,0]
	v_and_b32_e32 v68, s0, v208
	v_and_b32_e32 v69, s1, v208
	v_and_b32_e32 v76, s0, v209
	v_and_b32_e32 v77, s1, v209
	v_cvt_f32_ubyte2_e32 v102, v88
	v_cvt_f32_ubyte3_e32 v103, v88
	v_pk_fma_f32 v[80:81], v[38:39], v[98:99], v[80:81] op_sel:[1,0,0]
	v_cvt_f32_ubyte0_e32 v104, v89
	v_cvt_f32_ubyte1_e32 v105, v89
	v_pk_fma_f32 v[78:79], v[38:39], v[102:103], v[78:79] op_sel:[1,0,0]
	v_cvt_f32_ubyte2_e32 v146, v89
	v_cvt_f32_ubyte3_e32 v147, v89
	v_pk_fma_f32 v[70:71], v[46:47], v[104:105], v[70:71] op_sel:[1,0,0]
	v_cvt_f32_ubyte0_e32 v98, v68
	v_cvt_f32_ubyte1_e32 v99, v68
	v_pk_fma_f32 v[62:63], v[46:47], v[146:147], v[62:63] op_sel:[1,0,0]
	v_cvt_f32_ubyte2_e32 v102, v68
	v_cvt_f32_ubyte3_e32 v103, v68
	v_pk_fma_f32 v[92:93], v[40:41], v[98:99], v[92:93] op_sel_hi:[0,1,1]
	v_cvt_f32_ubyte0_e32 v104, v69
	v_cvt_f32_ubyte1_e32 v105, v69
	v_pk_fma_f32 v[90:91], v[40:41], v[102:103], v[90:91] op_sel_hi:[0,1,1]
	v_cvt_f32_ubyte2_e32 v146, v69
	v_cvt_f32_ubyte3_e32 v147, v69
	v_pk_fma_f32 v[86:87], v[48:49], v[104:105], v[86:87] op_sel_hi:[0,1,1]
	v_cvt_f32_ubyte0_e32 v98, v76
	v_cvt_f32_ubyte1_e32 v99, v76
	v_pk_fma_f32 v[84:85], v[48:49], v[146:147], v[84:85] op_sel_hi:[0,1,1]
	v_and_b32_e32 v82, s0, v210
	v_and_b32_e32 v83, s1, v210
	v_and_b32_e32 v88, s0, v211
	v_and_b32_e32 v89, s1, v211
	v_cvt_f32_ubyte2_e32 v102, v76
	v_cvt_f32_ubyte3_e32 v103, v76
	v_pk_fma_f32 v[80:81], v[40:41], v[98:99], v[80:81] op_sel_hi:[0,1,1]
	v_cvt_f32_ubyte0_e32 v104, v77
	v_cvt_f32_ubyte1_e32 v105, v77
	v_pk_fma_f32 v[78:79], v[40:41], v[102:103], v[78:79] op_sel_hi:[0,1,1]
	v_cvt_f32_ubyte2_e32 v146, v77
	v_cvt_f32_ubyte3_e32 v147, v77
	v_pk_fma_f32 v[70:71], v[48:49], v[104:105], v[70:71] op_sel_hi:[0,1,1]
	v_cvt_f32_ubyte0_e32 v98, v82
	v_cvt_f32_ubyte1_e32 v99, v82
	v_pk_fma_f32 v[62:63], v[48:49], v[146:147], v[62:63] op_sel_hi:[0,1,1]
	v_cvt_f32_ubyte2_e32 v102, v82
	v_cvt_f32_ubyte3_e32 v103, v82
	v_pk_fma_f32 v[92:93], v[40:41], v[98:99], v[92:93] op_sel:[1,0,0]
	v_cvt_f32_ubyte0_e32 v104, v83
	v_cvt_f32_ubyte1_e32 v105, v83
	v_pk_fma_f32 v[90:91], v[40:41], v[102:103], v[90:91] op_sel:[1,0,0]
	v_cvt_f32_ubyte2_e32 v146, v83
	v_cvt_f32_ubyte3_e32 v147, v83
	v_pk_fma_f32 v[86:87], v[48:49], v[104:105], v[86:87] op_sel:[1,0,0]
	v_cvt_f32_ubyte0_e32 v98, v88
	v_cvt_f32_ubyte1_e32 v99, v88
	v_pk_fma_f32 v[84:85], v[48:49], v[146:147], v[84:85] op_sel:[1,0,0]
	v_cvt_f32_ubyte2_e32 v102, v88
	v_cvt_f32_ubyte3_e32 v103, v88
	v_pk_fma_f32 v[80:81], v[40:41], v[98:99], v[80:81] op_sel:[1,0,0]
	v_cvt_f32_ubyte0_e32 v104, v89
	v_cvt_f32_ubyte1_e32 v105, v89
	v_pk_fma_f32 v[78:79], v[40:41], v[102:103], v[78:79] op_sel:[1,0,0]
	v_cvt_f32_ubyte2_e32 v146, v89
	v_cvt_f32_ubyte3_e32 v147, v89
	v_pk_fma_f32 v[70:71], v[48:49], v[104:105], v[70:71] op_sel:[1,0,0]
	v_pk_fma_f32 v[62:63], v[48:49], v[146:147], v[62:63] op_sel:[1,0,0]
	s_waitcnt lgkmcnt(0)
	s_waitcnt vmcnt(0)
	v_and_b32_e32 v68, s0, v212
	v_and_b32_e32 v69, s1, v212
	v_and_b32_e32 v76, s0, v213
	v_and_b32_e32 v77, s1, v213
	v_cvt_f32_ubyte0_e32 v98, v68
	v_cvt_f32_ubyte1_e32 v99, v68
	v_cvt_f32_ubyte2_e32 v102, v68
	v_cvt_f32_ubyte3_e32 v103, v68
	v_pk_fma_f32 v[92:93], v[50:51], v[98:99], v[92:93] op_sel_hi:[0,1,1]
	v_cvt_f32_ubyte0_e32 v104, v69
	v_cvt_f32_ubyte1_e32 v105, v69
	v_pk_fma_f32 v[90:91], v[50:51], v[102:103], v[90:91] op_sel_hi:[0,1,1]
	v_cvt_f32_ubyte2_e32 v146, v69
	v_cvt_f32_ubyte3_e32 v147, v69
	v_pk_fma_f32 v[86:87], v[58:59], v[104:105], v[86:87] op_sel_hi:[0,1,1]
	v_cvt_f32_ubyte0_e32 v98, v76
	v_cvt_f32_ubyte1_e32 v99, v76
	v_pk_fma_f32 v[84:85], v[58:59], v[146:147], v[84:85] op_sel_hi:[0,1,1]
	v_and_b32_e32 v82, s0, v214
	v_and_b32_e32 v83, s1, v214
	v_and_b32_e32 v88, s0, v215
	v_and_b32_e32 v89, s1, v215
	v_cvt_f32_ubyte2_e32 v102, v76
	v_cvt_f32_ubyte3_e32 v103, v76
	v_pk_fma_f32 v[80:81], v[50:51], v[98:99], v[80:81] op_sel_hi:[0,1,1]
	v_cvt_f32_ubyte0_e32 v104, v77
	v_cvt_f32_ubyte1_e32 v105, v77
	v_pk_fma_f32 v[78:79], v[50:51], v[102:103], v[78:79] op_sel_hi:[0,1,1]
	v_cvt_f32_ubyte2_e32 v146, v77
	v_cvt_f32_ubyte3_e32 v147, v77
	v_pk_fma_f32 v[70:71], v[58:59], v[104:105], v[70:71] op_sel_hi:[0,1,1]
	v_cvt_f32_ubyte0_e32 v98, v82
	v_cvt_f32_ubyte1_e32 v99, v82
	v_pk_fma_f32 v[62:63], v[58:59], v[146:147], v[62:63] op_sel_hi:[0,1,1]
	v_cvt_f32_ubyte2_e32 v102, v82
	v_cvt_f32_ubyte3_e32 v103, v82
	v_pk_fma_f32 v[92:93], v[50:51], v[98:99], v[92:93] op_sel:[1,0,0]
	v_cvt_f32_ubyte0_e32 v104, v83
	v_cvt_f32_ubyte1_e32 v105, v83
	v_pk_fma_f32 v[90:91], v[50:51], v[102:103], v[90:91] op_sel:[1,0,0]
	v_cvt_f32_ubyte2_e32 v146, v83
	v_cvt_f32_ubyte3_e32 v147, v83
	v_pk_fma_f32 v[86:87], v[58:59], v[104:105], v[86:87] op_sel:[1,0,0]
	v_cvt_f32_ubyte0_e32 v98, v88
	v_cvt_f32_ubyte1_e32 v99, v88
	v_pk_fma_f32 v[84:85], v[58:59], v[146:147], v[84:85] op_sel:[1,0,0]
	v_and_b32_e32 v68, s0, v216
	v_and_b32_e32 v69, s1, v216
	v_and_b32_e32 v76, s0, v217
	v_and_b32_e32 v77, s1, v217
	v_cvt_f32_ubyte2_e32 v102, v88
	v_cvt_f32_ubyte3_e32 v103, v88
	v_pk_fma_f32 v[80:81], v[50:51], v[98:99], v[80:81] op_sel:[1,0,0]
	v_cvt_f32_ubyte0_e32 v104, v89
	v_cvt_f32_ubyte1_e32 v105, v89
	v_pk_fma_f32 v[78:79], v[50:51], v[102:103], v[78:79] op_sel:[1,0,0]
	v_cvt_f32_ubyte2_e32 v146, v89
	v_cvt_f32_ubyte3_e32 v147, v89
	v_pk_fma_f32 v[70:71], v[58:59], v[104:105], v[70:71] op_sel:[1,0,0]
	v_cvt_f32_ubyte0_e32 v98, v68
	v_cvt_f32_ubyte1_e32 v99, v68
	v_pk_fma_f32 v[62:63], v[58:59], v[146:147], v[62:63] op_sel:[1,0,0]
	v_cvt_f32_ubyte2_e32 v102, v68
	v_cvt_f32_ubyte3_e32 v103, v68
	v_pk_fma_f32 v[92:93], v[52:53], v[98:99], v[92:93] op_sel_hi:[0,1,1]
	v_cvt_f32_ubyte0_e32 v104, v69
	v_cvt_f32_ubyte1_e32 v105, v69
	v_pk_fma_f32 v[90:91], v[52:53], v[102:103], v[90:91] op_sel_hi:[0,1,1]
	v_cvt_f32_ubyte2_e32 v146, v69
	v_cvt_f32_ubyte3_e32 v147, v69
	v_pk_fma_f32 v[86:87], v[60:61], v[104:105], v[86:87] op_sel_hi:[0,1,1]
	v_cvt_f32_ubyte0_e32 v98, v76
	v_cvt_f32_ubyte1_e32 v99, v76
	v_pk_fma_f32 v[84:85], v[60:61], v[146:147], v[84:85] op_sel_hi:[0,1,1]
	v_and_b32_e32 v82, s0, v218
	v_and_b32_e32 v83, s1, v218
	v_and_b32_e32 v88, s0, v219
	v_and_b32_e32 v89, s1, v219
	v_cvt_f32_ubyte2_e32 v102, v76
	v_cvt_f32_ubyte3_e32 v103, v76
	v_pk_fma_f32 v[80:81], v[52:53], v[98:99], v[80:81] op_sel_hi:[0,1,1]
	v_cvt_f32_ubyte0_e32 v104, v77
	v_cvt_f32_ubyte1_e32 v105, v77
	v_pk_fma_f32 v[78:79], v[52:53], v[102:103], v[78:79] op_sel_hi:[0,1,1]
	v_cvt_f32_ubyte2_e32 v146, v77
	v_cvt_f32_ubyte3_e32 v147, v77
	v_pk_fma_f32 v[70:71], v[60:61], v[104:105], v[70:71] op_sel_hi:[0,1,1]
	v_cvt_f32_ubyte0_e32 v98, v82
	v_cvt_f32_ubyte1_e32 v99, v82
	v_pk_fma_f32 v[62:63], v[60:61], v[146:147], v[62:63] op_sel_hi:[0,1,1]
	v_cvt_f32_ubyte2_e32 v102, v82
	v_cvt_f32_ubyte3_e32 v103, v82
	v_pk_fma_f32 v[92:93], v[52:53], v[98:99], v[92:93] op_sel:[1,0,0]
	v_cvt_f32_ubyte0_e32 v104, v83
	v_cvt_f32_ubyte1_e32 v105, v83
	v_pk_fma_f32 v[90:91], v[52:53], v[102:103], v[90:91] op_sel:[1,0,0]
	v_cvt_f32_ubyte2_e32 v146, v83
	v_cvt_f32_ubyte3_e32 v147, v83
	v_pk_fma_f32 v[86:87], v[60:61], v[104:105], v[86:87] op_sel:[1,0,0]
	v_cvt_f32_ubyte0_e32 v98, v88
	v_cvt_f32_ubyte1_e32 v99, v88
	v_pk_fma_f32 v[84:85], v[60:61], v[146:147], v[84:85] op_sel:[1,0,0]
	v_and_b32_e32 v68, s0, v220
	v_and_b32_e32 v69, s1, v220
	v_and_b32_e32 v76, s0, v221
	v_and_b32_e32 v77, s1, v221
	v_cvt_f32_ubyte2_e32 v102, v88
	v_cvt_f32_ubyte3_e32 v103, v88
	v_pk_fma_f32 v[80:81], v[52:53], v[98:99], v[80:81] op_sel:[1,0,0]
	v_cvt_f32_ubyte0_e32 v104, v89
	v_cvt_f32_ubyte1_e32 v105, v89
	v_pk_fma_f32 v[78:79], v[52:53], v[102:103], v[78:79] op_sel:[1,0,0]
	v_cvt_f32_ubyte2_e32 v146, v89
	v_cvt_f32_ubyte3_e32 v147, v89
	v_pk_fma_f32 v[70:71], v[60:61], v[104:105], v[70:71] op_sel:[1,0,0]
	v_cvt_f32_ubyte0_e32 v98, v68
	v_cvt_f32_ubyte1_e32 v99, v68
	v_pk_fma_f32 v[62:63], v[60:61], v[146:147], v[62:63] op_sel:[1,0,0]
	v_cvt_f32_ubyte2_e32 v102, v68
	v_cvt_f32_ubyte3_e32 v103, v68
	v_pk_fma_f32 v[92:93], v[54:55], v[98:99], v[92:93] op_sel_hi:[0,1,1]
	v_cvt_f32_ubyte0_e32 v104, v69
	v_cvt_f32_ubyte1_e32 v105, v69
	v_pk_fma_f32 v[90:91], v[54:55], v[102:103], v[90:91] op_sel_hi:[0,1,1]
	v_cvt_f32_ubyte2_e32 v146, v69
	v_cvt_f32_ubyte3_e32 v147, v69
	v_pk_fma_f32 v[86:87], v[64:65], v[104:105], v[86:87] op_sel_hi:[0,1,1]
	v_cvt_f32_ubyte0_e32 v98, v76
	v_cvt_f32_ubyte1_e32 v99, v76
	v_pk_fma_f32 v[84:85], v[64:65], v[146:147], v[84:85] op_sel_hi:[0,1,1]
	v_and_b32_e32 v82, s0, v222
	v_and_b32_e32 v83, s1, v222
	v_and_b32_e32 v88, s0, v223
	v_and_b32_e32 v89, s1, v223
	v_cvt_f32_ubyte2_e32 v102, v76
	v_cvt_f32_ubyte3_e32 v103, v76
	v_pk_fma_f32 v[80:81], v[54:55], v[98:99], v[80:81] op_sel_hi:[0,1,1]
	v_cvt_f32_ubyte0_e32 v104, v77
	v_cvt_f32_ubyte1_e32 v105, v77
	v_pk_fma_f32 v[78:79], v[54:55], v[102:103], v[78:79] op_sel_hi:[0,1,1]
	v_cvt_f32_ubyte2_e32 v146, v77
	v_cvt_f32_ubyte3_e32 v147, v77
	v_pk_fma_f32 v[70:71], v[64:65], v[104:105], v[70:71] op_sel_hi:[0,1,1]
	v_cvt_f32_ubyte0_e32 v98, v82
	v_cvt_f32_ubyte1_e32 v99, v82
	v_pk_fma_f32 v[62:63], v[64:65], v[146:147], v[62:63] op_sel_hi:[0,1,1]
	v_cvt_f32_ubyte2_e32 v102, v82
	v_cvt_f32_ubyte3_e32 v103, v82
	v_pk_fma_f32 v[92:93], v[54:55], v[98:99], v[92:93] op_sel:[1,0,0]
	v_cvt_f32_ubyte0_e32 v104, v83
	v_cvt_f32_ubyte1_e32 v105, v83
	v_pk_fma_f32 v[90:91], v[54:55], v[102:103], v[90:91] op_sel:[1,0,0]
	v_cvt_f32_ubyte2_e32 v146, v83
	v_cvt_f32_ubyte3_e32 v147, v83
	v_pk_fma_f32 v[86:87], v[64:65], v[104:105], v[86:87] op_sel:[1,0,0]
	v_cvt_f32_ubyte0_e32 v98, v88
	v_cvt_f32_ubyte1_e32 v99, v88
	v_pk_fma_f32 v[84:85], v[64:65], v[146:147], v[84:85] op_sel:[1,0,0]
	v_and_b32_e32 v68, s0, v224
	v_and_b32_e32 v69, s1, v224
	v_and_b32_e32 v76, s0, v225
	v_and_b32_e32 v77, s1, v225
	v_cvt_f32_ubyte2_e32 v102, v88
	v_cvt_f32_ubyte3_e32 v103, v88
	v_pk_fma_f32 v[80:81], v[54:55], v[98:99], v[80:81] op_sel:[1,0,0]
	v_cvt_f32_ubyte0_e32 v104, v89
	v_cvt_f32_ubyte1_e32 v105, v89
	v_pk_fma_f32 v[78:79], v[54:55], v[102:103], v[78:79] op_sel:[1,0,0]
	v_cvt_f32_ubyte2_e32 v146, v89
	v_cvt_f32_ubyte3_e32 v147, v89
	v_pk_fma_f32 v[70:71], v[64:65], v[104:105], v[70:71] op_sel:[1,0,0]
	v_cvt_f32_ubyte0_e32 v98, v68
	v_cvt_f32_ubyte1_e32 v99, v68
	v_pk_fma_f32 v[62:63], v[64:65], v[146:147], v[62:63] op_sel:[1,0,0]
	v_cvt_f32_ubyte2_e32 v102, v68
	v_cvt_f32_ubyte3_e32 v103, v68
	v_pk_fma_f32 v[92:93], v[56:57], v[98:99], v[92:93] op_sel_hi:[0,1,1]
	v_cvt_f32_ubyte0_e32 v104, v69
	v_cvt_f32_ubyte1_e32 v105, v69
	v_pk_fma_f32 v[90:91], v[56:57], v[102:103], v[90:91] op_sel_hi:[0,1,1]
	v_cvt_f32_ubyte2_e32 v146, v69
	v_cvt_f32_ubyte3_e32 v147, v69
	v_pk_fma_f32 v[86:87], v[66:67], v[104:105], v[86:87] op_sel_hi:[0,1,1]
	v_cvt_f32_ubyte0_e32 v98, v76
	v_cvt_f32_ubyte1_e32 v99, v76
	v_pk_fma_f32 v[84:85], v[66:67], v[146:147], v[84:85] op_sel_hi:[0,1,1]
	v_and_b32_e32 v82, s0, v226
	v_and_b32_e32 v83, s1, v226
	v_and_b32_e32 v88, s0, v227
	v_and_b32_e32 v89, s1, v227
	v_cvt_f32_ubyte2_e32 v102, v76
	v_cvt_f32_ubyte3_e32 v103, v76
	v_pk_fma_f32 v[80:81], v[56:57], v[98:99], v[80:81] op_sel_hi:[0,1,1]
	v_cvt_f32_ubyte0_e32 v104, v77
	v_cvt_f32_ubyte1_e32 v105, v77
	v_pk_fma_f32 v[78:79], v[56:57], v[102:103], v[78:79] op_sel_hi:[0,1,1]
	v_cvt_f32_ubyte2_e32 v146, v77
	v_cvt_f32_ubyte3_e32 v147, v77
	v_pk_fma_f32 v[70:71], v[66:67], v[104:105], v[70:71] op_sel_hi:[0,1,1]
	v_cvt_f32_ubyte0_e32 v98, v82
	v_cvt_f32_ubyte1_e32 v99, v82
	v_pk_fma_f32 v[62:63], v[66:67], v[146:147], v[62:63] op_sel_hi:[0,1,1]
	v_cvt_f32_ubyte2_e32 v102, v82
	v_cvt_f32_ubyte3_e32 v103, v82
	v_pk_fma_f32 v[92:93], v[56:57], v[98:99], v[92:93] op_sel:[1,0,0]
	v_cvt_f32_ubyte0_e32 v104, v83
	v_cvt_f32_ubyte1_e32 v105, v83
	v_pk_fma_f32 v[90:91], v[56:57], v[102:103], v[90:91] op_sel:[1,0,0]
	v_cvt_f32_ubyte2_e32 v146, v83
	v_cvt_f32_ubyte3_e32 v147, v83
	v_pk_fma_f32 v[86:87], v[66:67], v[104:105], v[86:87] op_sel:[1,0,0]
	v_cvt_f32_ubyte0_e32 v98, v88
	v_cvt_f32_ubyte1_e32 v99, v88
	v_pk_fma_f32 v[84:85], v[66:67], v[146:147], v[84:85] op_sel:[1,0,0]
	v_cvt_f32_ubyte2_e32 v102, v88
	v_cvt_f32_ubyte3_e32 v103, v88
	v_pk_fma_f32 v[80:81], v[56:57], v[98:99], v[80:81] op_sel:[1,0,0]
	v_cvt_f32_ubyte0_e32 v104, v89
	v_cvt_f32_ubyte1_e32 v105, v89
	v_pk_fma_f32 v[78:79], v[56:57], v[102:103], v[78:79] op_sel:[1,0,0]
	v_cvt_f32_ubyte2_e32 v146, v89
	v_cvt_f32_ubyte3_e32 v147, v89
	v_pk_fma_f32 v[70:71], v[66:67], v[104:105], v[70:71] op_sel:[1,0,0]
	v_pk_fma_f32 v[62:63], v[66:67], v[146:147], v[62:63] op_sel:[1,0,0]
	s_waitcnt lgkmcnt(0)
	s_branch .LBB0_608
